# GEMM K-loops: loop-back counter/pointer/exit-test block moved in front of the iteration's last barrier (behind the final MFMAs)
# baseline (speedup 1.0000x reference)
.LBB0_270:
	s_ashr_i32 s25, s24, 31
	s_lshl_b64 s[22:23], s[24:25], 19
	s_add_u32 s26, s16, s22
	s_addc_u32 s27, s17, s23
	s_and_b64 s[22:23], s[4:5], exec
	s_cselect_b32 s25, s27, s15
	s_cselect_b32 s56, s26, s14
	s_ashr_i32 s21, s20, 31
	s_lshl_b64 s[22:23], s[20:21], 19
	s_add_u32 s28, s34, s22
	s_addc_u32 s29, s35, s23
	s_and_b64 s[22:23], s[4:5], exec
	s_cselect_b32 s21, s29, s3
	s_cselect_b32 s57, s28, s2
	s_add_u32 s14, s14, 0x40080
	s_addc_u32 s15, s15, 0
	s_add_u32 s58, s2, 0x100
	s_addc_u32 s59, s3, 0
	s_mov_b32 s64, -2
	s_waitcnt lgkmcnt(0)
	s_waitcnt vmcnt(0)
	ds_read_b128 v[136:139], v159
	ds_read_b128 v[164:167], v159 offset:1024
	ds_read_b128 v[180:183], v159 offset:2048
	ds_read_b128 v[184:187], v159 offset:3072
	ds_read_b128 v[188:191], v160
	ds_read_b128 v[196:199], v160 offset:1024
	ds_read_b128 v[200:203], v160 offset:2048
	ds_read_b128 v[204:207], v160 offset:3072
	s_add_u32 s2, s14, 0xfffc0080
	s_addc_u32 s3, s15, -1
	s_cmp_eq_u32 s64, 12
	s_cselect_b32 s23, s25, s3
	s_cselect_b32 s22, s56, s2
	s_cselect_b32 s3, s21, s59
	s_cselect_b32 s2, s57, s58
	v_lshl_add_u64 v[168:169], s[14:15], 0, v[128:129]
	s_add_i32 m0, s31, 0xc000
	ds_read_b128 v[208:211], v161
	ds_read_b128 v[212:215], v161 offset:1024
	ds_read_b128 v[216:219], v161 offset:2048
	ds_read_b128 v[220:223], v161 offset:3072
	ds_read_b128 v[224:227], v161 offset:4096
	ds_read_b128 v[228:231], v161 offset:5120
	ds_read_b128 v[232:235], v161 offset:6144
	ds_read_b128 v[236:239], v161 offset:7168
	global_load_lds_dwordx4 v[168:169], off
	v_lshl_add_u64 v[168:169], s[14:15], 0, v[130:131]
	s_add_i32 m0, s31, 0xe000
	s_nop 0
	global_load_lds_dwordx4 v[168:169], off
	s_waitcnt vmcnt(8)
	s_waitcnt lgkmcnt(0)
	s_barrier
	s_setprio 1
	s_waitcnt lgkmcnt(0)
	v_mfma_f32_16x16x32_bf16 v[116:119], v[136:139], v[208:211], 0
	v_mfma_f32_16x16x32_bf16 v[112:115], v[180:183], v[208:211], 0
	v_mfma_f32_16x16x32_bf16 v[108:111], v[136:139], v[216:219], 0
	v_mfma_f32_16x16x32_bf16 v[104:107], v[180:183], v[216:219], 0
	v_mfma_f32_16x16x32_bf16 v[92:95], v[136:139], v[224:227], 0
	v_mfma_f32_16x16x32_bf16 v[88:91], v[180:183], v[224:227], 0
	v_mfma_f32_16x16x32_bf16 v[76:79], v[136:139], v[232:235], 0
	v_mfma_f32_16x16x32_bf16 v[72:75], v[180:183], v[232:235], 0
	v_mfma_f32_16x16x32_bf16 v[116:119], v[164:167], v[212:215], v[116:119]
	v_mfma_f32_16x16x32_bf16 v[112:115], v[184:187], v[212:215], v[112:115]
	v_mfma_f32_16x16x32_bf16 v[108:111], v[164:167], v[220:223], v[108:111]
	v_mfma_f32_16x16x32_bf16 v[104:107], v[184:187], v[220:223], v[104:107]
	v_mfma_f32_16x16x32_bf16 v[92:95], v[164:167], v[228:231], v[92:95]
	v_mfma_f32_16x16x32_bf16 v[88:91], v[184:187], v[228:231], v[88:91]
	v_mfma_f32_16x16x32_bf16 v[76:79], v[164:167], v[236:239], v[76:79]
	v_mfma_f32_16x16x32_bf16 v[72:75], v[184:187], v[236:239], v[72:75]
	s_setprio 0
	s_setprio 1
	v_mfma_f32_16x16x32_bf16 v[124:127], v[188:191], v[208:211], 0
	v_mfma_f32_16x16x32_bf16 v[120:123], v[200:203], v[208:211], 0
	v_mfma_f32_16x16x32_bf16 v[100:103], v[188:191], v[216:219], 0
	v_mfma_f32_16x16x32_bf16 v[96:99], v[200:203], v[216:219], 0
	v_mfma_f32_16x16x32_bf16 v[84:87], v[188:191], v[224:227], 0
	v_mfma_f32_16x16x32_bf16 v[80:83], v[200:203], v[224:227], 0
	v_mfma_f32_16x16x32_bf16 v[68:71], v[188:191], v[232:235], 0
	v_mfma_f32_16x16x32_bf16 v[64:67], v[200:203], v[232:235], 0
	v_mfma_f32_16x16x32_bf16 v[124:127], v[196:199], v[212:215], v[124:127]
	v_mfma_f32_16x16x32_bf16 v[120:123], v[204:207], v[212:215], v[120:123]
	v_mfma_f32_16x16x32_bf16 v[100:103], v[196:199], v[220:223], v[100:103]
	v_mfma_f32_16x16x32_bf16 v[96:99], v[204:207], v[220:223], v[96:99]
	v_mfma_f32_16x16x32_bf16 v[84:87], v[196:199], v[228:231], v[84:87]
	v_mfma_f32_16x16x32_bf16 v[80:83], v[204:207], v[228:231], v[80:83]
	v_mfma_f32_16x16x32_bf16 v[68:71], v[196:199], v[236:239], v[68:71]
	v_mfma_f32_16x16x32_bf16 v[64:67], v[204:207], v[236:239], v[64:67]
	s_setprio 0
	s_barrier
	s_add_i32 s65, s49, s37
	v_lshl_add_u64 v[168:169], s[2:3], 0, v[142:143]
	s_mov_b32 m0, s65
	ds_read_b128 v[208:211], v161 offset:16384
	ds_read_b128 v[212:215], v161 offset:17408
	ds_read_b128 v[216:219], v161 offset:18432
	ds_read_b128 v[220:223], v161 offset:19456
	ds_read_b128 v[224:227], v161 offset:20480
	ds_read_b128 v[228:231], v161 offset:21504
	ds_read_b128 v[232:235], v161 offset:22528
	ds_read_b128 v[236:239], v161 offset:23552
	global_load_lds_dwordx4 v[168:169], off
	s_add_i32 m0, s65, 0x2000
	s_add_u32 s66, s2, 0x40000
	v_lshl_add_u64 v[192:193], s[2:3], 0, v[146:147]
	s_addc_u32 s67, s3, 0
	s_add_i32 s65, s50, s37
	global_load_lds_dwordx4 v[192:193], off
	v_lshl_add_u64 v[240:241], s[66:67], 0, v[142:143]
	s_mov_b32 m0, s65
	v_lshl_add_u64 v[242:243], s[22:23], 0, v[144:145]
	global_load_lds_dwordx4 v[240:241], off
	v_lshl_add_u64 v[240:241], s[66:67], 0, v[146:147]
	s_add_i32 m0, s65, 0x2000
	s_nop 0
	global_load_lds_dwordx4 v[240:241], off
	v_lshl_add_u64 v[240:241], s[22:23], 0, v[140:141]
	s_mov_b32 m0, s31
	s_nop 0
	global_load_lds_dwordx4 v[240:241], off
	s_mov_b32 m0, s38
	s_nop 0
	global_load_lds_dwordx4 v[242:243], off
	s_waitcnt vmcnt(8)
	s_waitcnt lgkmcnt(0)
	s_barrier
	s_setprio 1
	s_waitcnt lgkmcnt(0)
	v_mfma_f32_16x16x32_bf16 v[52:55], v[136:139], v[208:211], 0
	v_mfma_f32_16x16x32_bf16 v[48:51], v[180:183], v[208:211], 0
	v_mfma_f32_16x16x32_bf16 v[44:47], v[136:139], v[216:219], 0
	v_mfma_f32_16x16x32_bf16 v[40:43], v[180:183], v[216:219], 0
	v_mfma_f32_16x16x32_bf16 v[28:31], v[136:139], v[224:227], 0
	v_mfma_f32_16x16x32_bf16 v[24:27], v[180:183], v[224:227], 0
	v_mfma_f32_16x16x32_bf16 v[12:15], v[136:139], v[232:235], 0
	v_mfma_f32_16x16x32_bf16 v[8:11], v[180:183], v[232:235], 0
	v_mfma_f32_16x16x32_bf16 v[52:55], v[164:167], v[212:215], v[52:55]
	v_mfma_f32_16x16x32_bf16 v[48:51], v[184:187], v[212:215], v[48:51]
	v_mfma_f32_16x16x32_bf16 v[44:47], v[164:167], v[220:223], v[44:47]
	v_mfma_f32_16x16x32_bf16 v[40:43], v[184:187], v[220:223], v[40:43]
	v_mfma_f32_16x16x32_bf16 v[28:31], v[164:167], v[228:231], v[28:31]
	v_mfma_f32_16x16x32_bf16 v[24:27], v[184:187], v[228:231], v[24:27]
	v_mfma_f32_16x16x32_bf16 v[12:15], v[164:167], v[236:239], v[12:15]
	v_mfma_f32_16x16x32_bf16 v[8:11], v[184:187], v[236:239], v[8:11]
	s_setprio 0
	s_setprio 1
	v_mfma_f32_16x16x32_bf16 v[60:63], v[188:191], v[208:211], 0
	v_mfma_f32_16x16x32_bf16 v[56:59], v[200:203], v[208:211], 0
	v_mfma_f32_16x16x32_bf16 v[36:39], v[188:191], v[216:219], 0
	v_mfma_f32_16x16x32_bf16 v[32:35], v[200:203], v[216:219], 0
	v_mfma_f32_16x16x32_bf16 v[20:23], v[188:191], v[224:227], 0
	v_mfma_f32_16x16x32_bf16 v[16:19], v[200:203], v[224:227], 0
	v_mfma_f32_16x16x32_bf16 v[4:7], v[188:191], v[232:235], 0
	v_mfma_f32_16x16x32_bf16 v[0:3], v[200:203], v[232:235], 0
	v_mfma_f32_16x16x32_bf16 v[60:63], v[196:199], v[212:215], v[60:63]
	v_mfma_f32_16x16x32_bf16 v[56:59], v[204:207], v[212:215], v[56:59]
	v_mfma_f32_16x16x32_bf16 v[36:39], v[196:199], v[220:223], v[36:39]
	v_mfma_f32_16x16x32_bf16 v[32:35], v[204:207], v[220:223], v[32:35]
	v_mfma_f32_16x16x32_bf16 v[20:23], v[196:199], v[228:231], v[20:23]
	v_mfma_f32_16x16x32_bf16 v[16:19], v[204:207], v[228:231], v[16:19]
	v_mfma_f32_16x16x32_bf16 v[4:7], v[196:199], v[236:239], v[4:7]
	v_mfma_f32_16x16x32_bf16 v[0:3], v[204:207], v[236:239], v[0:3]
	s_setprio 0
	s_barrier
	s_add_i32 s65, 0, 0x18000
	v_add_u32_e32 v163, s65, v156
	s_add_i32 s66, 0, 0x1c000
	ds_read_b128 v[136:139], v163
	ds_read_b128 v[164:167], v163 offset:1024
	ds_read_b128 v[180:183], v163 offset:2048
	ds_read_b128 v[184:187], v163 offset:3072
	v_add_u32_e32 v163, s66, v156
	ds_read_b128 v[188:191], v163
	ds_read_b128 v[196:199], v163 offset:1024
	ds_read_b128 v[200:203], v163 offset:2048
	ds_read_b128 v[204:207], v163 offset:3072
	s_add_u32 s22, s22, 0x40000
	s_addc_u32 s23, s23, 0
	s_mov_b32 m0, s39
	v_lshl_add_u64 v[244:245], s[22:23], 0, v[140:141]
	ds_read_b128 v[208:211], v161 offset:32768
	ds_read_b128 v[212:215], v161 offset:33792
	ds_read_b128 v[216:219], v161 offset:34816
	ds_read_b128 v[220:223], v161 offset:35840
	ds_read_b128 v[224:227], v161 offset:36864
	ds_read_b128 v[228:231], v161 offset:37888
	ds_read_b128 v[232:235], v161 offset:38912
	ds_read_b128 v[236:239], v161 offset:39936
	global_load_lds_dwordx4 v[244:245], off
	v_lshl_add_u64 v[244:245], s[22:23], 0, v[144:145]
	s_mov_b32 m0, s40
	s_nop 0
	global_load_lds_dwordx4 v[244:245], off
	s_waitcnt vmcnt(8)
	s_waitcnt lgkmcnt(0)
	s_barrier
	s_setprio 1
	s_waitcnt lgkmcnt(0)
	v_mfma_f32_16x16x32_bf16 v[116:119], v[136:139], v[208:211], v[116:119]
	v_mfma_f32_16x16x32_bf16 v[112:115], v[180:183], v[208:211], v[112:115]
	v_mfma_f32_16x16x32_bf16 v[108:111], v[136:139], v[216:219], v[108:111]
	v_mfma_f32_16x16x32_bf16 v[104:107], v[180:183], v[216:219], v[104:107]
	v_mfma_f32_16x16x32_bf16 v[92:95], v[136:139], v[224:227], v[92:95]
	v_mfma_f32_16x16x32_bf16 v[88:91], v[180:183], v[224:227], v[88:91]
	v_mfma_f32_16x16x32_bf16 v[76:79], v[136:139], v[232:235], v[76:79]
	v_mfma_f32_16x16x32_bf16 v[72:75], v[180:183], v[232:235], v[72:75]
	v_mfma_f32_16x16x32_bf16 v[116:119], v[164:167], v[212:215], v[116:119]
	v_mfma_f32_16x16x32_bf16 v[112:115], v[184:187], v[212:215], v[112:115]
	v_mfma_f32_16x16x32_bf16 v[108:111], v[164:167], v[220:223], v[108:111]
	v_mfma_f32_16x16x32_bf16 v[104:107], v[184:187], v[220:223], v[104:107]
	v_mfma_f32_16x16x32_bf16 v[92:95], v[164:167], v[228:231], v[92:95]
	v_mfma_f32_16x16x32_bf16 v[88:91], v[184:187], v[228:231], v[88:91]
	v_mfma_f32_16x16x32_bf16 v[76:79], v[164:167], v[236:239], v[76:79]
	v_mfma_f32_16x16x32_bf16 v[72:75], v[184:187], v[236:239], v[72:75]
	s_setprio 0
	s_setprio 1
	v_mfma_f32_16x16x32_bf16 v[124:127], v[188:191], v[208:211], v[124:127]
	v_mfma_f32_16x16x32_bf16 v[120:123], v[200:203], v[208:211], v[120:123]
	v_mfma_f32_16x16x32_bf16 v[100:103], v[188:191], v[216:219], v[100:103]
	v_mfma_f32_16x16x32_bf16 v[96:99], v[200:203], v[216:219], v[96:99]
	v_mfma_f32_16x16x32_bf16 v[84:87], v[188:191], v[224:227], v[84:87]
	v_mfma_f32_16x16x32_bf16 v[80:83], v[200:203], v[224:227], v[80:83]
	v_mfma_f32_16x16x32_bf16 v[68:71], v[188:191], v[232:235], v[68:71]
	v_mfma_f32_16x16x32_bf16 v[64:67], v[200:203], v[232:235], v[64:67]
	v_mfma_f32_16x16x32_bf16 v[124:127], v[196:199], v[212:215], v[124:127]
	v_mfma_f32_16x16x32_bf16 v[120:123], v[204:207], v[212:215], v[120:123]
	v_mfma_f32_16x16x32_bf16 v[100:103], v[196:199], v[220:223], v[100:103]
	v_mfma_f32_16x16x32_bf16 v[96:99], v[204:207], v[220:223], v[96:99]
	v_mfma_f32_16x16x32_bf16 v[84:87], v[196:199], v[228:231], v[84:87]
	v_mfma_f32_16x16x32_bf16 v[80:83], v[204:207], v[228:231], v[80:83]
	v_mfma_f32_16x16x32_bf16 v[68:71], v[196:199], v[236:239], v[68:71]
	v_mfma_f32_16x16x32_bf16 v[64:67], v[204:207], v[236:239], v[64:67]
	s_setprio 0
	s_barrier
	s_add_i32 s22, s65, s37
	v_lshl_add_u64 v[168:169], v[168:169], 0, s[10:11]
	s_mov_b32 m0, s22
	ds_read_b128 v[208:211], v161 offset:49152
	ds_read_b128 v[212:215], v161 offset:50176
	ds_read_b128 v[216:219], v161 offset:51200
	ds_read_b128 v[220:223], v161 offset:52224
	ds_read_b128 v[224:227], v161 offset:53248
	ds_read_b128 v[228:231], v161 offset:54272
	ds_read_b128 v[232:235], v161 offset:55296
	ds_read_b128 v[236:239], v161 offset:56320
	global_load_lds_dwordx4 v[168:169], off
	s_add_i32 m0, s22, 0x2000
	s_add_u32 s2, s2, 0x40080
	v_lshl_add_u64 v[168:169], v[192:193], 0, s[10:11]
	s_addc_u32 s3, s3, 0
	s_add_i32 s22, s66, s37
	global_load_lds_dwordx4 v[168:169], off
	v_lshl_add_u64 v[168:169], s[2:3], 0, v[142:143]
	s_mov_b32 m0, s22
	s_nop 0
	global_load_lds_dwordx4 v[168:169], off
	v_lshl_add_u64 v[168:169], s[2:3], 0, v[146:147]
	s_add_i32 m0, s22, 0x2000
	s_nop 0
	global_load_lds_dwordx4 v[168:169], off
	v_lshl_add_u64 v[168:169], v[240:241], 0, s[10:11]
	s_mov_b32 m0, s43
	s_nop 0
	global_load_lds_dwordx4 v[168:169], off
	v_lshl_add_u64 v[168:169], v[242:243], 0, s[10:11]
	s_mov_b32 m0, s44
	s_nop 0
	global_load_lds_dwordx4 v[168:169], off
	s_waitcnt vmcnt(8)
	s_waitcnt lgkmcnt(0)
	s_barrier
	s_setprio 1
	s_waitcnt lgkmcnt(0)
	v_mfma_f32_16x16x32_bf16 v[52:55], v[136:139], v[208:211], v[52:55]
	v_mfma_f32_16x16x32_bf16 v[48:51], v[180:183], v[208:211], v[48:51]
	v_mfma_f32_16x16x32_bf16 v[44:47], v[136:139], v[216:219], v[44:47]
	v_mfma_f32_16x16x32_bf16 v[40:43], v[180:183], v[216:219], v[40:43]
	v_mfma_f32_16x16x32_bf16 v[28:31], v[136:139], v[224:227], v[28:31]
	v_mfma_f32_16x16x32_bf16 v[24:27], v[180:183], v[224:227], v[24:27]
	v_mfma_f32_16x16x32_bf16 v[12:15], v[136:139], v[232:235], v[12:15]
	v_mfma_f32_16x16x32_bf16 v[8:11], v[180:183], v[232:235], v[8:11]
	v_mfma_f32_16x16x32_bf16 v[52:55], v[164:167], v[212:215], v[52:55]
	v_mfma_f32_16x16x32_bf16 v[48:51], v[184:187], v[212:215], v[48:51]
	v_mfma_f32_16x16x32_bf16 v[44:47], v[164:167], v[220:223], v[44:47]
	v_mfma_f32_16x16x32_bf16 v[40:43], v[184:187], v[220:223], v[40:43]
	v_mfma_f32_16x16x32_bf16 v[28:31], v[164:167], v[228:231], v[28:31]
	v_mfma_f32_16x16x32_bf16 v[24:27], v[184:187], v[228:231], v[24:27]
	v_mfma_f32_16x16x32_bf16 v[12:15], v[164:167], v[236:239], v[12:15]
	v_mfma_f32_16x16x32_bf16 v[8:11], v[184:187], v[236:239], v[8:11]
	s_setprio 0
	s_setprio 1
	v_mfma_f32_16x16x32_bf16 v[60:63], v[188:191], v[208:211], v[60:63]
	v_mfma_f32_16x16x32_bf16 v[56:59], v[200:203], v[208:211], v[56:59]
	v_mfma_f32_16x16x32_bf16 v[36:39], v[188:191], v[216:219], v[36:39]
	v_mfma_f32_16x16x32_bf16 v[32:35], v[200:203], v[216:219], v[32:35]
	v_mfma_f32_16x16x32_bf16 v[20:23], v[188:191], v[224:227], v[20:23]
	v_mfma_f32_16x16x32_bf16 v[16:19], v[200:203], v[224:227], v[16:19]
	v_mfma_f32_16x16x32_bf16 v[4:7], v[188:191], v[232:235], v[4:7]
	v_mfma_f32_16x16x32_bf16 v[0:3], v[200:203], v[232:235], v[0:3]
	v_mfma_f32_16x16x32_bf16 v[60:63], v[196:199], v[212:215], v[60:63]
	v_mfma_f32_16x16x32_bf16 v[56:59], v[204:207], v[212:215], v[56:59]
	v_mfma_f32_16x16x32_bf16 v[36:39], v[196:199], v[220:223], v[36:39]
	v_mfma_f32_16x16x32_bf16 v[32:35], v[204:207], v[220:223], v[32:35]
	v_mfma_f32_16x16x32_bf16 v[20:23], v[196:199], v[228:231], v[20:23]
	v_mfma_f32_16x16x32_bf16 v[16:19], v[204:207], v[228:231], v[16:19]
	v_mfma_f32_16x16x32_bf16 v[4:7], v[196:199], v[236:239], v[4:7]
	v_mfma_f32_16x16x32_bf16 v[0:3], v[204:207], v[236:239], v[0:3]
	s_setprio 0
	s_add_i32 s64, s64, 2
	s_add_u32 s14, s14, 0x100
	s_addc_u32 s15, s15, 0
	s_add_u32 s58, s58, 0x100
	s_addc_u32 s59, s59, 0
	s_cmp_gt_u32 s64, 13
	s_barrier
	s_cbranch_scc1 .Lgemm_kdone_0
.LBB0_271:
	ds_read_b128 v[136:139], v159
	ds_read_b128 v[164:167], v159 offset:1024
	ds_read_b128 v[180:183], v159 offset:2048
	ds_read_b128 v[184:187], v159 offset:3072
	ds_read_b128 v[188:191], v160
	ds_read_b128 v[196:199], v160 offset:1024
	ds_read_b128 v[200:203], v160 offset:2048
	ds_read_b128 v[204:207], v160 offset:3072
	s_add_u32 s2, s14, 0xfffc0080
	s_addc_u32 s3, s15, -1
	s_cmp_eq_u32 s64, 12
	s_cselect_b32 s23, s25, s3
	s_cselect_b32 s22, s56, s2
	s_cselect_b32 s3, s21, s59
	s_cselect_b32 s2, s57, s58
	v_lshl_add_u64 v[168:169], s[14:15], 0, v[128:129]
	s_add_i32 m0, s31, 0xc000
	ds_read_b128 v[208:211], v161
	ds_read_b128 v[212:215], v161 offset:1024
	ds_read_b128 v[216:219], v161 offset:2048
	ds_read_b128 v[220:223], v161 offset:3072
	ds_read_b128 v[224:227], v161 offset:4096
	ds_read_b128 v[228:231], v161 offset:5120
	ds_read_b128 v[232:235], v161 offset:6144
	ds_read_b128 v[236:239], v161 offset:7168
	global_load_lds_dwordx4 v[168:169], off
	v_lshl_add_u64 v[168:169], s[14:15], 0, v[130:131]
	s_add_i32 m0, s31, 0xe000
	s_nop 0
	global_load_lds_dwordx4 v[168:169], off
	s_waitcnt vmcnt(8)
	s_waitcnt lgkmcnt(0)
	s_barrier
	s_setprio 1
	s_waitcnt lgkmcnt(0)
	v_mfma_f32_16x16x32_bf16 v[116:119], v[136:139], v[208:211], v[116:119]
	v_mfma_f32_16x16x32_bf16 v[112:115], v[180:183], v[208:211], v[112:115]
	v_mfma_f32_16x16x32_bf16 v[108:111], v[136:139], v[216:219], v[108:111]
	v_mfma_f32_16x16x32_bf16 v[104:107], v[180:183], v[216:219], v[104:107]
	v_mfma_f32_16x16x32_bf16 v[92:95], v[136:139], v[224:227], v[92:95]
	v_mfma_f32_16x16x32_bf16 v[88:91], v[180:183], v[224:227], v[88:91]
	v_mfma_f32_16x16x32_bf16 v[76:79], v[136:139], v[232:235], v[76:79]
	v_mfma_f32_16x16x32_bf16 v[72:75], v[180:183], v[232:235], v[72:75]
	v_mfma_f32_16x16x32_bf16 v[116:119], v[164:167], v[212:215], v[116:119]
	v_mfma_f32_16x16x32_bf16 v[112:115], v[184:187], v[212:215], v[112:115]
	v_mfma_f32_16x16x32_bf16 v[108:111], v[164:167], v[220:223], v[108:111]
	v_mfma_f32_16x16x32_bf16 v[104:107], v[184:187], v[220:223], v[104:107]
	v_mfma_f32_16x16x32_bf16 v[92:95], v[164:167], v[228:231], v[92:95]
	v_mfma_f32_16x16x32_bf16 v[88:91], v[184:187], v[228:231], v[88:91]
	v_mfma_f32_16x16x32_bf16 v[76:79], v[164:167], v[236:239], v[76:79]
	v_mfma_f32_16x16x32_bf16 v[72:75], v[184:187], v[236:239], v[72:75]
	s_setprio 0
	s_setprio 1
	v_mfma_f32_16x16x32_bf16 v[124:127], v[188:191], v[208:211], v[124:127]
	v_mfma_f32_16x16x32_bf16 v[120:123], v[200:203], v[208:211], v[120:123]
	v_mfma_f32_16x16x32_bf16 v[100:103], v[188:191], v[216:219], v[100:103]
	v_mfma_f32_16x16x32_bf16 v[96:99], v[200:203], v[216:219], v[96:99]
	v_mfma_f32_16x16x32_bf16 v[84:87], v[188:191], v[224:227], v[84:87]
	v_mfma_f32_16x16x32_bf16 v[80:83], v[200:203], v[224:227], v[80:83]
	v_mfma_f32_16x16x32_bf16 v[68:71], v[188:191], v[232:235], v[68:71]
	v_mfma_f32_16x16x32_bf16 v[64:67], v[200:203], v[232:235], v[64:67]
	v_mfma_f32_16x16x32_bf16 v[124:127], v[196:199], v[212:215], v[124:127]
	v_mfma_f32_16x16x32_bf16 v[120:123], v[204:207], v[212:215], v[120:123]
	v_mfma_f32_16x16x32_bf16 v[100:103], v[196:199], v[220:223], v[100:103]
	v_mfma_f32_16x16x32_bf16 v[96:99], v[204:207], v[220:223], v[96:99]
	v_mfma_f32_16x16x32_bf16 v[84:87], v[196:199], v[228:231], v[84:87]
	v_mfma_f32_16x16x32_bf16 v[80:83], v[204:207], v[228:231], v[80:83]
	v_mfma_f32_16x16x32_bf16 v[68:71], v[196:199], v[236:239], v[68:71]
	v_mfma_f32_16x16x32_bf16 v[64:67], v[204:207], v[236:239], v[64:67]
	s_setprio 0
	s_barrier
	s_add_i32 s65, s49, s37
	v_lshl_add_u64 v[168:169], s[2:3], 0, v[142:143]
	s_mov_b32 m0, s65
	ds_read_b128 v[208:211], v161 offset:16384
	ds_read_b128 v[212:215], v161 offset:17408
	ds_read_b128 v[216:219], v161 offset:18432
	ds_read_b128 v[220:223], v161 offset:19456
	ds_read_b128 v[224:227], v161 offset:20480
	ds_read_b128 v[228:231], v161 offset:21504
	ds_read_b128 v[232:235], v161 offset:22528
	ds_read_b128 v[236:239], v161 offset:23552
	global_load_lds_dwordx4 v[168:169], off
	s_add_i32 m0, s65, 0x2000
	s_add_u32 s66, s2, 0x40000
	v_lshl_add_u64 v[192:193], s[2:3], 0, v[146:147]
	s_addc_u32 s67, s3, 0
	s_add_i32 s65, s50, s37
	global_load_lds_dwordx4 v[192:193], off
	v_lshl_add_u64 v[240:241], s[66:67], 0, v[142:143]
	s_mov_b32 m0, s65
	v_lshl_add_u64 v[242:243], s[22:23], 0, v[144:145]
	global_load_lds_dwordx4 v[240:241], off
	v_lshl_add_u64 v[240:241], s[66:67], 0, v[146:147]
	s_add_i32 m0, s65, 0x2000
	s_nop 0
	global_load_lds_dwordx4 v[240:241], off
	v_lshl_add_u64 v[240:241], s[22:23], 0, v[140:141]
	s_mov_b32 m0, s31
	s_nop 0
	global_load_lds_dwordx4 v[240:241], off
	s_mov_b32 m0, s38
	s_nop 0
	global_load_lds_dwordx4 v[242:243], off
	s_waitcnt vmcnt(8)
	s_waitcnt lgkmcnt(0)
	s_barrier
	s_setprio 1
	s_waitcnt lgkmcnt(0)
	v_mfma_f32_16x16x32_bf16 v[52:55], v[136:139], v[208:211], v[52:55]
	v_mfma_f32_16x16x32_bf16 v[48:51], v[180:183], v[208:211], v[48:51]
	v_mfma_f32_16x16x32_bf16 v[44:47], v[136:139], v[216:219], v[44:47]
	v_mfma_f32_16x16x32_bf16 v[40:43], v[180:183], v[216:219], v[40:43]
	v_mfma_f32_16x16x32_bf16 v[28:31], v[136:139], v[224:227], v[28:31]
	v_mfma_f32_16x16x32_bf16 v[24:27], v[180:183], v[224:227], v[24:27]
	v_mfma_f32_16x16x32_bf16 v[12:15], v[136:139], v[232:235], v[12:15]
	v_mfma_f32_16x16x32_bf16 v[8:11], v[180:183], v[232:235], v[8:11]
	v_mfma_f32_16x16x32_bf16 v[52:55], v[164:167], v[212:215], v[52:55]
	v_mfma_f32_16x16x32_bf16 v[48:51], v[184:187], v[212:215], v[48:51]
	v_mfma_f32_16x16x32_bf16 v[44:47], v[164:167], v[220:223], v[44:47]
	v_mfma_f32_16x16x32_bf16 v[40:43], v[184:187], v[220:223], v[40:43]
	v_mfma_f32_16x16x32_bf16 v[28:31], v[164:167], v[228:231], v[28:31]
	v_mfma_f32_16x16x32_bf16 v[24:27], v[184:187], v[228:231], v[24:27]
	v_mfma_f32_16x16x32_bf16 v[12:15], v[164:167], v[236:239], v[12:15]
	v_mfma_f32_16x16x32_bf16 v[8:11], v[184:187], v[236:239], v[8:11]
	s_setprio 0
	s_setprio 1
	v_mfma_f32_16x16x32_bf16 v[60:63], v[188:191], v[208:211], v[60:63]
	v_mfma_f32_16x16x32_bf16 v[56:59], v[200:203], v[208:211], v[56:59]
	v_mfma_f32_16x16x32_bf16 v[36:39], v[188:191], v[216:219], v[36:39]
	v_mfma_f32_16x16x32_bf16 v[32:35], v[200:203], v[216:219], v[32:35]
	v_mfma_f32_16x16x32_bf16 v[20:23], v[188:191], v[224:227], v[20:23]
	v_mfma_f32_16x16x32_bf16 v[16:19], v[200:203], v[224:227], v[16:19]
	v_mfma_f32_16x16x32_bf16 v[4:7], v[188:191], v[232:235], v[4:7]
	v_mfma_f32_16x16x32_bf16 v[0:3], v[200:203], v[232:235], v[0:3]
	v_mfma_f32_16x16x32_bf16 v[60:63], v[196:199], v[212:215], v[60:63]
	v_mfma_f32_16x16x32_bf16 v[56:59], v[204:207], v[212:215], v[56:59]
	v_mfma_f32_16x16x32_bf16 v[36:39], v[196:199], v[220:223], v[36:39]
	v_mfma_f32_16x16x32_bf16 v[32:35], v[204:207], v[220:223], v[32:35]
	v_mfma_f32_16x16x32_bf16 v[20:23], v[196:199], v[228:231], v[20:23]
	v_mfma_f32_16x16x32_bf16 v[16:19], v[204:207], v[228:231], v[16:19]
	v_mfma_f32_16x16x32_bf16 v[4:7], v[196:199], v[236:239], v[4:7]
	v_mfma_f32_16x16x32_bf16 v[0:3], v[204:207], v[236:239], v[0:3]
	s_setprio 0
	s_barrier
	s_add_i32 s65, 0, 0x18000
	v_add_u32_e32 v163, s65, v156
	s_add_i32 s66, 0, 0x1c000
	ds_read_b128 v[136:139], v163
	ds_read_b128 v[164:167], v163 offset:1024
	ds_read_b128 v[180:183], v163 offset:2048
	ds_read_b128 v[184:187], v163 offset:3072
	v_add_u32_e32 v163, s66, v156
	ds_read_b128 v[188:191], v163
	ds_read_b128 v[196:199], v163 offset:1024
	ds_read_b128 v[200:203], v163 offset:2048
	ds_read_b128 v[204:207], v163 offset:3072
	s_add_u32 s22, s22, 0x40000
	s_addc_u32 s23, s23, 0
	s_mov_b32 m0, s39
	v_lshl_add_u64 v[244:245], s[22:23], 0, v[140:141]
	ds_read_b128 v[208:211], v161 offset:32768
	ds_read_b128 v[212:215], v161 offset:33792
	ds_read_b128 v[216:219], v161 offset:34816
	ds_read_b128 v[220:223], v161 offset:35840
	ds_read_b128 v[224:227], v161 offset:36864
	ds_read_b128 v[228:231], v161 offset:37888
	ds_read_b128 v[232:235], v161 offset:38912
	ds_read_b128 v[236:239], v161 offset:39936
	global_load_lds_dwordx4 v[244:245], off
	v_lshl_add_u64 v[244:245], s[22:23], 0, v[144:145]
	s_mov_b32 m0, s40
	s_nop 0
	global_load_lds_dwordx4 v[244:245], off
	s_waitcnt vmcnt(8)
	s_waitcnt lgkmcnt(0)
	s_barrier
	s_setprio 1
	s_waitcnt lgkmcnt(0)
	v_mfma_f32_16x16x32_bf16 v[116:119], v[136:139], v[208:211], v[116:119]
	v_mfma_f32_16x16x32_bf16 v[112:115], v[180:183], v[208:211], v[112:115]
	v_mfma_f32_16x16x32_bf16 v[108:111], v[136:139], v[216:219], v[108:111]
	v_mfma_f32_16x16x32_bf16 v[104:107], v[180:183], v[216:219], v[104:107]
	v_mfma_f32_16x16x32_bf16 v[92:95], v[136:139], v[224:227], v[92:95]
	v_mfma_f32_16x16x32_bf16 v[88:91], v[180:183], v[224:227], v[88:91]
	v_mfma_f32_16x16x32_bf16 v[76:79], v[136:139], v[232:235], v[76:79]
	v_mfma_f32_16x16x32_bf16 v[72:75], v[180:183], v[232:235], v[72:75]
	v_mfma_f32_16x16x32_bf16 v[116:119], v[164:167], v[212:215], v[116:119]
	v_mfma_f32_16x16x32_bf16 v[112:115], v[184:187], v[212:215], v[112:115]
	v_mfma_f32_16x16x32_bf16 v[108:111], v[164:167], v[220:223], v[108:111]
	v_mfma_f32_16x16x32_bf16 v[104:107], v[184:187], v[220:223], v[104:107]
	v_mfma_f32_16x16x32_bf16 v[92:95], v[164:167], v[228:231], v[92:95]
	v_mfma_f32_16x16x32_bf16 v[88:91], v[184:187], v[228:231], v[88:91]
	v_mfma_f32_16x16x32_bf16 v[76:79], v[164:167], v[236:239], v[76:79]
	v_mfma_f32_16x16x32_bf16 v[72:75], v[184:187], v[236:239], v[72:75]
	s_setprio 0
	s_setprio 1
	v_mfma_f32_16x16x32_bf16 v[124:127], v[188:191], v[208:211], v[124:127]
	v_mfma_f32_16x16x32_bf16 v[120:123], v[200:203], v[208:211], v[120:123]
	v_mfma_f32_16x16x32_bf16 v[100:103], v[188:191], v[216:219], v[100:103]
	v_mfma_f32_16x16x32_bf16 v[96:99], v[200:203], v[216:219], v[96:99]
	v_mfma_f32_16x16x32_bf16 v[84:87], v[188:191], v[224:227], v[84:87]
	v_mfma_f32_16x16x32_bf16 v[80:83], v[200:203], v[224:227], v[80:83]
	v_mfma_f32_16x16x32_bf16 v[68:71], v[188:191], v[232:235], v[68:71]
	v_mfma_f32_16x16x32_bf16 v[64:67], v[200:203], v[232:235], v[64:67]
	v_mfma_f32_16x16x32_bf16 v[124:127], v[196:199], v[212:215], v[124:127]
	v_mfma_f32_16x16x32_bf16 v[120:123], v[204:207], v[212:215], v[120:123]
	v_mfma_f32_16x16x32_bf16 v[100:103], v[196:199], v[220:223], v[100:103]
	v_mfma_f32_16x16x32_bf16 v[96:99], v[204:207], v[220:223], v[96:99]
	v_mfma_f32_16x16x32_bf16 v[84:87], v[196:199], v[228:231], v[84:87]
	v_mfma_f32_16x16x32_bf16 v[80:83], v[204:207], v[228:231], v[80:83]
	v_mfma_f32_16x16x32_bf16 v[68:71], v[196:199], v[236:239], v[68:71]
	v_mfma_f32_16x16x32_bf16 v[64:67], v[204:207], v[236:239], v[64:67]
	s_setprio 0
	s_barrier
	s_add_i32 s22, s65, s37
	v_lshl_add_u64 v[168:169], v[168:169], 0, s[10:11]
	s_mov_b32 m0, s22
	ds_read_b128 v[208:211], v161 offset:49152
	ds_read_b128 v[212:215], v161 offset:50176
	ds_read_b128 v[216:219], v161 offset:51200
	ds_read_b128 v[220:223], v161 offset:52224
	ds_read_b128 v[224:227], v161 offset:53248
	ds_read_b128 v[228:231], v161 offset:54272
	ds_read_b128 v[232:235], v161 offset:55296
	ds_read_b128 v[236:239], v161 offset:56320
	global_load_lds_dwordx4 v[168:169], off
	s_add_i32 m0, s22, 0x2000
	s_add_u32 s2, s2, 0x40080
	v_lshl_add_u64 v[168:169], v[192:193], 0, s[10:11]
	s_addc_u32 s3, s3, 0
	s_add_i32 s22, s66, s37
	global_load_lds_dwordx4 v[168:169], off
	v_lshl_add_u64 v[168:169], s[2:3], 0, v[142:143]
	s_mov_b32 m0, s22
	s_nop 0
	global_load_lds_dwordx4 v[168:169], off
	v_lshl_add_u64 v[168:169], s[2:3], 0, v[146:147]
	s_add_i32 m0, s22, 0x2000
	s_nop 0
	global_load_lds_dwordx4 v[168:169], off
	v_lshl_add_u64 v[168:169], v[240:241], 0, s[10:11]
	s_mov_b32 m0, s43
	s_nop 0
	global_load_lds_dwordx4 v[168:169], off
	v_lshl_add_u64 v[168:169], v[242:243], 0, s[10:11]
	s_mov_b32 m0, s44
	s_nop 0
	global_load_lds_dwordx4 v[168:169], off
	s_waitcnt vmcnt(8)
	s_waitcnt lgkmcnt(0)
	s_barrier
	s_setprio 1
	s_waitcnt lgkmcnt(0)
	v_mfma_f32_16x16x32_bf16 v[52:55], v[136:139], v[208:211], v[52:55]
	v_mfma_f32_16x16x32_bf16 v[48:51], v[180:183], v[208:211], v[48:51]
	v_mfma_f32_16x16x32_bf16 v[44:47], v[136:139], v[216:219], v[44:47]
	v_mfma_f32_16x16x32_bf16 v[40:43], v[180:183], v[216:219], v[40:43]
	v_mfma_f32_16x16x32_bf16 v[28:31], v[136:139], v[224:227], v[28:31]
	v_mfma_f32_16x16x32_bf16 v[24:27], v[180:183], v[224:227], v[24:27]
	v_mfma_f32_16x16x32_bf16 v[12:15], v[136:139], v[232:235], v[12:15]
	v_mfma_f32_16x16x32_bf16 v[8:11], v[180:183], v[232:235], v[8:11]
	v_mfma_f32_16x16x32_bf16 v[52:55], v[164:167], v[212:215], v[52:55]
	v_mfma_f32_16x16x32_bf16 v[48:51], v[184:187], v[212:215], v[48:51]
	v_mfma_f32_16x16x32_bf16 v[44:47], v[164:167], v[220:223], v[44:47]
	v_mfma_f32_16x16x32_bf16 v[40:43], v[184:187], v[220:223], v[40:43]
	v_mfma_f32_16x16x32_bf16 v[28:31], v[164:167], v[228:231], v[28:31]
	v_mfma_f32_16x16x32_bf16 v[24:27], v[184:187], v[228:231], v[24:27]
	v_mfma_f32_16x16x32_bf16 v[12:15], v[164:167], v[236:239], v[12:15]
	v_mfma_f32_16x16x32_bf16 v[8:11], v[184:187], v[236:239], v[8:11]
	s_setprio 0
	s_setprio 1
	v_mfma_f32_16x16x32_bf16 v[60:63], v[188:191], v[208:211], v[60:63]
	v_mfma_f32_16x16x32_bf16 v[56:59], v[200:203], v[208:211], v[56:59]
	v_mfma_f32_16x16x32_bf16 v[36:39], v[188:191], v[216:219], v[36:39]
	v_mfma_f32_16x16x32_bf16 v[32:35], v[200:203], v[216:219], v[32:35]
	v_mfma_f32_16x16x32_bf16 v[20:23], v[188:191], v[224:227], v[20:23]
	v_mfma_f32_16x16x32_bf16 v[16:19], v[200:203], v[224:227], v[16:19]
	v_mfma_f32_16x16x32_bf16 v[4:7], v[188:191], v[232:235], v[4:7]
	v_mfma_f32_16x16x32_bf16 v[0:3], v[200:203], v[232:235], v[0:3]
	v_mfma_f32_16x16x32_bf16 v[60:63], v[196:199], v[212:215], v[60:63]
	v_mfma_f32_16x16x32_bf16 v[56:59], v[204:207], v[212:215], v[56:59]
	v_mfma_f32_16x16x32_bf16 v[36:39], v[196:199], v[220:223], v[36:39]
	v_mfma_f32_16x16x32_bf16 v[32:35], v[204:207], v[220:223], v[32:35]
	v_mfma_f32_16x16x32_bf16 v[20:23], v[196:199], v[228:231], v[20:23]
	v_mfma_f32_16x16x32_bf16 v[16:19], v[204:207], v[228:231], v[16:19]
	v_mfma_f32_16x16x32_bf16 v[4:7], v[196:199], v[236:239], v[4:7]
	v_mfma_f32_16x16x32_bf16 v[0:3], v[204:207], v[236:239], v[0:3]
	s_setprio 0
	s_add_i32 s64, s64, 2
	s_add_u32 s14, s14, 0x100
	s_addc_u32 s15, s15, 0
	s_add_u32 s58, s58, 0x100
	s_addc_u32 s59, s59, 0
	s_cmp_gt_u32 s64, 13
	s_barrier
	s_cbranch_scc0 .LBB0_271

.LBB0_367:
	s_ashr_i32 s25, s24, 31
	s_lshl_b64 s[22:23], s[24:25], 19
	s_add_u32 s26, s84, s22
	s_addc_u32 s27, s85, s23
	s_and_b64 s[22:23], s[0:1], exec
	s_cselect_b32 s25, s27, s15
	s_cselect_b32 s50, s26, s14
	s_ashr_i32 s21, s20, 31
	s_lshl_b64 s[22:23], s[20:21], 19
	s_add_u32 s28, s30, s22
	s_addc_u32 s29, s31, s23
	s_and_b64 s[22:23], s[0:1], exec
	s_cselect_b32 s21, s29, s3
	s_cselect_b32 s51, s28, s2
	s_add_u32 s14, s14, 0x40080
	s_addc_u32 s15, s15, 0
	s_add_u32 s52, s2, 0x100
	s_addc_u32 s53, s3, 0
	s_mov_b32 s54, -2
	s_waitcnt vmcnt(0)
	ds_read_b128 v[158:161], v154
	ds_read_b128 v[162:165], v154 offset:1024
	ds_read_b128 v[166:169], v154 offset:2048
	ds_read_b128 v[182:185], v154 offset:3072
	ds_read_b128 v[186:189], v155
	ds_read_b128 v[190:193], v155 offset:1024
	ds_read_b128 v[196:199], v155 offset:2048
	ds_read_b128 v[200:203], v155 offset:3072
	s_add_u32 s2, s14, 0xfffc0080
	s_addc_u32 s3, s15, -1
	s_cmp_eq_u32 s54, 12
	s_cselect_b32 s23, s25, s3
	s_cselect_b32 s22, s50, s2
	s_cselect_b32 s3, s21, s53
	s_cselect_b32 s2, s51, s52
	v_lshl_add_u64 v[136:137], s[14:15], 0, v[128:129]
	s_add_i32 m0, s37, 0xc000
	ds_read_b128 v[204:207], v156
	ds_read_b128 v[208:211], v156 offset:1024
	ds_read_b128 v[212:215], v156 offset:2048
	ds_read_b128 v[216:219], v156 offset:3072
	ds_read_b128 v[220:223], v156 offset:4096
	ds_read_b128 v[224:227], v156 offset:5120
	ds_read_b128 v[228:231], v156 offset:6144
	ds_read_b128 v[232:235], v156 offset:7168
	global_load_lds_dwordx4 v[136:137], off
	v_lshl_add_u64 v[136:137], s[14:15], 0, v[130:131]
	s_add_i32 m0, s37, 0xe000
	s_nop 0
	global_load_lds_dwordx4 v[136:137], off
	s_waitcnt vmcnt(8)
	s_waitcnt lgkmcnt(0)
	s_barrier
	s_setprio 1
	s_waitcnt lgkmcnt(0)
	v_mfma_f32_16x16x32_bf16 v[112:115], v[158:161], v[204:207], 0
	v_mfma_f32_16x16x32_bf16 v[108:111], v[166:169], v[204:207], 0
	v_mfma_f32_16x16x32_bf16 v[104:107], v[158:161], v[212:215], 0
	v_mfma_f32_16x16x32_bf16 v[100:103], v[166:169], v[212:215], 0
	v_mfma_f32_16x16x32_bf16 v[92:95], v[158:161], v[220:223], 0
	v_mfma_f32_16x16x32_bf16 v[84:87], v[166:169], v[220:223], 0
	v_mfma_f32_16x16x32_bf16 v[76:79], v[158:161], v[228:231], 0
	v_mfma_f32_16x16x32_bf16 v[68:71], v[166:169], v[228:231], 0
	v_mfma_f32_16x16x32_bf16 v[112:115], v[162:165], v[208:211], v[112:115]
	v_mfma_f32_16x16x32_bf16 v[108:111], v[182:185], v[208:211], v[108:111]
	v_mfma_f32_16x16x32_bf16 v[104:107], v[162:165], v[216:219], v[104:107]
	v_mfma_f32_16x16x32_bf16 v[100:103], v[182:185], v[216:219], v[100:103]
	v_mfma_f32_16x16x32_bf16 v[92:95], v[162:165], v[224:227], v[92:95]
	v_mfma_f32_16x16x32_bf16 v[84:87], v[182:185], v[224:227], v[84:87]
	v_mfma_f32_16x16x32_bf16 v[76:79], v[162:165], v[232:235], v[76:79]
	v_mfma_f32_16x16x32_bf16 v[68:71], v[182:185], v[232:235], v[68:71]
	s_setprio 0
	s_setprio 1
	v_mfma_f32_16x16x32_bf16 v[124:127], v[186:189], v[204:207], 0
	v_mfma_f32_16x16x32_bf16 v[120:123], v[196:199], v[204:207], 0
	v_mfma_f32_16x16x32_bf16 v[116:119], v[186:189], v[212:215], 0
	v_mfma_f32_16x16x32_bf16 v[96:99], v[196:199], v[212:215], 0
	v_mfma_f32_16x16x32_bf16 v[88:91], v[186:189], v[220:223], 0
	v_mfma_f32_16x16x32_bf16 v[80:83], v[196:199], v[220:223], 0
	v_mfma_f32_16x16x32_bf16 v[72:75], v[186:189], v[228:231], 0
	v_mfma_f32_16x16x32_bf16 v[64:67], v[196:199], v[228:231], 0
	v_mfma_f32_16x16x32_bf16 v[124:127], v[190:193], v[208:211], v[124:127]
	v_mfma_f32_16x16x32_bf16 v[120:123], v[200:203], v[208:211], v[120:123]
	v_mfma_f32_16x16x32_bf16 v[116:119], v[190:193], v[216:219], v[116:119]
	v_mfma_f32_16x16x32_bf16 v[96:99], v[200:203], v[216:219], v[96:99]
	v_mfma_f32_16x16x32_bf16 v[88:91], v[190:193], v[224:227], v[88:91]
	v_mfma_f32_16x16x32_bf16 v[80:83], v[200:203], v[224:227], v[80:83]
	v_mfma_f32_16x16x32_bf16 v[72:75], v[190:193], v[232:235], v[72:75]
	v_mfma_f32_16x16x32_bf16 v[64:67], v[200:203], v[232:235], v[64:67]
	s_setprio 0
	s_barrier
	s_add_i32 s55, s46, s34
	v_lshl_add_u64 v[136:137], s[2:3], 0, v[142:143]
	s_mov_b32 m0, s55
	ds_read_b128 v[204:207], v156 offset:16384
	ds_read_b128 v[208:211], v156 offset:17408
	ds_read_b128 v[212:215], v156 offset:18432
	ds_read_b128 v[216:219], v156 offset:19456
	ds_read_b128 v[220:223], v156 offset:20480
	ds_read_b128 v[224:227], v156 offset:21504
	ds_read_b128 v[228:231], v156 offset:22528
	ds_read_b128 v[232:235], v156 offset:23552
	global_load_lds_dwordx4 v[136:137], off
	s_add_i32 m0, s55, 0x2000
	s_add_u32 s56, s2, 0x40000
	v_lshl_add_u64 v[236:237], s[2:3], 0, v[146:147]
	s_addc_u32 s57, s3, 0
	s_add_i32 s55, s47, s34
	global_load_lds_dwordx4 v[236:237], off
	v_lshl_add_u64 v[238:239], s[56:57], 0, v[142:143]
	s_mov_b32 m0, s55
	v_lshl_add_u64 v[240:241], s[22:23], 0, v[144:145]
	global_load_lds_dwordx4 v[238:239], off
	v_lshl_add_u64 v[238:239], s[56:57], 0, v[146:147]
	s_add_i32 m0, s55, 0x2000
	s_nop 0
	global_load_lds_dwordx4 v[238:239], off
	v_lshl_add_u64 v[238:239], s[22:23], 0, v[140:141]
	s_mov_b32 m0, s37
	s_nop 0
	global_load_lds_dwordx4 v[238:239], off
	s_mov_b32 m0, s38
	s_nop 0
	global_load_lds_dwordx4 v[240:241], off
	s_waitcnt vmcnt(8)
	s_waitcnt lgkmcnt(0)
	s_barrier
	s_setprio 1
	s_waitcnt lgkmcnt(0)
	v_mfma_f32_16x16x32_bf16 v[60:63], v[158:161], v[204:207], 0
	v_mfma_f32_16x16x32_bf16 v[52:55], v[166:169], v[204:207], 0
	v_mfma_f32_16x16x32_bf16 v[44:47], v[158:161], v[212:215], 0
	v_mfma_f32_16x16x32_bf16 v[36:39], v[166:169], v[212:215], 0
	v_mfma_f32_16x16x32_bf16 v[28:31], v[158:161], v[220:223], 0
	v_mfma_f32_16x16x32_bf16 v[20:23], v[166:169], v[220:223], 0
	v_mfma_f32_16x16x32_bf16 v[12:15], v[158:161], v[228:231], 0
	v_mfma_f32_16x16x32_bf16 v[4:7], v[166:169], v[228:231], 0
	v_mfma_f32_16x16x32_bf16 v[60:63], v[162:165], v[208:211], v[60:63]
	v_mfma_f32_16x16x32_bf16 v[52:55], v[182:185], v[208:211], v[52:55]
	v_mfma_f32_16x16x32_bf16 v[44:47], v[162:165], v[216:219], v[44:47]
	v_mfma_f32_16x16x32_bf16 v[36:39], v[182:185], v[216:219], v[36:39]
	v_mfma_f32_16x16x32_bf16 v[28:31], v[162:165], v[224:227], v[28:31]
	v_mfma_f32_16x16x32_bf16 v[20:23], v[182:185], v[224:227], v[20:23]
	v_mfma_f32_16x16x32_bf16 v[12:15], v[162:165], v[232:235], v[12:15]
	v_mfma_f32_16x16x32_bf16 v[4:7], v[182:185], v[232:235], v[4:7]
	s_setprio 0
	s_setprio 1
	v_mfma_f32_16x16x32_bf16 v[56:59], v[186:189], v[204:207], 0
	v_mfma_f32_16x16x32_bf16 v[48:51], v[196:199], v[204:207], 0
	v_mfma_f32_16x16x32_bf16 v[40:43], v[186:189], v[212:215], 0
	v_mfma_f32_16x16x32_bf16 v[32:35], v[196:199], v[212:215], 0
	v_mfma_f32_16x16x32_bf16 v[24:27], v[186:189], v[220:223], 0
	v_mfma_f32_16x16x32_bf16 v[16:19], v[196:199], v[220:223], 0
	v_mfma_f32_16x16x32_bf16 v[8:11], v[186:189], v[228:231], 0
	v_mfma_f32_16x16x32_bf16 v[0:3], v[196:199], v[228:231], 0
	v_mfma_f32_16x16x32_bf16 v[56:59], v[190:193], v[208:211], v[56:59]
	v_mfma_f32_16x16x32_bf16 v[48:51], v[200:203], v[208:211], v[48:51]
	v_mfma_f32_16x16x32_bf16 v[40:43], v[190:193], v[216:219], v[40:43]
	v_mfma_f32_16x16x32_bf16 v[32:35], v[200:203], v[216:219], v[32:35]
	v_mfma_f32_16x16x32_bf16 v[24:27], v[190:193], v[224:227], v[24:27]
	v_mfma_f32_16x16x32_bf16 v[16:19], v[200:203], v[224:227], v[16:19]
	v_mfma_f32_16x16x32_bf16 v[8:11], v[190:193], v[232:235], v[8:11]
	v_mfma_f32_16x16x32_bf16 v[0:3], v[200:203], v[232:235], v[0:3]
	s_setprio 0
	s_barrier
	s_add_i32 s55, 0, 0x18000
	s_add_i32 s56, 0, 0x1c000
	v_add_u32_e32 v182, s55, v139
	v_add_u32_e32 v200, s56, v139
	ds_read_b128 v[158:161], v182
	ds_read_b128 v[162:165], v182 offset:1024
	ds_read_b128 v[166:169], v182 offset:2048
	ds_read_b128 v[182:185], v182 offset:3072
	ds_read_b128 v[186:189], v200
	ds_read_b128 v[190:193], v200 offset:1024
	ds_read_b128 v[196:199], v200 offset:2048
	ds_read_b128 v[200:203], v200 offset:3072
	s_add_u32 s22, s22, 0x40000
	s_addc_u32 s23, s23, 0
	s_mov_b32 m0, s39
	v_lshl_add_u64 v[242:243], s[22:23], 0, v[140:141]
	ds_read_b128 v[204:207], v156 offset:32768
	ds_read_b128 v[208:211], v156 offset:33792
	ds_read_b128 v[212:215], v156 offset:34816
	ds_read_b128 v[216:219], v156 offset:35840
	ds_read_b128 v[220:223], v156 offset:36864
	ds_read_b128 v[224:227], v156 offset:37888
	ds_read_b128 v[228:231], v156 offset:38912
	ds_read_b128 v[232:235], v156 offset:39936
	global_load_lds_dwordx4 v[242:243], off
	v_lshl_add_u64 v[242:243], s[22:23], 0, v[144:145]
	s_mov_b32 m0, s40
	s_nop 0
	global_load_lds_dwordx4 v[242:243], off
	s_waitcnt vmcnt(8)
	s_waitcnt lgkmcnt(0)
	s_barrier
	s_setprio 1
	s_waitcnt lgkmcnt(0)
	v_mfma_f32_16x16x32_bf16 v[112:115], v[158:161], v[204:207], v[112:115]
	v_mfma_f32_16x16x32_bf16 v[108:111], v[166:169], v[204:207], v[108:111]
	v_mfma_f32_16x16x32_bf16 v[104:107], v[158:161], v[212:215], v[104:107]
	v_mfma_f32_16x16x32_bf16 v[100:103], v[166:169], v[212:215], v[100:103]
	v_mfma_f32_16x16x32_bf16 v[92:95], v[158:161], v[220:223], v[92:95]
	v_mfma_f32_16x16x32_bf16 v[84:87], v[166:169], v[220:223], v[84:87]
	v_mfma_f32_16x16x32_bf16 v[76:79], v[158:161], v[228:231], v[76:79]
	v_mfma_f32_16x16x32_bf16 v[68:71], v[166:169], v[228:231], v[68:71]
	v_mfma_f32_16x16x32_bf16 v[112:115], v[162:165], v[208:211], v[112:115]
	v_mfma_f32_16x16x32_bf16 v[108:111], v[182:185], v[208:211], v[108:111]
	v_mfma_f32_16x16x32_bf16 v[104:107], v[162:165], v[216:219], v[104:107]
	v_mfma_f32_16x16x32_bf16 v[100:103], v[182:185], v[216:219], v[100:103]
	v_mfma_f32_16x16x32_bf16 v[92:95], v[162:165], v[224:227], v[92:95]
	v_mfma_f32_16x16x32_bf16 v[84:87], v[182:185], v[224:227], v[84:87]
	v_mfma_f32_16x16x32_bf16 v[76:79], v[162:165], v[232:235], v[76:79]
	v_mfma_f32_16x16x32_bf16 v[68:71], v[182:185], v[232:235], v[68:71]
	s_setprio 0
	s_setprio 1
	v_mfma_f32_16x16x32_bf16 v[124:127], v[186:189], v[204:207], v[124:127]
	v_mfma_f32_16x16x32_bf16 v[120:123], v[196:199], v[204:207], v[120:123]
	v_mfma_f32_16x16x32_bf16 v[116:119], v[186:189], v[212:215], v[116:119]
	v_mfma_f32_16x16x32_bf16 v[96:99], v[196:199], v[212:215], v[96:99]
	v_mfma_f32_16x16x32_bf16 v[88:91], v[186:189], v[220:223], v[88:91]
	v_mfma_f32_16x16x32_bf16 v[80:83], v[196:199], v[220:223], v[80:83]
	v_mfma_f32_16x16x32_bf16 v[72:75], v[186:189], v[228:231], v[72:75]
	v_mfma_f32_16x16x32_bf16 v[64:67], v[196:199], v[228:231], v[64:67]
	v_mfma_f32_16x16x32_bf16 v[124:127], v[190:193], v[208:211], v[124:127]
	v_mfma_f32_16x16x32_bf16 v[120:123], v[200:203], v[208:211], v[120:123]
	v_mfma_f32_16x16x32_bf16 v[116:119], v[190:193], v[216:219], v[116:119]
	v_mfma_f32_16x16x32_bf16 v[96:99], v[200:203], v[216:219], v[96:99]
	v_mfma_f32_16x16x32_bf16 v[88:91], v[190:193], v[224:227], v[88:91]
	v_mfma_f32_16x16x32_bf16 v[80:83], v[200:203], v[224:227], v[80:83]
	v_mfma_f32_16x16x32_bf16 v[72:75], v[190:193], v[232:235], v[72:75]
	v_mfma_f32_16x16x32_bf16 v[64:67], v[200:203], v[232:235], v[64:67]
	s_setprio 0
	s_barrier
	s_add_i32 s22, s55, s34
	v_lshl_add_u64 v[136:137], v[136:137], 0, s[8:9]
	s_mov_b32 m0, s22
	ds_read_b128 v[204:207], v156 offset:49152
	ds_read_b128 v[208:211], v156 offset:50176
	ds_read_b128 v[212:215], v156 offset:51200
	ds_read_b128 v[216:219], v156 offset:52224
	ds_read_b128 v[220:223], v156 offset:53248
	ds_read_b128 v[224:227], v156 offset:54272
	ds_read_b128 v[228:231], v156 offset:55296
	ds_read_b128 v[232:235], v156 offset:56320
	global_load_lds_dwordx4 v[136:137], off
	s_add_i32 m0, s22, 0x2000
	s_add_u32 s2, s2, 0x40080
	v_lshl_add_u64 v[136:137], v[236:237], 0, s[8:9]
	s_addc_u32 s3, s3, 0
	s_add_i32 s22, s56, s34
	global_load_lds_dwordx4 v[136:137], off
	v_lshl_add_u64 v[136:137], s[2:3], 0, v[142:143]
	s_mov_b32 m0, s22
	s_nop 0
	global_load_lds_dwordx4 v[136:137], off
	v_lshl_add_u64 v[136:137], s[2:3], 0, v[146:147]
	s_add_i32 m0, s22, 0x2000
	s_nop 0
	global_load_lds_dwordx4 v[136:137], off
	v_lshl_add_u64 v[136:137], v[238:239], 0, s[8:9]
	s_mov_b32 m0, s42
	s_nop 0
	global_load_lds_dwordx4 v[136:137], off
	v_lshl_add_u64 v[136:137], v[240:241], 0, s[8:9]
	s_mov_b32 m0, s43
	s_nop 0
	global_load_lds_dwordx4 v[136:137], off
	s_waitcnt vmcnt(8)
	s_waitcnt lgkmcnt(0)
	s_barrier
	s_setprio 1
	s_waitcnt lgkmcnt(0)
	v_mfma_f32_16x16x32_bf16 v[60:63], v[158:161], v[204:207], v[60:63]
	v_mfma_f32_16x16x32_bf16 v[52:55], v[166:169], v[204:207], v[52:55]
	v_mfma_f32_16x16x32_bf16 v[44:47], v[158:161], v[212:215], v[44:47]
	v_mfma_f32_16x16x32_bf16 v[36:39], v[166:169], v[212:215], v[36:39]
	v_mfma_f32_16x16x32_bf16 v[28:31], v[158:161], v[220:223], v[28:31]
	v_mfma_f32_16x16x32_bf16 v[20:23], v[166:169], v[220:223], v[20:23]
	v_mfma_f32_16x16x32_bf16 v[12:15], v[158:161], v[228:231], v[12:15]
	v_mfma_f32_16x16x32_bf16 v[4:7], v[166:169], v[228:231], v[4:7]
	v_mfma_f32_16x16x32_bf16 v[60:63], v[162:165], v[208:211], v[60:63]
	v_mfma_f32_16x16x32_bf16 v[52:55], v[182:185], v[208:211], v[52:55]
	v_mfma_f32_16x16x32_bf16 v[44:47], v[162:165], v[216:219], v[44:47]
	v_mfma_f32_16x16x32_bf16 v[36:39], v[182:185], v[216:219], v[36:39]
	v_mfma_f32_16x16x32_bf16 v[28:31], v[162:165], v[224:227], v[28:31]
	v_mfma_f32_16x16x32_bf16 v[20:23], v[182:185], v[224:227], v[20:23]
	v_mfma_f32_16x16x32_bf16 v[12:15], v[162:165], v[232:235], v[12:15]
	v_mfma_f32_16x16x32_bf16 v[4:7], v[182:185], v[232:235], v[4:7]
	s_setprio 0
	s_setprio 1
	v_mfma_f32_16x16x32_bf16 v[56:59], v[186:189], v[204:207], v[56:59]
	v_mfma_f32_16x16x32_bf16 v[48:51], v[196:199], v[204:207], v[48:51]
	v_mfma_f32_16x16x32_bf16 v[40:43], v[186:189], v[212:215], v[40:43]
	v_mfma_f32_16x16x32_bf16 v[32:35], v[196:199], v[212:215], v[32:35]
	v_mfma_f32_16x16x32_bf16 v[24:27], v[186:189], v[220:223], v[24:27]
	v_mfma_f32_16x16x32_bf16 v[16:19], v[196:199], v[220:223], v[16:19]
	v_mfma_f32_16x16x32_bf16 v[8:11], v[186:189], v[228:231], v[8:11]
	v_mfma_f32_16x16x32_bf16 v[0:3], v[196:199], v[228:231], v[0:3]
	v_mfma_f32_16x16x32_bf16 v[56:59], v[190:193], v[208:211], v[56:59]
	v_mfma_f32_16x16x32_bf16 v[48:51], v[200:203], v[208:211], v[48:51]
	v_mfma_f32_16x16x32_bf16 v[40:43], v[190:193], v[216:219], v[40:43]
	v_mfma_f32_16x16x32_bf16 v[32:35], v[200:203], v[216:219], v[32:35]
	v_mfma_f32_16x16x32_bf16 v[24:27], v[190:193], v[224:227], v[24:27]
	v_mfma_f32_16x16x32_bf16 v[16:19], v[200:203], v[224:227], v[16:19]
	v_mfma_f32_16x16x32_bf16 v[8:11], v[190:193], v[232:235], v[8:11]
	v_mfma_f32_16x16x32_bf16 v[0:3], v[200:203], v[232:235], v[0:3]
	s_setprio 0
	s_add_i32 s54, s54, 2
	s_add_u32 s14, s14, 0x100
	s_addc_u32 s15, s15, 0
	s_add_u32 s52, s52, 0x100
	s_addc_u32 s53, s53, 0
	s_cmp_gt_u32 s54, 13
	s_barrier
	s_cbranch_scc1 .Lgemm_kdone_1
.LBB0_368:
	ds_read_b128 v[158:161], v154
	ds_read_b128 v[162:165], v154 offset:1024
	ds_read_b128 v[166:169], v154 offset:2048
	ds_read_b128 v[182:185], v154 offset:3072
	ds_read_b128 v[186:189], v155
	ds_read_b128 v[190:193], v155 offset:1024
	ds_read_b128 v[196:199], v155 offset:2048
	ds_read_b128 v[200:203], v155 offset:3072
	s_add_u32 s2, s14, 0xfffc0080
	s_addc_u32 s3, s15, -1
	s_cmp_eq_u32 s54, 12
	s_cselect_b32 s23, s25, s3
	s_cselect_b32 s22, s50, s2
	s_cselect_b32 s3, s21, s53
	s_cselect_b32 s2, s51, s52
	v_lshl_add_u64 v[136:137], s[14:15], 0, v[128:129]
	s_add_i32 m0, s37, 0xc000
	ds_read_b128 v[204:207], v156
	ds_read_b128 v[208:211], v156 offset:1024
	ds_read_b128 v[212:215], v156 offset:2048
	ds_read_b128 v[216:219], v156 offset:3072
	ds_read_b128 v[220:223], v156 offset:4096
	ds_read_b128 v[224:227], v156 offset:5120
	ds_read_b128 v[228:231], v156 offset:6144
	ds_read_b128 v[232:235], v156 offset:7168
	global_load_lds_dwordx4 v[136:137], off
	v_lshl_add_u64 v[136:137], s[14:15], 0, v[130:131]
	s_add_i32 m0, s37, 0xe000
	s_nop 0
	global_load_lds_dwordx4 v[136:137], off
	s_waitcnt vmcnt(8)
	s_waitcnt lgkmcnt(0)
	s_barrier
	s_setprio 1
	s_waitcnt lgkmcnt(0)
	v_mfma_f32_16x16x32_bf16 v[112:115], v[158:161], v[204:207], v[112:115]
	v_mfma_f32_16x16x32_bf16 v[108:111], v[166:169], v[204:207], v[108:111]
	v_mfma_f32_16x16x32_bf16 v[104:107], v[158:161], v[212:215], v[104:107]
	v_mfma_f32_16x16x32_bf16 v[100:103], v[166:169], v[212:215], v[100:103]
	v_mfma_f32_16x16x32_bf16 v[92:95], v[158:161], v[220:223], v[92:95]
	v_mfma_f32_16x16x32_bf16 v[84:87], v[166:169], v[220:223], v[84:87]
	v_mfma_f32_16x16x32_bf16 v[76:79], v[158:161], v[228:231], v[76:79]
	v_mfma_f32_16x16x32_bf16 v[68:71], v[166:169], v[228:231], v[68:71]
	v_mfma_f32_16x16x32_bf16 v[112:115], v[162:165], v[208:211], v[112:115]
	v_mfma_f32_16x16x32_bf16 v[108:111], v[182:185], v[208:211], v[108:111]
	v_mfma_f32_16x16x32_bf16 v[104:107], v[162:165], v[216:219], v[104:107]
	v_mfma_f32_16x16x32_bf16 v[100:103], v[182:185], v[216:219], v[100:103]
	v_mfma_f32_16x16x32_bf16 v[92:95], v[162:165], v[224:227], v[92:95]
	v_mfma_f32_16x16x32_bf16 v[84:87], v[182:185], v[224:227], v[84:87]
	v_mfma_f32_16x16x32_bf16 v[76:79], v[162:165], v[232:235], v[76:79]
	v_mfma_f32_16x16x32_bf16 v[68:71], v[182:185], v[232:235], v[68:71]
	s_setprio 0
	s_setprio 1
	v_mfma_f32_16x16x32_bf16 v[124:127], v[186:189], v[204:207], v[124:127]
	v_mfma_f32_16x16x32_bf16 v[120:123], v[196:199], v[204:207], v[120:123]
	v_mfma_f32_16x16x32_bf16 v[116:119], v[186:189], v[212:215], v[116:119]
	v_mfma_f32_16x16x32_bf16 v[96:99], v[196:199], v[212:215], v[96:99]
	v_mfma_f32_16x16x32_bf16 v[88:91], v[186:189], v[220:223], v[88:91]
	v_mfma_f32_16x16x32_bf16 v[80:83], v[196:199], v[220:223], v[80:83]
	v_mfma_f32_16x16x32_bf16 v[72:75], v[186:189], v[228:231], v[72:75]
	v_mfma_f32_16x16x32_bf16 v[64:67], v[196:199], v[228:231], v[64:67]
	v_mfma_f32_16x16x32_bf16 v[124:127], v[190:193], v[208:211], v[124:127]
	v_mfma_f32_16x16x32_bf16 v[120:123], v[200:203], v[208:211], v[120:123]
	v_mfma_f32_16x16x32_bf16 v[116:119], v[190:193], v[216:219], v[116:119]
	v_mfma_f32_16x16x32_bf16 v[96:99], v[200:203], v[216:219], v[96:99]
	v_mfma_f32_16x16x32_bf16 v[88:91], v[190:193], v[224:227], v[88:91]
	v_mfma_f32_16x16x32_bf16 v[80:83], v[200:203], v[224:227], v[80:83]
	v_mfma_f32_16x16x32_bf16 v[72:75], v[190:193], v[232:235], v[72:75]
	v_mfma_f32_16x16x32_bf16 v[64:67], v[200:203], v[232:235], v[64:67]
	s_setprio 0
	s_barrier
	s_add_i32 s55, s46, s34
	v_lshl_add_u64 v[136:137], s[2:3], 0, v[142:143]
	s_mov_b32 m0, s55
	ds_read_b128 v[204:207], v156 offset:16384
	ds_read_b128 v[208:211], v156 offset:17408
	ds_read_b128 v[212:215], v156 offset:18432
	ds_read_b128 v[216:219], v156 offset:19456
	ds_read_b128 v[220:223], v156 offset:20480
	ds_read_b128 v[224:227], v156 offset:21504
	ds_read_b128 v[228:231], v156 offset:22528
	ds_read_b128 v[232:235], v156 offset:23552
	global_load_lds_dwordx4 v[136:137], off
	s_add_i32 m0, s55, 0x2000
	s_add_u32 s56, s2, 0x40000
	v_lshl_add_u64 v[236:237], s[2:3], 0, v[146:147]
	s_addc_u32 s57, s3, 0
	s_add_i32 s55, s47, s34
	global_load_lds_dwordx4 v[236:237], off
	v_lshl_add_u64 v[238:239], s[56:57], 0, v[142:143]
	s_mov_b32 m0, s55
	v_lshl_add_u64 v[240:241], s[22:23], 0, v[144:145]
	global_load_lds_dwordx4 v[238:239], off
	v_lshl_add_u64 v[238:239], s[56:57], 0, v[146:147]
	s_add_i32 m0, s55, 0x2000
	s_nop 0
	global_load_lds_dwordx4 v[238:239], off
	v_lshl_add_u64 v[238:239], s[22:23], 0, v[140:141]
	s_mov_b32 m0, s37
	s_nop 0
	global_load_lds_dwordx4 v[238:239], off
	s_mov_b32 m0, s38
	s_nop 0
	global_load_lds_dwordx4 v[240:241], off
	s_waitcnt vmcnt(8)
	s_waitcnt lgkmcnt(0)
	s_barrier
	s_setprio 1
	s_waitcnt lgkmcnt(0)
	v_mfma_f32_16x16x32_bf16 v[60:63], v[158:161], v[204:207], v[60:63]
	v_mfma_f32_16x16x32_bf16 v[52:55], v[166:169], v[204:207], v[52:55]
	v_mfma_f32_16x16x32_bf16 v[44:47], v[158:161], v[212:215], v[44:47]
	v_mfma_f32_16x16x32_bf16 v[36:39], v[166:169], v[212:215], v[36:39]
	v_mfma_f32_16x16x32_bf16 v[28:31], v[158:161], v[220:223], v[28:31]
	v_mfma_f32_16x16x32_bf16 v[20:23], v[166:169], v[220:223], v[20:23]
	v_mfma_f32_16x16x32_bf16 v[12:15], v[158:161], v[228:231], v[12:15]
	v_mfma_f32_16x16x32_bf16 v[4:7], v[166:169], v[228:231], v[4:7]
	v_mfma_f32_16x16x32_bf16 v[60:63], v[162:165], v[208:211], v[60:63]
	v_mfma_f32_16x16x32_bf16 v[52:55], v[182:185], v[208:211], v[52:55]
	v_mfma_f32_16x16x32_bf16 v[44:47], v[162:165], v[216:219], v[44:47]
	v_mfma_f32_16x16x32_bf16 v[36:39], v[182:185], v[216:219], v[36:39]
	v_mfma_f32_16x16x32_bf16 v[28:31], v[162:165], v[224:227], v[28:31]
	v_mfma_f32_16x16x32_bf16 v[20:23], v[182:185], v[224:227], v[20:23]
	v_mfma_f32_16x16x32_bf16 v[12:15], v[162:165], v[232:235], v[12:15]
	v_mfma_f32_16x16x32_bf16 v[4:7], v[182:185], v[232:235], v[4:7]
	s_setprio 0
	s_setprio 1
	v_mfma_f32_16x16x32_bf16 v[56:59], v[186:189], v[204:207], v[56:59]
	v_mfma_f32_16x16x32_bf16 v[48:51], v[196:199], v[204:207], v[48:51]
	v_mfma_f32_16x16x32_bf16 v[40:43], v[186:189], v[212:215], v[40:43]
	v_mfma_f32_16x16x32_bf16 v[32:35], v[196:199], v[212:215], v[32:35]
	v_mfma_f32_16x16x32_bf16 v[24:27], v[186:189], v[220:223], v[24:27]
	v_mfma_f32_16x16x32_bf16 v[16:19], v[196:199], v[220:223], v[16:19]
	v_mfma_f32_16x16x32_bf16 v[8:11], v[186:189], v[228:231], v[8:11]
	v_mfma_f32_16x16x32_bf16 v[0:3], v[196:199], v[228:231], v[0:3]
	v_mfma_f32_16x16x32_bf16 v[56:59], v[190:193], v[208:211], v[56:59]
	v_mfma_f32_16x16x32_bf16 v[48:51], v[200:203], v[208:211], v[48:51]
	v_mfma_f32_16x16x32_bf16 v[40:43], v[190:193], v[216:219], v[40:43]
	v_mfma_f32_16x16x32_bf16 v[32:35], v[200:203], v[216:219], v[32:35]
	v_mfma_f32_16x16x32_bf16 v[24:27], v[190:193], v[224:227], v[24:27]
	v_mfma_f32_16x16x32_bf16 v[16:19], v[200:203], v[224:227], v[16:19]
	v_mfma_f32_16x16x32_bf16 v[8:11], v[190:193], v[232:235], v[8:11]
	v_mfma_f32_16x16x32_bf16 v[0:3], v[200:203], v[232:235], v[0:3]
	s_setprio 0
	s_barrier
	s_add_i32 s55, 0, 0x18000
	s_add_i32 s56, 0, 0x1c000
	v_add_u32_e32 v182, s55, v139
	v_add_u32_e32 v200, s56, v139
	ds_read_b128 v[158:161], v182
	ds_read_b128 v[162:165], v182 offset:1024
	ds_read_b128 v[166:169], v182 offset:2048
	ds_read_b128 v[182:185], v182 offset:3072
	ds_read_b128 v[186:189], v200
	ds_read_b128 v[190:193], v200 offset:1024
	ds_read_b128 v[196:199], v200 offset:2048
	ds_read_b128 v[200:203], v200 offset:3072
	s_add_u32 s22, s22, 0x40000
	s_addc_u32 s23, s23, 0
	s_mov_b32 m0, s39
	v_lshl_add_u64 v[242:243], s[22:23], 0, v[140:141]
	ds_read_b128 v[204:207], v156 offset:32768
	ds_read_b128 v[208:211], v156 offset:33792
	ds_read_b128 v[212:215], v156 offset:34816
	ds_read_b128 v[216:219], v156 offset:35840
	ds_read_b128 v[220:223], v156 offset:36864
	ds_read_b128 v[224:227], v156 offset:37888
	ds_read_b128 v[228:231], v156 offset:38912
	ds_read_b128 v[232:235], v156 offset:39936
	global_load_lds_dwordx4 v[242:243], off
	v_lshl_add_u64 v[242:243], s[22:23], 0, v[144:145]
	s_mov_b32 m0, s40
	s_nop 0
	global_load_lds_dwordx4 v[242:243], off
	s_waitcnt vmcnt(8)
	s_waitcnt lgkmcnt(0)
	s_barrier
	s_setprio 1
	s_waitcnt lgkmcnt(0)
	v_mfma_f32_16x16x32_bf16 v[112:115], v[158:161], v[204:207], v[112:115]
	v_mfma_f32_16x16x32_bf16 v[108:111], v[166:169], v[204:207], v[108:111]
	v_mfma_f32_16x16x32_bf16 v[104:107], v[158:161], v[212:215], v[104:107]
	v_mfma_f32_16x16x32_bf16 v[100:103], v[166:169], v[212:215], v[100:103]
	v_mfma_f32_16x16x32_bf16 v[92:95], v[158:161], v[220:223], v[92:95]
	v_mfma_f32_16x16x32_bf16 v[84:87], v[166:169], v[220:223], v[84:87]
	v_mfma_f32_16x16x32_bf16 v[76:79], v[158:161], v[228:231], v[76:79]
	v_mfma_f32_16x16x32_bf16 v[68:71], v[166:169], v[228:231], v[68:71]
	v_mfma_f32_16x16x32_bf16 v[112:115], v[162:165], v[208:211], v[112:115]
	v_mfma_f32_16x16x32_bf16 v[108:111], v[182:185], v[208:211], v[108:111]
	v_mfma_f32_16x16x32_bf16 v[104:107], v[162:165], v[216:219], v[104:107]
	v_mfma_f32_16x16x32_bf16 v[100:103], v[182:185], v[216:219], v[100:103]
	v_mfma_f32_16x16x32_bf16 v[92:95], v[162:165], v[224:227], v[92:95]
	v_mfma_f32_16x16x32_bf16 v[84:87], v[182:185], v[224:227], v[84:87]
	v_mfma_f32_16x16x32_bf16 v[76:79], v[162:165], v[232:235], v[76:79]
	v_mfma_f32_16x16x32_bf16 v[68:71], v[182:185], v[232:235], v[68:71]
	s_setprio 0
	s_setprio 1
	v_mfma_f32_16x16x32_bf16 v[124:127], v[186:189], v[204:207], v[124:127]
	v_mfma_f32_16x16x32_bf16 v[120:123], v[196:199], v[204:207], v[120:123]
	v_mfma_f32_16x16x32_bf16 v[116:119], v[186:189], v[212:215], v[116:119]
	v_mfma_f32_16x16x32_bf16 v[96:99], v[196:199], v[212:215], v[96:99]
	v_mfma_f32_16x16x32_bf16 v[88:91], v[186:189], v[220:223], v[88:91]
	v_mfma_f32_16x16x32_bf16 v[80:83], v[196:199], v[220:223], v[80:83]
	v_mfma_f32_16x16x32_bf16 v[72:75], v[186:189], v[228:231], v[72:75]
	v_mfma_f32_16x16x32_bf16 v[64:67], v[196:199], v[228:231], v[64:67]
	v_mfma_f32_16x16x32_bf16 v[124:127], v[190:193], v[208:211], v[124:127]
	v_mfma_f32_16x16x32_bf16 v[120:123], v[200:203], v[208:211], v[120:123]
	v_mfma_f32_16x16x32_bf16 v[116:119], v[190:193], v[216:219], v[116:119]
	v_mfma_f32_16x16x32_bf16 v[96:99], v[200:203], v[216:219], v[96:99]
	v_mfma_f32_16x16x32_bf16 v[88:91], v[190:193], v[224:227], v[88:91]
	v_mfma_f32_16x16x32_bf16 v[80:83], v[200:203], v[224:227], v[80:83]
	v_mfma_f32_16x16x32_bf16 v[72:75], v[190:193], v[232:235], v[72:75]
	v_mfma_f32_16x16x32_bf16 v[64:67], v[200:203], v[232:235], v[64:67]
	s_setprio 0
	s_barrier
	s_add_i32 s22, s55, s34
	v_lshl_add_u64 v[136:137], v[136:137], 0, s[8:9]
	s_mov_b32 m0, s22
	ds_read_b128 v[204:207], v156 offset:49152
	ds_read_b128 v[208:211], v156 offset:50176
	ds_read_b128 v[212:215], v156 offset:51200
	ds_read_b128 v[216:219], v156 offset:52224
	ds_read_b128 v[220:223], v156 offset:53248
	ds_read_b128 v[224:227], v156 offset:54272
	ds_read_b128 v[228:231], v156 offset:55296
	ds_read_b128 v[232:235], v156 offset:56320
	global_load_lds_dwordx4 v[136:137], off
	s_add_i32 m0, s22, 0x2000
	s_add_u32 s2, s2, 0x40080
	v_lshl_add_u64 v[136:137], v[236:237], 0, s[8:9]
	s_addc_u32 s3, s3, 0
	s_add_i32 s22, s56, s34
	global_load_lds_dwordx4 v[136:137], off
	v_lshl_add_u64 v[136:137], s[2:3], 0, v[142:143]
	s_mov_b32 m0, s22
	s_nop 0
	global_load_lds_dwordx4 v[136:137], off
	v_lshl_add_u64 v[136:137], s[2:3], 0, v[146:147]
	s_add_i32 m0, s22, 0x2000
	s_nop 0
	global_load_lds_dwordx4 v[136:137], off
	v_lshl_add_u64 v[136:137], v[238:239], 0, s[8:9]
	s_mov_b32 m0, s42
	s_nop 0
	global_load_lds_dwordx4 v[136:137], off
	v_lshl_add_u64 v[136:137], v[240:241], 0, s[8:9]
	s_mov_b32 m0, s43
	s_nop 0
	global_load_lds_dwordx4 v[136:137], off
	s_waitcnt vmcnt(8)
	s_waitcnt lgkmcnt(0)
	s_barrier
	s_setprio 1
	s_waitcnt lgkmcnt(0)
	v_mfma_f32_16x16x32_bf16 v[60:63], v[158:161], v[204:207], v[60:63]
	v_mfma_f32_16x16x32_bf16 v[52:55], v[166:169], v[204:207], v[52:55]
	v_mfma_f32_16x16x32_bf16 v[44:47], v[158:161], v[212:215], v[44:47]
	v_mfma_f32_16x16x32_bf16 v[36:39], v[166:169], v[212:215], v[36:39]
	v_mfma_f32_16x16x32_bf16 v[28:31], v[158:161], v[220:223], v[28:31]
	v_mfma_f32_16x16x32_bf16 v[20:23], v[166:169], v[220:223], v[20:23]
	v_mfma_f32_16x16x32_bf16 v[12:15], v[158:161], v[228:231], v[12:15]
	v_mfma_f32_16x16x32_bf16 v[4:7], v[166:169], v[228:231], v[4:7]
	v_mfma_f32_16x16x32_bf16 v[60:63], v[162:165], v[208:211], v[60:63]
	v_mfma_f32_16x16x32_bf16 v[52:55], v[182:185], v[208:211], v[52:55]
	v_mfma_f32_16x16x32_bf16 v[44:47], v[162:165], v[216:219], v[44:47]
	v_mfma_f32_16x16x32_bf16 v[36:39], v[182:185], v[216:219], v[36:39]
	v_mfma_f32_16x16x32_bf16 v[28:31], v[162:165], v[224:227], v[28:31]
	v_mfma_f32_16x16x32_bf16 v[20:23], v[182:185], v[224:227], v[20:23]
	v_mfma_f32_16x16x32_bf16 v[12:15], v[162:165], v[232:235], v[12:15]
	v_mfma_f32_16x16x32_bf16 v[4:7], v[182:185], v[232:235], v[4:7]
	s_setprio 0
	s_setprio 1
	v_mfma_f32_16x16x32_bf16 v[56:59], v[186:189], v[204:207], v[56:59]
	v_mfma_f32_16x16x32_bf16 v[48:51], v[196:199], v[204:207], v[48:51]
	v_mfma_f32_16x16x32_bf16 v[40:43], v[186:189], v[212:215], v[40:43]
	v_mfma_f32_16x16x32_bf16 v[32:35], v[196:199], v[212:215], v[32:35]
	v_mfma_f32_16x16x32_bf16 v[24:27], v[186:189], v[220:223], v[24:27]
	v_mfma_f32_16x16x32_bf16 v[16:19], v[196:199], v[220:223], v[16:19]
	v_mfma_f32_16x16x32_bf16 v[8:11], v[186:189], v[228:231], v[8:11]
	v_mfma_f32_16x16x32_bf16 v[0:3], v[196:199], v[228:231], v[0:3]
	v_mfma_f32_16x16x32_bf16 v[56:59], v[190:193], v[208:211], v[56:59]
	v_mfma_f32_16x16x32_bf16 v[48:51], v[200:203], v[208:211], v[48:51]
	v_mfma_f32_16x16x32_bf16 v[40:43], v[190:193], v[216:219], v[40:43]
	v_mfma_f32_16x16x32_bf16 v[32:35], v[200:203], v[216:219], v[32:35]
	v_mfma_f32_16x16x32_bf16 v[24:27], v[190:193], v[224:227], v[24:27]
	v_mfma_f32_16x16x32_bf16 v[16:19], v[200:203], v[224:227], v[16:19]
	v_mfma_f32_16x16x32_bf16 v[8:11], v[190:193], v[232:235], v[8:11]
	v_mfma_f32_16x16x32_bf16 v[0:3], v[200:203], v[232:235], v[0:3]
	s_setprio 0
	s_add_i32 s54, s54, 2
	s_add_u32 s14, s14, 0x100
	s_addc_u32 s15, s15, 0
	s_add_u32 s52, s52, 0x100
	s_addc_u32 s53, s53, 0
	s_cmp_gt_u32 s54, 13
	s_barrier
	s_cbranch_scc0 .LBB0_368

.LBB0_454:
	s_add_u32 s14, s14, 0xb0080
	s_addc_u32 s15, s15, 0
	s_add_u32 s65, s2, 0x100
	s_addc_u32 s66, s3, 0
	s_mov_b32 s67, -2
	s_waitcnt lgkmcnt(0)
	s_waitcnt vmcnt(0)
	ds_read_b128 v[128:131], v147
	ds_read_b128 v[132:135], v147 offset:1024
	ds_read_b128 v[136:139], v147 offset:2048
	ds_read_b128 v[164:167], v147 offset:3072
	ds_read_b128 v[188:191], v184
	ds_read_b128 v[196:199], v184 offset:1024
	ds_read_b128 v[200:203], v184 offset:2048
	ds_read_b128 v[204:207], v184 offset:3072
	s_add_u32 s2, s14, 0xfff50080
	s_addc_u32 s3, s15, -1
	s_cmp_eq_u32 s67, 40
	s_cselect_b32 s23, s1, s3
	s_cselect_b32 s22, s0, s2
	s_cselect_b32 s3, s31, s66
	s_cselect_b32 s2, s30, s65
	v_lshl_add_u64 v[168:169], s[14:15], 0, v[156:157]
	s_add_i32 m0, s37, 0xc000
	ds_read_b128 v[208:211], v185
	ds_read_b128 v[212:215], v185 offset:1024
	ds_read_b128 v[216:219], v185 offset:2048
	ds_read_b128 v[220:223], v185 offset:3072
	ds_read_b128 v[224:227], v185 offset:4096
	ds_read_b128 v[228:231], v185 offset:5120
	ds_read_b128 v[232:235], v185 offset:6144
	ds_read_b128 v[236:239], v185 offset:7168
	global_load_lds_dwordx4 v[168:169], off
	v_lshl_add_u64 v[168:169], s[14:15], 0, v[158:159]
	s_add_i32 m0, s37, 0xe000
	s_nop 0
	global_load_lds_dwordx4 v[168:169], off
	s_waitcnt vmcnt(8)
	s_waitcnt lgkmcnt(0)
	s_barrier
	s_setprio 1
	s_waitcnt lgkmcnt(0)
	v_mfma_f32_16x16x32_bf16 v[124:127], v[128:131], v[208:211], 0
	v_mfma_f32_16x16x32_bf16 v[120:123], v[136:139], v[208:211], 0
	v_mfma_f32_16x16x32_bf16 v[108:111], v[128:131], v[216:219], 0
	v_mfma_f32_16x16x32_bf16 v[104:107], v[136:139], v[216:219], 0
	v_mfma_f32_16x16x32_bf16 v[92:95], v[128:131], v[224:227], 0
	v_mfma_f32_16x16x32_bf16 v[88:91], v[136:139], v[224:227], 0
	v_mfma_f32_16x16x32_bf16 v[76:79], v[128:131], v[232:235], 0
	v_mfma_f32_16x16x32_bf16 v[72:75], v[136:139], v[232:235], 0
	v_mfma_f32_16x16x32_bf16 v[124:127], v[132:135], v[212:215], v[124:127]
	v_mfma_f32_16x16x32_bf16 v[120:123], v[164:167], v[212:215], v[120:123]
	v_mfma_f32_16x16x32_bf16 v[108:111], v[132:135], v[220:223], v[108:111]
	v_mfma_f32_16x16x32_bf16 v[104:107], v[164:167], v[220:223], v[104:107]
	v_mfma_f32_16x16x32_bf16 v[92:95], v[132:135], v[228:231], v[92:95]
	v_mfma_f32_16x16x32_bf16 v[88:91], v[164:167], v[228:231], v[88:91]
	v_mfma_f32_16x16x32_bf16 v[76:79], v[132:135], v[236:239], v[76:79]
	v_mfma_f32_16x16x32_bf16 v[72:75], v[164:167], v[236:239], v[72:75]
	s_setprio 0
	s_setprio 1
	v_mfma_f32_16x16x32_bf16 v[116:119], v[188:191], v[208:211], 0
	v_mfma_f32_16x16x32_bf16 v[112:115], v[200:203], v[208:211], 0
	v_mfma_f32_16x16x32_bf16 v[100:103], v[188:191], v[216:219], 0
	v_mfma_f32_16x16x32_bf16 v[96:99], v[200:203], v[216:219], 0
	v_mfma_f32_16x16x32_bf16 v[84:87], v[188:191], v[224:227], 0
	v_mfma_f32_16x16x32_bf16 v[80:83], v[200:203], v[224:227], 0
	v_mfma_f32_16x16x32_bf16 v[68:71], v[188:191], v[232:235], 0
	v_mfma_f32_16x16x32_bf16 v[64:67], v[200:203], v[232:235], 0
	v_mfma_f32_16x16x32_bf16 v[116:119], v[196:199], v[212:215], v[116:119]
	v_mfma_f32_16x16x32_bf16 v[112:115], v[204:207], v[212:215], v[112:115]
	v_mfma_f32_16x16x32_bf16 v[100:103], v[196:199], v[220:223], v[100:103]
	v_mfma_f32_16x16x32_bf16 v[96:99], v[204:207], v[220:223], v[96:99]
	v_mfma_f32_16x16x32_bf16 v[84:87], v[196:199], v[228:231], v[84:87]
	v_mfma_f32_16x16x32_bf16 v[80:83], v[204:207], v[228:231], v[80:83]
	v_mfma_f32_16x16x32_bf16 v[68:71], v[196:199], v[236:239], v[68:71]
	v_mfma_f32_16x16x32_bf16 v[64:67], v[204:207], v[236:239], v[64:67]
	s_setprio 0
	s_barrier
	s_add_i32 s68, s51, s36
	v_lshl_add_u64 v[168:169], s[2:3], 0, v[150:151]
	s_mov_b32 m0, s68
	ds_read_b128 v[208:211], v185 offset:16384
	ds_read_b128 v[212:215], v185 offset:17408
	ds_read_b128 v[216:219], v185 offset:18432
	ds_read_b128 v[220:223], v185 offset:19456
	ds_read_b128 v[224:227], v185 offset:20480
	ds_read_b128 v[228:231], v185 offset:21504
	ds_read_b128 v[232:235], v185 offset:22528
	ds_read_b128 v[236:239], v185 offset:23552
	global_load_lds_dwordx4 v[168:169], off
	s_add_i32 m0, s68, 0x2000
	s_add_u32 s68, s2, 0xb0000
	v_lshl_add_u64 v[192:193], s[2:3], 0, v[154:155]
	s_addc_u32 s69, s3, 0
	s_add_i32 s70, s52, s36
	global_load_lds_dwordx4 v[192:193], off
	v_lshl_add_u64 v[240:241], s[68:69], 0, v[150:151]
	s_mov_b32 m0, s70
	v_lshl_add_u64 v[242:243], s[22:23], 0, v[152:153]
	global_load_lds_dwordx4 v[240:241], off
	v_lshl_add_u64 v[240:241], s[68:69], 0, v[154:155]
	s_add_i32 m0, s70, 0x2000
	s_nop 0
	global_load_lds_dwordx4 v[240:241], off
	v_lshl_add_u64 v[240:241], s[22:23], 0, v[148:149]
	s_mov_b32 m0, s37
	s_nop 0
	global_load_lds_dwordx4 v[240:241], off
	s_mov_b32 m0, s38
	s_nop 0
	global_load_lds_dwordx4 v[242:243], off
	s_waitcnt vmcnt(8)
	s_waitcnt lgkmcnt(0)
	s_barrier
	s_setprio 1
	s_waitcnt lgkmcnt(0)
	v_mfma_f32_16x16x32_bf16 v[60:63], v[128:131], v[208:211], 0
	v_mfma_f32_16x16x32_bf16 v[56:59], v[136:139], v[208:211], 0
	v_mfma_f32_16x16x32_bf16 v[44:47], v[128:131], v[216:219], 0
	v_mfma_f32_16x16x32_bf16 v[40:43], v[136:139], v[216:219], 0
	v_mfma_f32_16x16x32_bf16 v[28:31], v[128:131], v[224:227], 0
	v_mfma_f32_16x16x32_bf16 v[24:27], v[136:139], v[224:227], 0
	v_mfma_f32_16x16x32_bf16 v[12:15], v[128:131], v[232:235], 0
	v_mfma_f32_16x16x32_bf16 v[8:11], v[136:139], v[232:235], 0
	v_mfma_f32_16x16x32_bf16 v[60:63], v[132:135], v[212:215], v[60:63]
	v_mfma_f32_16x16x32_bf16 v[56:59], v[164:167], v[212:215], v[56:59]
	v_mfma_f32_16x16x32_bf16 v[44:47], v[132:135], v[220:223], v[44:47]
	v_mfma_f32_16x16x32_bf16 v[40:43], v[164:167], v[220:223], v[40:43]
	v_mfma_f32_16x16x32_bf16 v[28:31], v[132:135], v[228:231], v[28:31]
	v_mfma_f32_16x16x32_bf16 v[24:27], v[164:167], v[228:231], v[24:27]
	v_mfma_f32_16x16x32_bf16 v[12:15], v[132:135], v[236:239], v[12:15]
	v_mfma_f32_16x16x32_bf16 v[8:11], v[164:167], v[236:239], v[8:11]
	s_setprio 0
	s_setprio 1
	v_mfma_f32_16x16x32_bf16 v[52:55], v[188:191], v[208:211], 0
	v_mfma_f32_16x16x32_bf16 v[48:51], v[200:203], v[208:211], 0
	v_mfma_f32_16x16x32_bf16 v[36:39], v[188:191], v[216:219], 0
	v_mfma_f32_16x16x32_bf16 v[32:35], v[200:203], v[216:219], 0
	v_mfma_f32_16x16x32_bf16 v[20:23], v[188:191], v[224:227], 0
	v_mfma_f32_16x16x32_bf16 v[16:19], v[200:203], v[224:227], 0
	v_mfma_f32_16x16x32_bf16 v[4:7], v[188:191], v[232:235], 0
	v_mfma_f32_16x16x32_bf16 v[0:3], v[200:203], v[232:235], 0
	v_mfma_f32_16x16x32_bf16 v[52:55], v[196:199], v[212:215], v[52:55]
	v_mfma_f32_16x16x32_bf16 v[48:51], v[204:207], v[212:215], v[48:51]
	v_mfma_f32_16x16x32_bf16 v[36:39], v[196:199], v[220:223], v[36:39]
	v_mfma_f32_16x16x32_bf16 v[32:35], v[204:207], v[220:223], v[32:35]
	v_mfma_f32_16x16x32_bf16 v[20:23], v[196:199], v[228:231], v[20:23]
	v_mfma_f32_16x16x32_bf16 v[16:19], v[204:207], v[228:231], v[16:19]
	v_mfma_f32_16x16x32_bf16 v[4:7], v[196:199], v[236:239], v[4:7]
	v_mfma_f32_16x16x32_bf16 v[0:3], v[204:207], v[236:239], v[0:3]
	s_setprio 0
	s_barrier
	s_add_i32 s68, 0, 0x18000
	s_add_i32 s69, 0, 0x1c000
	v_add_u32_e32 v164, s68, v141
	v_add_u32_e32 v187, s69, v141
	ds_read_b128 v[128:131], v164
	ds_read_b128 v[132:135], v164 offset:1024
	ds_read_b128 v[136:139], v164 offset:2048
	ds_read_b128 v[164:167], v164 offset:3072
	ds_read_b128 v[188:191], v187
	ds_read_b128 v[196:199], v187 offset:1024
	ds_read_b128 v[200:203], v187 offset:2048
	ds_read_b128 v[204:207], v187 offset:3072
	s_add_u32 s22, s22, 0xb0000
	s_addc_u32 s23, s23, 0
	s_mov_b32 m0, s39
	v_lshl_add_u64 v[244:245], s[22:23], 0, v[148:149]
	ds_read_b128 v[208:211], v185 offset:32768
	ds_read_b128 v[212:215], v185 offset:33792
	ds_read_b128 v[216:219], v185 offset:34816
	ds_read_b128 v[220:223], v185 offset:35840
	ds_read_b128 v[224:227], v185 offset:36864
	ds_read_b128 v[228:231], v185 offset:37888
	ds_read_b128 v[232:235], v185 offset:38912
	ds_read_b128 v[236:239], v185 offset:39936
	global_load_lds_dwordx4 v[244:245], off
	v_lshl_add_u64 v[244:245], s[22:23], 0, v[152:153]
	s_mov_b32 m0, s40
	s_nop 0
	global_load_lds_dwordx4 v[244:245], off
	s_waitcnt vmcnt(8)
	s_waitcnt lgkmcnt(0)
	s_barrier
	s_setprio 1
	s_waitcnt lgkmcnt(0)
	v_mfma_f32_16x16x32_bf16 v[124:127], v[128:131], v[208:211], v[124:127]
	v_mfma_f32_16x16x32_bf16 v[120:123], v[136:139], v[208:211], v[120:123]
	v_mfma_f32_16x16x32_bf16 v[108:111], v[128:131], v[216:219], v[108:111]
	v_mfma_f32_16x16x32_bf16 v[104:107], v[136:139], v[216:219], v[104:107]
	v_mfma_f32_16x16x32_bf16 v[92:95], v[128:131], v[224:227], v[92:95]
	v_mfma_f32_16x16x32_bf16 v[88:91], v[136:139], v[224:227], v[88:91]
	v_mfma_f32_16x16x32_bf16 v[76:79], v[128:131], v[232:235], v[76:79]
	v_mfma_f32_16x16x32_bf16 v[72:75], v[136:139], v[232:235], v[72:75]
	v_mfma_f32_16x16x32_bf16 v[124:127], v[132:135], v[212:215], v[124:127]
	v_mfma_f32_16x16x32_bf16 v[120:123], v[164:167], v[212:215], v[120:123]
	v_mfma_f32_16x16x32_bf16 v[108:111], v[132:135], v[220:223], v[108:111]
	v_mfma_f32_16x16x32_bf16 v[104:107], v[164:167], v[220:223], v[104:107]
	v_mfma_f32_16x16x32_bf16 v[92:95], v[132:135], v[228:231], v[92:95]
	v_mfma_f32_16x16x32_bf16 v[88:91], v[164:167], v[228:231], v[88:91]
	v_mfma_f32_16x16x32_bf16 v[76:79], v[132:135], v[236:239], v[76:79]
	v_mfma_f32_16x16x32_bf16 v[72:75], v[164:167], v[236:239], v[72:75]
	s_setprio 0
	s_setprio 1
	v_mfma_f32_16x16x32_bf16 v[116:119], v[188:191], v[208:211], v[116:119]
	v_mfma_f32_16x16x32_bf16 v[112:115], v[200:203], v[208:211], v[112:115]
	v_mfma_f32_16x16x32_bf16 v[100:103], v[188:191], v[216:219], v[100:103]
	v_mfma_f32_16x16x32_bf16 v[96:99], v[200:203], v[216:219], v[96:99]
	v_mfma_f32_16x16x32_bf16 v[84:87], v[188:191], v[224:227], v[84:87]
	v_mfma_f32_16x16x32_bf16 v[80:83], v[200:203], v[224:227], v[80:83]
	v_mfma_f32_16x16x32_bf16 v[68:71], v[188:191], v[232:235], v[68:71]
	v_mfma_f32_16x16x32_bf16 v[64:67], v[200:203], v[232:235], v[64:67]
	v_mfma_f32_16x16x32_bf16 v[116:119], v[196:199], v[212:215], v[116:119]
	v_mfma_f32_16x16x32_bf16 v[112:115], v[204:207], v[212:215], v[112:115]
	v_mfma_f32_16x16x32_bf16 v[100:103], v[196:199], v[220:223], v[100:103]
	v_mfma_f32_16x16x32_bf16 v[96:99], v[204:207], v[220:223], v[96:99]
	v_mfma_f32_16x16x32_bf16 v[84:87], v[196:199], v[228:231], v[84:87]
	v_mfma_f32_16x16x32_bf16 v[80:83], v[204:207], v[228:231], v[80:83]
	v_mfma_f32_16x16x32_bf16 v[68:71], v[196:199], v[236:239], v[68:71]
	v_mfma_f32_16x16x32_bf16 v[64:67], v[204:207], v[236:239], v[64:67]
	s_setprio 0
	s_barrier
	s_add_i32 s22, s68, s36
	v_lshl_add_u64 v[168:169], v[168:169], 0, s[26:27]
	s_mov_b32 m0, s22
	ds_read_b128 v[208:211], v185 offset:49152
	ds_read_b128 v[212:215], v185 offset:50176
	ds_read_b128 v[216:219], v185 offset:51200
	ds_read_b128 v[220:223], v185 offset:52224
	ds_read_b128 v[224:227], v185 offset:53248
	ds_read_b128 v[228:231], v185 offset:54272
	ds_read_b128 v[232:235], v185 offset:55296
	ds_read_b128 v[236:239], v185 offset:56320
	global_load_lds_dwordx4 v[168:169], off
	s_add_i32 m0, s22, 0x2000
	s_add_u32 s2, s2, 0xb0080
	v_lshl_add_u64 v[168:169], v[192:193], 0, s[26:27]
	s_addc_u32 s3, s3, 0
	s_add_i32 s22, s69, s36
	global_load_lds_dwordx4 v[168:169], off
	v_lshl_add_u64 v[168:169], s[2:3], 0, v[150:151]
	s_mov_b32 m0, s22
	s_nop 0
	global_load_lds_dwordx4 v[168:169], off
	v_lshl_add_u64 v[168:169], s[2:3], 0, v[154:155]
	s_add_i32 m0, s22, 0x2000
	s_nop 0
	global_load_lds_dwordx4 v[168:169], off
	v_lshl_add_u64 v[168:169], v[240:241], 0, s[26:27]
	s_mov_b32 m0, s44
	s_nop 0
	global_load_lds_dwordx4 v[168:169], off
	v_lshl_add_u64 v[168:169], v[242:243], 0, s[26:27]
	s_mov_b32 m0, s45
	s_nop 0
	global_load_lds_dwordx4 v[168:169], off
	s_waitcnt vmcnt(8)
	s_waitcnt lgkmcnt(0)
	s_barrier
	s_setprio 1
	s_waitcnt lgkmcnt(0)
	v_mfma_f32_16x16x32_bf16 v[60:63], v[128:131], v[208:211], v[60:63]
	v_mfma_f32_16x16x32_bf16 v[56:59], v[136:139], v[208:211], v[56:59]
	v_mfma_f32_16x16x32_bf16 v[44:47], v[128:131], v[216:219], v[44:47]
	v_mfma_f32_16x16x32_bf16 v[40:43], v[136:139], v[216:219], v[40:43]
	v_mfma_f32_16x16x32_bf16 v[28:31], v[128:131], v[224:227], v[28:31]
	v_mfma_f32_16x16x32_bf16 v[24:27], v[136:139], v[224:227], v[24:27]
	v_mfma_f32_16x16x32_bf16 v[12:15], v[128:131], v[232:235], v[12:15]
	v_mfma_f32_16x16x32_bf16 v[8:11], v[136:139], v[232:235], v[8:11]
	v_mfma_f32_16x16x32_bf16 v[60:63], v[132:135], v[212:215], v[60:63]
	v_mfma_f32_16x16x32_bf16 v[56:59], v[164:167], v[212:215], v[56:59]
	v_mfma_f32_16x16x32_bf16 v[44:47], v[132:135], v[220:223], v[44:47]
	v_mfma_f32_16x16x32_bf16 v[40:43], v[164:167], v[220:223], v[40:43]
	v_mfma_f32_16x16x32_bf16 v[28:31], v[132:135], v[228:231], v[28:31]
	v_mfma_f32_16x16x32_bf16 v[24:27], v[164:167], v[228:231], v[24:27]
	v_mfma_f32_16x16x32_bf16 v[12:15], v[132:135], v[236:239], v[12:15]
	v_mfma_f32_16x16x32_bf16 v[8:11], v[164:167], v[236:239], v[8:11]
	s_setprio 0
	s_setprio 1
	v_mfma_f32_16x16x32_bf16 v[52:55], v[188:191], v[208:211], v[52:55]
	v_mfma_f32_16x16x32_bf16 v[48:51], v[200:203], v[208:211], v[48:51]
	v_mfma_f32_16x16x32_bf16 v[36:39], v[188:191], v[216:219], v[36:39]
	v_mfma_f32_16x16x32_bf16 v[32:35], v[200:203], v[216:219], v[32:35]
	v_mfma_f32_16x16x32_bf16 v[20:23], v[188:191], v[224:227], v[20:23]
	v_mfma_f32_16x16x32_bf16 v[16:19], v[200:203], v[224:227], v[16:19]
	v_mfma_f32_16x16x32_bf16 v[4:7], v[188:191], v[232:235], v[4:7]
	v_mfma_f32_16x16x32_bf16 v[0:3], v[200:203], v[232:235], v[0:3]
	v_mfma_f32_16x16x32_bf16 v[52:55], v[196:199], v[212:215], v[52:55]
	v_mfma_f32_16x16x32_bf16 v[48:51], v[204:207], v[212:215], v[48:51]
	v_mfma_f32_16x16x32_bf16 v[36:39], v[196:199], v[220:223], v[36:39]
	v_mfma_f32_16x16x32_bf16 v[32:35], v[204:207], v[220:223], v[32:35]
	v_mfma_f32_16x16x32_bf16 v[20:23], v[196:199], v[228:231], v[20:23]
	v_mfma_f32_16x16x32_bf16 v[16:19], v[204:207], v[228:231], v[16:19]
	v_mfma_f32_16x16x32_bf16 v[4:7], v[196:199], v[236:239], v[4:7]
	v_mfma_f32_16x16x32_bf16 v[0:3], v[204:207], v[236:239], v[0:3]
	s_setprio 0
	s_add_i32 s67, s67, 2
	s_add_u32 s14, s14, 0x100
	s_addc_u32 s15, s15, 0
	s_add_u32 s65, s65, 0x100
	s_addc_u32 s66, s66, 0
	s_cmp_gt_u32 s67, 41
	s_barrier
	s_cbranch_scc1 .Lgemm_kdone_2
.LBB0_455:
	ds_read_b128 v[128:131], v147
	ds_read_b128 v[132:135], v147 offset:1024
	ds_read_b128 v[136:139], v147 offset:2048
	ds_read_b128 v[164:167], v147 offset:3072
	ds_read_b128 v[188:191], v184
	ds_read_b128 v[196:199], v184 offset:1024
	ds_read_b128 v[200:203], v184 offset:2048
	ds_read_b128 v[204:207], v184 offset:3072
	s_add_u32 s2, s14, 0xfff50080
	s_addc_u32 s3, s15, -1
	s_cmp_eq_u32 s67, 40
	s_cselect_b32 s23, s1, s3
	s_cselect_b32 s22, s0, s2
	s_cselect_b32 s3, s31, s66
	s_cselect_b32 s2, s30, s65
	v_lshl_add_u64 v[168:169], s[14:15], 0, v[156:157]
	s_add_i32 m0, s37, 0xc000
	ds_read_b128 v[208:211], v185
	ds_read_b128 v[212:215], v185 offset:1024
	ds_read_b128 v[216:219], v185 offset:2048
	ds_read_b128 v[220:223], v185 offset:3072
	ds_read_b128 v[224:227], v185 offset:4096
	ds_read_b128 v[228:231], v185 offset:5120
	ds_read_b128 v[232:235], v185 offset:6144
	ds_read_b128 v[236:239], v185 offset:7168
	global_load_lds_dwordx4 v[168:169], off
	v_lshl_add_u64 v[168:169], s[14:15], 0, v[158:159]
	s_add_i32 m0, s37, 0xe000
	s_nop 0
	global_load_lds_dwordx4 v[168:169], off
	s_waitcnt vmcnt(8)
	s_waitcnt lgkmcnt(0)
	s_barrier
	s_setprio 1
	s_waitcnt lgkmcnt(0)
	v_mfma_f32_16x16x32_bf16 v[124:127], v[128:131], v[208:211], v[124:127]
	v_mfma_f32_16x16x32_bf16 v[120:123], v[136:139], v[208:211], v[120:123]
	v_mfma_f32_16x16x32_bf16 v[108:111], v[128:131], v[216:219], v[108:111]
	v_mfma_f32_16x16x32_bf16 v[104:107], v[136:139], v[216:219], v[104:107]
	v_mfma_f32_16x16x32_bf16 v[92:95], v[128:131], v[224:227], v[92:95]
	v_mfma_f32_16x16x32_bf16 v[88:91], v[136:139], v[224:227], v[88:91]
	v_mfma_f32_16x16x32_bf16 v[76:79], v[128:131], v[232:235], v[76:79]
	v_mfma_f32_16x16x32_bf16 v[72:75], v[136:139], v[232:235], v[72:75]
	v_mfma_f32_16x16x32_bf16 v[124:127], v[132:135], v[212:215], v[124:127]
	v_mfma_f32_16x16x32_bf16 v[120:123], v[164:167], v[212:215], v[120:123]
	v_mfma_f32_16x16x32_bf16 v[108:111], v[132:135], v[220:223], v[108:111]
	v_mfma_f32_16x16x32_bf16 v[104:107], v[164:167], v[220:223], v[104:107]
	v_mfma_f32_16x16x32_bf16 v[92:95], v[132:135], v[228:231], v[92:95]
	v_mfma_f32_16x16x32_bf16 v[88:91], v[164:167], v[228:231], v[88:91]
	v_mfma_f32_16x16x32_bf16 v[76:79], v[132:135], v[236:239], v[76:79]
	v_mfma_f32_16x16x32_bf16 v[72:75], v[164:167], v[236:239], v[72:75]
	s_setprio 0
	s_setprio 1
	v_mfma_f32_16x16x32_bf16 v[116:119], v[188:191], v[208:211], v[116:119]
	v_mfma_f32_16x16x32_bf16 v[112:115], v[200:203], v[208:211], v[112:115]
	v_mfma_f32_16x16x32_bf16 v[100:103], v[188:191], v[216:219], v[100:103]
	v_mfma_f32_16x16x32_bf16 v[96:99], v[200:203], v[216:219], v[96:99]
	v_mfma_f32_16x16x32_bf16 v[84:87], v[188:191], v[224:227], v[84:87]
	v_mfma_f32_16x16x32_bf16 v[80:83], v[200:203], v[224:227], v[80:83]
	v_mfma_f32_16x16x32_bf16 v[68:71], v[188:191], v[232:235], v[68:71]
	v_mfma_f32_16x16x32_bf16 v[64:67], v[200:203], v[232:235], v[64:67]
	v_mfma_f32_16x16x32_bf16 v[116:119], v[196:199], v[212:215], v[116:119]
	v_mfma_f32_16x16x32_bf16 v[112:115], v[204:207], v[212:215], v[112:115]
	v_mfma_f32_16x16x32_bf16 v[100:103], v[196:199], v[220:223], v[100:103]
	v_mfma_f32_16x16x32_bf16 v[96:99], v[204:207], v[220:223], v[96:99]
	v_mfma_f32_16x16x32_bf16 v[84:87], v[196:199], v[228:231], v[84:87]
	v_mfma_f32_16x16x32_bf16 v[80:83], v[204:207], v[228:231], v[80:83]
	v_mfma_f32_16x16x32_bf16 v[68:71], v[196:199], v[236:239], v[68:71]
	v_mfma_f32_16x16x32_bf16 v[64:67], v[204:207], v[236:239], v[64:67]
	s_setprio 0
	s_barrier
	s_add_i32 s68, s51, s36
	v_lshl_add_u64 v[168:169], s[2:3], 0, v[150:151]
	s_mov_b32 m0, s68
	ds_read_b128 v[208:211], v185 offset:16384
	ds_read_b128 v[212:215], v185 offset:17408
	ds_read_b128 v[216:219], v185 offset:18432
	ds_read_b128 v[220:223], v185 offset:19456
	ds_read_b128 v[224:227], v185 offset:20480
	ds_read_b128 v[228:231], v185 offset:21504
	ds_read_b128 v[232:235], v185 offset:22528
	ds_read_b128 v[236:239], v185 offset:23552
	global_load_lds_dwordx4 v[168:169], off
	s_add_i32 m0, s68, 0x2000
	s_add_u32 s68, s2, 0xb0000
	v_lshl_add_u64 v[192:193], s[2:3], 0, v[154:155]
	s_addc_u32 s69, s3, 0
	s_add_i32 s70, s52, s36
	global_load_lds_dwordx4 v[192:193], off
	v_lshl_add_u64 v[240:241], s[68:69], 0, v[150:151]
	s_mov_b32 m0, s70
	v_lshl_add_u64 v[242:243], s[22:23], 0, v[152:153]
	global_load_lds_dwordx4 v[240:241], off
	v_lshl_add_u64 v[240:241], s[68:69], 0, v[154:155]
	s_add_i32 m0, s70, 0x2000
	s_nop 0
	global_load_lds_dwordx4 v[240:241], off
	v_lshl_add_u64 v[240:241], s[22:23], 0, v[148:149]
	s_mov_b32 m0, s37
	s_nop 0
	global_load_lds_dwordx4 v[240:241], off
	s_mov_b32 m0, s38
	s_nop 0
	global_load_lds_dwordx4 v[242:243], off
	s_waitcnt vmcnt(8)
	s_waitcnt lgkmcnt(0)
	s_barrier
	s_setprio 1
	s_waitcnt lgkmcnt(0)
	v_mfma_f32_16x16x32_bf16 v[60:63], v[128:131], v[208:211], v[60:63]
	v_mfma_f32_16x16x32_bf16 v[56:59], v[136:139], v[208:211], v[56:59]
	v_mfma_f32_16x16x32_bf16 v[44:47], v[128:131], v[216:219], v[44:47]
	v_mfma_f32_16x16x32_bf16 v[40:43], v[136:139], v[216:219], v[40:43]
	v_mfma_f32_16x16x32_bf16 v[28:31], v[128:131], v[224:227], v[28:31]
	v_mfma_f32_16x16x32_bf16 v[24:27], v[136:139], v[224:227], v[24:27]
	v_mfma_f32_16x16x32_bf16 v[12:15], v[128:131], v[232:235], v[12:15]
	v_mfma_f32_16x16x32_bf16 v[8:11], v[136:139], v[232:235], v[8:11]
	v_mfma_f32_16x16x32_bf16 v[60:63], v[132:135], v[212:215], v[60:63]
	v_mfma_f32_16x16x32_bf16 v[56:59], v[164:167], v[212:215], v[56:59]
	v_mfma_f32_16x16x32_bf16 v[44:47], v[132:135], v[220:223], v[44:47]
	v_mfma_f32_16x16x32_bf16 v[40:43], v[164:167], v[220:223], v[40:43]
	v_mfma_f32_16x16x32_bf16 v[28:31], v[132:135], v[228:231], v[28:31]
	v_mfma_f32_16x16x32_bf16 v[24:27], v[164:167], v[228:231], v[24:27]
	v_mfma_f32_16x16x32_bf16 v[12:15], v[132:135], v[236:239], v[12:15]
	v_mfma_f32_16x16x32_bf16 v[8:11], v[164:167], v[236:239], v[8:11]
	s_setprio 0
	s_setprio 1
	v_mfma_f32_16x16x32_bf16 v[52:55], v[188:191], v[208:211], v[52:55]
	v_mfma_f32_16x16x32_bf16 v[48:51], v[200:203], v[208:211], v[48:51]
	v_mfma_f32_16x16x32_bf16 v[36:39], v[188:191], v[216:219], v[36:39]
	v_mfma_f32_16x16x32_bf16 v[32:35], v[200:203], v[216:219], v[32:35]
	v_mfma_f32_16x16x32_bf16 v[20:23], v[188:191], v[224:227], v[20:23]
	v_mfma_f32_16x16x32_bf16 v[16:19], v[200:203], v[224:227], v[16:19]
	v_mfma_f32_16x16x32_bf16 v[4:7], v[188:191], v[232:235], v[4:7]
	v_mfma_f32_16x16x32_bf16 v[0:3], v[200:203], v[232:235], v[0:3]
	v_mfma_f32_16x16x32_bf16 v[52:55], v[196:199], v[212:215], v[52:55]
	v_mfma_f32_16x16x32_bf16 v[48:51], v[204:207], v[212:215], v[48:51]
	v_mfma_f32_16x16x32_bf16 v[36:39], v[196:199], v[220:223], v[36:39]
	v_mfma_f32_16x16x32_bf16 v[32:35], v[204:207], v[220:223], v[32:35]
	v_mfma_f32_16x16x32_bf16 v[20:23], v[196:199], v[228:231], v[20:23]
	v_mfma_f32_16x16x32_bf16 v[16:19], v[204:207], v[228:231], v[16:19]
	v_mfma_f32_16x16x32_bf16 v[4:7], v[196:199], v[236:239], v[4:7]
	v_mfma_f32_16x16x32_bf16 v[0:3], v[204:207], v[236:239], v[0:3]
	s_setprio 0
	s_barrier
	s_add_i32 s68, 0, 0x18000
	s_add_i32 s69, 0, 0x1c000
	v_add_u32_e32 v164, s68, v141
	v_add_u32_e32 v187, s69, v141
	ds_read_b128 v[128:131], v164
	ds_read_b128 v[132:135], v164 offset:1024
	ds_read_b128 v[136:139], v164 offset:2048
	ds_read_b128 v[164:167], v164 offset:3072
	ds_read_b128 v[188:191], v187
	ds_read_b128 v[196:199], v187 offset:1024
	ds_read_b128 v[200:203], v187 offset:2048
	ds_read_b128 v[204:207], v187 offset:3072
	s_add_u32 s22, s22, 0xb0000
	s_addc_u32 s23, s23, 0
	s_mov_b32 m0, s39
	v_lshl_add_u64 v[244:245], s[22:23], 0, v[148:149]
	ds_read_b128 v[208:211], v185 offset:32768
	ds_read_b128 v[212:215], v185 offset:33792
	ds_read_b128 v[216:219], v185 offset:34816
	ds_read_b128 v[220:223], v185 offset:35840
	ds_read_b128 v[224:227], v185 offset:36864
	ds_read_b128 v[228:231], v185 offset:37888
	ds_read_b128 v[232:235], v185 offset:38912
	ds_read_b128 v[236:239], v185 offset:39936
	global_load_lds_dwordx4 v[244:245], off
	v_lshl_add_u64 v[244:245], s[22:23], 0, v[152:153]
	s_mov_b32 m0, s40
	s_nop 0
	global_load_lds_dwordx4 v[244:245], off
	s_waitcnt vmcnt(8)
	s_waitcnt lgkmcnt(0)
	s_barrier
	s_setprio 1
	s_waitcnt lgkmcnt(0)
	v_mfma_f32_16x16x32_bf16 v[124:127], v[128:131], v[208:211], v[124:127]
	v_mfma_f32_16x16x32_bf16 v[120:123], v[136:139], v[208:211], v[120:123]
	v_mfma_f32_16x16x32_bf16 v[108:111], v[128:131], v[216:219], v[108:111]
	v_mfma_f32_16x16x32_bf16 v[104:107], v[136:139], v[216:219], v[104:107]
	v_mfma_f32_16x16x32_bf16 v[92:95], v[128:131], v[224:227], v[92:95]
	v_mfma_f32_16x16x32_bf16 v[88:91], v[136:139], v[224:227], v[88:91]
	v_mfma_f32_16x16x32_bf16 v[76:79], v[128:131], v[232:235], v[76:79]
	v_mfma_f32_16x16x32_bf16 v[72:75], v[136:139], v[232:235], v[72:75]
	v_mfma_f32_16x16x32_bf16 v[124:127], v[132:135], v[212:215], v[124:127]
	v_mfma_f32_16x16x32_bf16 v[120:123], v[164:167], v[212:215], v[120:123]
	v_mfma_f32_16x16x32_bf16 v[108:111], v[132:135], v[220:223], v[108:111]
	v_mfma_f32_16x16x32_bf16 v[104:107], v[164:167], v[220:223], v[104:107]
	v_mfma_f32_16x16x32_bf16 v[92:95], v[132:135], v[228:231], v[92:95]
	v_mfma_f32_16x16x32_bf16 v[88:91], v[164:167], v[228:231], v[88:91]
	v_mfma_f32_16x16x32_bf16 v[76:79], v[132:135], v[236:239], v[76:79]
	v_mfma_f32_16x16x32_bf16 v[72:75], v[164:167], v[236:239], v[72:75]
	s_setprio 0
	s_setprio 1
	v_mfma_f32_16x16x32_bf16 v[116:119], v[188:191], v[208:211], v[116:119]
	v_mfma_f32_16x16x32_bf16 v[112:115], v[200:203], v[208:211], v[112:115]
	v_mfma_f32_16x16x32_bf16 v[100:103], v[188:191], v[216:219], v[100:103]
	v_mfma_f32_16x16x32_bf16 v[96:99], v[200:203], v[216:219], v[96:99]
	v_mfma_f32_16x16x32_bf16 v[84:87], v[188:191], v[224:227], v[84:87]
	v_mfma_f32_16x16x32_bf16 v[80:83], v[200:203], v[224:227], v[80:83]
	v_mfma_f32_16x16x32_bf16 v[68:71], v[188:191], v[232:235], v[68:71]
	v_mfma_f32_16x16x32_bf16 v[64:67], v[200:203], v[232:235], v[64:67]
	v_mfma_f32_16x16x32_bf16 v[116:119], v[196:199], v[212:215], v[116:119]
	v_mfma_f32_16x16x32_bf16 v[112:115], v[204:207], v[212:215], v[112:115]
	v_mfma_f32_16x16x32_bf16 v[100:103], v[196:199], v[220:223], v[100:103]
	v_mfma_f32_16x16x32_bf16 v[96:99], v[204:207], v[220:223], v[96:99]
	v_mfma_f32_16x16x32_bf16 v[84:87], v[196:199], v[228:231], v[84:87]
	v_mfma_f32_16x16x32_bf16 v[80:83], v[204:207], v[228:231], v[80:83]
	v_mfma_f32_16x16x32_bf16 v[68:71], v[196:199], v[236:239], v[68:71]
	v_mfma_f32_16x16x32_bf16 v[64:67], v[204:207], v[236:239], v[64:67]
	s_setprio 0
	s_barrier
	s_add_i32 s22, s68, s36
	v_lshl_add_u64 v[168:169], v[168:169], 0, s[26:27]
	s_mov_b32 m0, s22
	ds_read_b128 v[208:211], v185 offset:49152
	ds_read_b128 v[212:215], v185 offset:50176
	ds_read_b128 v[216:219], v185 offset:51200
	ds_read_b128 v[220:223], v185 offset:52224
	ds_read_b128 v[224:227], v185 offset:53248
	ds_read_b128 v[228:231], v185 offset:54272
	ds_read_b128 v[232:235], v185 offset:55296
	ds_read_b128 v[236:239], v185 offset:56320
	global_load_lds_dwordx4 v[168:169], off
	s_add_i32 m0, s22, 0x2000
	s_add_u32 s2, s2, 0xb0080
	v_lshl_add_u64 v[168:169], v[192:193], 0, s[26:27]
	s_addc_u32 s3, s3, 0
	s_add_i32 s22, s69, s36
	global_load_lds_dwordx4 v[168:169], off
	v_lshl_add_u64 v[168:169], s[2:3], 0, v[150:151]
	s_mov_b32 m0, s22
	s_nop 0
	global_load_lds_dwordx4 v[168:169], off
	v_lshl_add_u64 v[168:169], s[2:3], 0, v[154:155]
	s_add_i32 m0, s22, 0x2000
	s_nop 0
	global_load_lds_dwordx4 v[168:169], off
	v_lshl_add_u64 v[168:169], v[240:241], 0, s[26:27]
	s_mov_b32 m0, s44
	s_nop 0
	global_load_lds_dwordx4 v[168:169], off
	v_lshl_add_u64 v[168:169], v[242:243], 0, s[26:27]
	s_mov_b32 m0, s45
	s_nop 0
	global_load_lds_dwordx4 v[168:169], off
	s_waitcnt vmcnt(8)
	s_waitcnt lgkmcnt(0)
	s_barrier
	s_setprio 1
	s_waitcnt lgkmcnt(0)
	v_mfma_f32_16x16x32_bf16 v[60:63], v[128:131], v[208:211], v[60:63]
	v_mfma_f32_16x16x32_bf16 v[56:59], v[136:139], v[208:211], v[56:59]
	v_mfma_f32_16x16x32_bf16 v[44:47], v[128:131], v[216:219], v[44:47]
	v_mfma_f32_16x16x32_bf16 v[40:43], v[136:139], v[216:219], v[40:43]
	v_mfma_f32_16x16x32_bf16 v[28:31], v[128:131], v[224:227], v[28:31]
	v_mfma_f32_16x16x32_bf16 v[24:27], v[136:139], v[224:227], v[24:27]
	v_mfma_f32_16x16x32_bf16 v[12:15], v[128:131], v[232:235], v[12:15]
	v_mfma_f32_16x16x32_bf16 v[8:11], v[136:139], v[232:235], v[8:11]
	v_mfma_f32_16x16x32_bf16 v[60:63], v[132:135], v[212:215], v[60:63]
	v_mfma_f32_16x16x32_bf16 v[56:59], v[164:167], v[212:215], v[56:59]
	v_mfma_f32_16x16x32_bf16 v[44:47], v[132:135], v[220:223], v[44:47]
	v_mfma_f32_16x16x32_bf16 v[40:43], v[164:167], v[220:223], v[40:43]
	v_mfma_f32_16x16x32_bf16 v[28:31], v[132:135], v[228:231], v[28:31]
	v_mfma_f32_16x16x32_bf16 v[24:27], v[164:167], v[228:231], v[24:27]
	v_mfma_f32_16x16x32_bf16 v[12:15], v[132:135], v[236:239], v[12:15]
	v_mfma_f32_16x16x32_bf16 v[8:11], v[164:167], v[236:239], v[8:11]
	s_setprio 0
	s_setprio 1
	v_mfma_f32_16x16x32_bf16 v[52:55], v[188:191], v[208:211], v[52:55]
	v_mfma_f32_16x16x32_bf16 v[48:51], v[200:203], v[208:211], v[48:51]
	v_mfma_f32_16x16x32_bf16 v[36:39], v[188:191], v[216:219], v[36:39]
	v_mfma_f32_16x16x32_bf16 v[32:35], v[200:203], v[216:219], v[32:35]
	v_mfma_f32_16x16x32_bf16 v[20:23], v[188:191], v[224:227], v[20:23]
	v_mfma_f32_16x16x32_bf16 v[16:19], v[200:203], v[224:227], v[16:19]
	v_mfma_f32_16x16x32_bf16 v[4:7], v[188:191], v[232:235], v[4:7]
	v_mfma_f32_16x16x32_bf16 v[0:3], v[200:203], v[232:235], v[0:3]
	v_mfma_f32_16x16x32_bf16 v[52:55], v[196:199], v[212:215], v[52:55]
	v_mfma_f32_16x16x32_bf16 v[48:51], v[204:207], v[212:215], v[48:51]
	v_mfma_f32_16x16x32_bf16 v[36:39], v[196:199], v[220:223], v[36:39]
	v_mfma_f32_16x16x32_bf16 v[32:35], v[204:207], v[220:223], v[32:35]
	v_mfma_f32_16x16x32_bf16 v[20:23], v[196:199], v[228:231], v[20:23]
	v_mfma_f32_16x16x32_bf16 v[16:19], v[204:207], v[228:231], v[16:19]
	v_mfma_f32_16x16x32_bf16 v[4:7], v[196:199], v[236:239], v[4:7]
	v_mfma_f32_16x16x32_bf16 v[0:3], v[204:207], v[236:239], v[0:3]
	s_setprio 0
	s_add_i32 s67, s67, 2
	s_add_u32 s14, s14, 0x100
	s_addc_u32 s15, s15, 0
	s_add_u32 s65, s65, 0x100
	s_addc_u32 s66, s66, 0
	s_cmp_gt_u32 s67, 41
	s_barrier
	s_cbranch_scc0 .LBB0_455

.LBB0_551:
	s_ashr_i32 s41, s40, 31
	s_lshl_b64 s[22:23], s[40:41], 19
	s_add_u32 s42, s84, s22
	s_addc_u32 s43, s85, s23
	s_and_b64 s[22:23], s[4:5], exec
	s_cselect_b32 s41, s43, s15
	s_cselect_b32 s69, s42, s14
	s_ashr_i32 s39, s38, 31
	s_lshl_b64 s[22:23], s[38:39], 19
	s_add_u32 s44, s34, s22
	s_addc_u32 s45, s35, s23
	s_and_b64 s[22:23], s[4:5], exec
	s_cselect_b32 s39, s45, s3
	s_cselect_b32 s70, s44, s2
	s_add_u32 s14, s14, 0x40080
	s_addc_u32 s15, s15, 0
	s_add_u32 s71, s2, 0x100
	s_addc_u32 s72, s3, 0
	s_mov_b32 s73, -2
	s_waitcnt vmcnt(0)
	ds_read_b128 v[156:159], v155
	ds_read_b128 v[160:163], v155 offset:1024
	ds_read_b128 v[184:187], v155 offset:2048
	ds_read_b128 v[188:191], v155 offset:3072
	ds_read_b128 v[196:199], v166
	ds_read_b128 v[200:203], v166 offset:1024
	ds_read_b128 v[204:207], v166 offset:2048
	ds_read_b128 v[208:211], v166 offset:3072
	s_add_u32 s2, s14, 0xfffc0080
	s_addc_u32 s3, s15, -1
	s_cmp_eq_u32 s73, 12
	s_cselect_b32 s23, s41, s3
	s_cselect_b32 s22, s69, s2
	s_cselect_b32 s3, s39, s72
	s_cselect_b32 s2, s70, s71
	v_lshl_add_u64 v[138:139], s[14:15], 0, v[130:131]
	s_add_i32 m0, s49, 0xc000
	ds_read_b128 v[212:215], v167
	ds_read_b128 v[216:219], v167 offset:1024
	ds_read_b128 v[220:223], v167 offset:2048
	ds_read_b128 v[224:227], v167 offset:3072
	ds_read_b128 v[228:231], v167 offset:4096
	ds_read_b128 v[232:235], v167 offset:5120
	ds_read_b128 v[236:239], v167 offset:6144
	ds_read_b128 v[240:243], v167 offset:7168
	global_load_lds_dwordx4 v[138:139], off
	v_lshl_add_u64 v[138:139], s[14:15], 0, v[132:133]
	s_add_i32 m0, s49, 0xe000
	s_nop 0
	global_load_lds_dwordx4 v[138:139], off
	s_waitcnt vmcnt(8)
	s_waitcnt lgkmcnt(0)
	s_barrier
	s_setprio 1
	s_waitcnt lgkmcnt(0)
	v_mfma_f32_16x16x32_bf16 v[124:127], v[156:159], v[212:215], 0
	v_mfma_f32_16x16x32_bf16 v[120:123], v[184:187], v[212:215], 0
	v_mfma_f32_16x16x32_bf16 v[116:119], v[156:159], v[220:223], 0
	v_mfma_f32_16x16x32_bf16 v[112:115], v[184:187], v[220:223], 0
	v_mfma_f32_16x16x32_bf16 v[92:95], v[156:159], v[228:231], 0
	v_mfma_f32_16x16x32_bf16 v[88:91], v[184:187], v[228:231], 0
	v_mfma_f32_16x16x32_bf16 v[76:79], v[156:159], v[236:239], 0
	v_mfma_f32_16x16x32_bf16 v[72:75], v[184:187], v[236:239], 0
	v_mfma_f32_16x16x32_bf16 v[124:127], v[160:163], v[216:219], v[124:127]
	v_mfma_f32_16x16x32_bf16 v[120:123], v[188:191], v[216:219], v[120:123]
	v_mfma_f32_16x16x32_bf16 v[116:119], v[160:163], v[224:227], v[116:119]
	v_mfma_f32_16x16x32_bf16 v[112:115], v[188:191], v[224:227], v[112:115]
	v_mfma_f32_16x16x32_bf16 v[92:95], v[160:163], v[232:235], v[92:95]
	v_mfma_f32_16x16x32_bf16 v[88:91], v[188:191], v[232:235], v[88:91]
	v_mfma_f32_16x16x32_bf16 v[76:79], v[160:163], v[240:243], v[76:79]
	v_mfma_f32_16x16x32_bf16 v[72:75], v[188:191], v[240:243], v[72:75]
	s_setprio 0
	s_setprio 1
	v_mfma_f32_16x16x32_bf16 v[108:111], v[196:199], v[212:215], 0
	v_mfma_f32_16x16x32_bf16 v[104:107], v[204:207], v[212:215], 0
	v_mfma_f32_16x16x32_bf16 v[100:103], v[196:199], v[220:223], 0
	v_mfma_f32_16x16x32_bf16 v[96:99], v[204:207], v[220:223], 0
	v_mfma_f32_16x16x32_bf16 v[84:87], v[196:199], v[228:231], 0
	v_mfma_f32_16x16x32_bf16 v[80:83], v[204:207], v[228:231], 0
	v_mfma_f32_16x16x32_bf16 v[68:71], v[196:199], v[236:239], 0
	v_mfma_f32_16x16x32_bf16 v[64:67], v[204:207], v[236:239], 0
	v_mfma_f32_16x16x32_bf16 v[108:111], v[200:203], v[216:219], v[108:111]
	v_mfma_f32_16x16x32_bf16 v[104:107], v[208:211], v[216:219], v[104:107]
	v_mfma_f32_16x16x32_bf16 v[100:103], v[200:203], v[224:227], v[100:103]
	v_mfma_f32_16x16x32_bf16 v[96:99], v[208:211], v[224:227], v[96:99]
	v_mfma_f32_16x16x32_bf16 v[84:87], v[200:203], v[232:235], v[84:87]
	v_mfma_f32_16x16x32_bf16 v[80:83], v[208:211], v[232:235], v[80:83]
	v_mfma_f32_16x16x32_bf16 v[68:71], v[200:203], v[240:243], v[68:71]
	v_mfma_f32_16x16x32_bf16 v[64:67], v[208:211], v[240:243], v[64:67]
	s_setprio 0
	s_barrier
	s_add_i32 s74, s58, s46
	v_lshl_add_u64 v[138:139], s[2:3], 0, v[142:143]
	s_mov_b32 m0, s74
	ds_read_b128 v[212:215], v167 offset:16384
	ds_read_b128 v[216:219], v167 offset:17408
	ds_read_b128 v[220:223], v167 offset:18432
	ds_read_b128 v[224:227], v167 offset:19456
	ds_read_b128 v[228:231], v167 offset:20480
	ds_read_b128 v[232:235], v167 offset:21504
	ds_read_b128 v[236:239], v167 offset:22528
	ds_read_b128 v[240:243], v167 offset:23552
	global_load_lds_dwordx4 v[138:139], off
	s_add_i32 m0, s74, 0x2000
	s_add_u32 s74, s2, 0x40000
	v_lshl_add_u64 v[164:165], s[2:3], 0, v[146:147]
	s_addc_u32 s75, s3, 0
	s_add_i32 s76, s59, s46
	global_load_lds_dwordx4 v[164:165], off
	v_lshl_add_u64 v[192:193], s[74:75], 0, v[142:143]
	s_mov_b32 m0, s76
	v_lshl_add_u64 v[244:245], s[22:23], 0, v[144:145]
	global_load_lds_dwordx4 v[192:193], off
	v_lshl_add_u64 v[192:193], s[74:75], 0, v[146:147]
	s_add_i32 m0, s76, 0x2000
	s_nop 0
	global_load_lds_dwordx4 v[192:193], off
	v_lshl_add_u64 v[192:193], s[22:23], 0, v[140:141]
	s_mov_b32 m0, s49
	s_nop 0
	global_load_lds_dwordx4 v[192:193], off
	s_mov_b32 m0, s50
	s_nop 0
	global_load_lds_dwordx4 v[244:245], off
	s_waitcnt vmcnt(8)
	s_waitcnt lgkmcnt(0)
	s_barrier
	s_setprio 1
	s_waitcnt lgkmcnt(0)
	v_mfma_f32_16x16x32_bf16 v[60:63], v[156:159], v[212:215], 0
	v_mfma_f32_16x16x32_bf16 v[56:59], v[184:187], v[212:215], 0
	v_mfma_f32_16x16x32_bf16 v[44:47], v[156:159], v[220:223], 0
	v_mfma_f32_16x16x32_bf16 v[40:43], v[184:187], v[220:223], 0
	v_mfma_f32_16x16x32_bf16 v[28:31], v[156:159], v[228:231], 0
	v_mfma_f32_16x16x32_bf16 v[24:27], v[184:187], v[228:231], 0
	v_mfma_f32_16x16x32_bf16 v[12:15], v[156:159], v[236:239], 0
	v_mfma_f32_16x16x32_bf16 v[8:11], v[184:187], v[236:239], 0
	v_mfma_f32_16x16x32_bf16 v[60:63], v[160:163], v[216:219], v[60:63]
	v_mfma_f32_16x16x32_bf16 v[56:59], v[188:191], v[216:219], v[56:59]
	v_mfma_f32_16x16x32_bf16 v[44:47], v[160:163], v[224:227], v[44:47]
	v_mfma_f32_16x16x32_bf16 v[40:43], v[188:191], v[224:227], v[40:43]
	v_mfma_f32_16x16x32_bf16 v[28:31], v[160:163], v[232:235], v[28:31]
	v_mfma_f32_16x16x32_bf16 v[24:27], v[188:191], v[232:235], v[24:27]
	v_mfma_f32_16x16x32_bf16 v[12:15], v[160:163], v[240:243], v[12:15]
	v_mfma_f32_16x16x32_bf16 v[8:11], v[188:191], v[240:243], v[8:11]
	s_setprio 0
	s_setprio 1
	v_mfma_f32_16x16x32_bf16 v[52:55], v[196:199], v[212:215], 0
	v_mfma_f32_16x16x32_bf16 v[48:51], v[204:207], v[212:215], 0
	v_mfma_f32_16x16x32_bf16 v[36:39], v[196:199], v[220:223], 0
	v_mfma_f32_16x16x32_bf16 v[32:35], v[204:207], v[220:223], 0
	v_mfma_f32_16x16x32_bf16 v[20:23], v[196:199], v[228:231], 0
	v_mfma_f32_16x16x32_bf16 v[16:19], v[204:207], v[228:231], 0
	v_mfma_f32_16x16x32_bf16 v[4:7], v[196:199], v[236:239], 0
	v_mfma_f32_16x16x32_bf16 v[0:3], v[204:207], v[236:239], 0
	v_mfma_f32_16x16x32_bf16 v[52:55], v[200:203], v[216:219], v[52:55]
	v_mfma_f32_16x16x32_bf16 v[48:51], v[208:211], v[216:219], v[48:51]
	v_mfma_f32_16x16x32_bf16 v[36:39], v[200:203], v[224:227], v[36:39]
	v_mfma_f32_16x16x32_bf16 v[32:35], v[208:211], v[224:227], v[32:35]
	v_mfma_f32_16x16x32_bf16 v[20:23], v[200:203], v[232:235], v[20:23]
	v_mfma_f32_16x16x32_bf16 v[16:19], v[208:211], v[232:235], v[16:19]
	v_mfma_f32_16x16x32_bf16 v[4:7], v[200:203], v[240:243], v[4:7]
	v_mfma_f32_16x16x32_bf16 v[0:3], v[208:211], v[240:243], v[0:3]
	s_setprio 0
	s_barrier
	s_add_i32 s74, 0, 0x18000
	v_add_u32_e32 v128, s74, v151
	s_add_i32 s75, 0, 0x1c000
	ds_read_b128 v[156:159], v128
	ds_read_b128 v[160:163], v128 offset:1024
	ds_read_b128 v[184:187], v128 offset:2048
	ds_read_b128 v[188:191], v128 offset:3072
	v_add_u32_e32 v128, s75, v151
	ds_read_b128 v[196:199], v128
	ds_read_b128 v[200:203], v128 offset:1024
	ds_read_b128 v[204:207], v128 offset:2048
	ds_read_b128 v[208:211], v128 offset:3072
	s_add_u32 s22, s22, 0x40000
	s_addc_u32 s23, s23, 0
	s_mov_b32 m0, s51
	v_lshl_add_u64 v[246:247], s[22:23], 0, v[140:141]
	ds_read_b128 v[212:215], v167 offset:32768
	ds_read_b128 v[216:219], v167 offset:33792
	ds_read_b128 v[220:223], v167 offset:34816
	ds_read_b128 v[224:227], v167 offset:35840
	ds_read_b128 v[228:231], v167 offset:36864
	ds_read_b128 v[232:235], v167 offset:37888
	ds_read_b128 v[236:239], v167 offset:38912
	ds_read_b128 v[240:243], v167 offset:39936
	global_load_lds_dwordx4 v[246:247], off
	v_lshl_add_u64 v[246:247], s[22:23], 0, v[144:145]
	s_mov_b32 m0, s52
	s_nop 0
	global_load_lds_dwordx4 v[246:247], off
	s_waitcnt vmcnt(8)
	s_waitcnt lgkmcnt(0)
	s_barrier
	s_setprio 1
	s_waitcnt lgkmcnt(0)
	v_mfma_f32_16x16x32_bf16 v[124:127], v[156:159], v[212:215], v[124:127]
	v_mfma_f32_16x16x32_bf16 v[120:123], v[184:187], v[212:215], v[120:123]
	v_mfma_f32_16x16x32_bf16 v[116:119], v[156:159], v[220:223], v[116:119]
	v_mfma_f32_16x16x32_bf16 v[112:115], v[184:187], v[220:223], v[112:115]
	v_mfma_f32_16x16x32_bf16 v[92:95], v[156:159], v[228:231], v[92:95]
	v_mfma_f32_16x16x32_bf16 v[88:91], v[184:187], v[228:231], v[88:91]
	v_mfma_f32_16x16x32_bf16 v[76:79], v[156:159], v[236:239], v[76:79]
	v_mfma_f32_16x16x32_bf16 v[72:75], v[184:187], v[236:239], v[72:75]
	v_mfma_f32_16x16x32_bf16 v[124:127], v[160:163], v[216:219], v[124:127]
	v_mfma_f32_16x16x32_bf16 v[120:123], v[188:191], v[216:219], v[120:123]
	v_mfma_f32_16x16x32_bf16 v[116:119], v[160:163], v[224:227], v[116:119]
	v_mfma_f32_16x16x32_bf16 v[112:115], v[188:191], v[224:227], v[112:115]
	v_mfma_f32_16x16x32_bf16 v[92:95], v[160:163], v[232:235], v[92:95]
	v_mfma_f32_16x16x32_bf16 v[88:91], v[188:191], v[232:235], v[88:91]
	v_mfma_f32_16x16x32_bf16 v[76:79], v[160:163], v[240:243], v[76:79]
	v_mfma_f32_16x16x32_bf16 v[72:75], v[188:191], v[240:243], v[72:75]
	s_setprio 0
	s_setprio 1
	v_mfma_f32_16x16x32_bf16 v[108:111], v[196:199], v[212:215], v[108:111]
	v_mfma_f32_16x16x32_bf16 v[104:107], v[204:207], v[212:215], v[104:107]
	v_mfma_f32_16x16x32_bf16 v[100:103], v[196:199], v[220:223], v[100:103]
	v_mfma_f32_16x16x32_bf16 v[96:99], v[204:207], v[220:223], v[96:99]
	v_mfma_f32_16x16x32_bf16 v[84:87], v[196:199], v[228:231], v[84:87]
	v_mfma_f32_16x16x32_bf16 v[80:83], v[204:207], v[228:231], v[80:83]
	v_mfma_f32_16x16x32_bf16 v[68:71], v[196:199], v[236:239], v[68:71]
	v_mfma_f32_16x16x32_bf16 v[64:67], v[204:207], v[236:239], v[64:67]
	v_mfma_f32_16x16x32_bf16 v[108:111], v[200:203], v[216:219], v[108:111]
	v_mfma_f32_16x16x32_bf16 v[104:107], v[208:211], v[216:219], v[104:107]
	v_mfma_f32_16x16x32_bf16 v[100:103], v[200:203], v[224:227], v[100:103]
	v_mfma_f32_16x16x32_bf16 v[96:99], v[208:211], v[224:227], v[96:99]
	v_mfma_f32_16x16x32_bf16 v[84:87], v[200:203], v[232:235], v[84:87]
	v_mfma_f32_16x16x32_bf16 v[80:83], v[208:211], v[232:235], v[80:83]
	v_mfma_f32_16x16x32_bf16 v[68:71], v[200:203], v[240:243], v[68:71]
	v_mfma_f32_16x16x32_bf16 v[64:67], v[208:211], v[240:243], v[64:67]
	s_setprio 0
	s_barrier
	s_add_i32 s22, s74, s46
	v_lshl_add_u64 v[138:139], v[138:139], 0, s[24:25]
	s_mov_b32 m0, s22
	ds_read_b128 v[212:215], v167 offset:49152
	ds_read_b128 v[216:219], v167 offset:50176
	ds_read_b128 v[220:223], v167 offset:51200
	ds_read_b128 v[224:227], v167 offset:52224
	ds_read_b128 v[228:231], v167 offset:53248
	ds_read_b128 v[232:235], v167 offset:54272
	ds_read_b128 v[236:239], v167 offset:55296
	ds_read_b128 v[240:243], v167 offset:56320
	global_load_lds_dwordx4 v[138:139], off
	s_add_i32 m0, s22, 0x2000
	s_add_u32 s2, s2, 0x40080
	v_lshl_add_u64 v[138:139], v[164:165], 0, s[24:25]
	s_addc_u32 s3, s3, 0
	s_add_i32 s22, s75, s46
	global_load_lds_dwordx4 v[138:139], off
	v_lshl_add_u64 v[138:139], s[2:3], 0, v[142:143]
	s_mov_b32 m0, s22
	s_nop 0
	global_load_lds_dwordx4 v[138:139], off
	v_lshl_add_u64 v[138:139], s[2:3], 0, v[146:147]
	s_add_i32 m0, s22, 0x2000
	s_nop 0
	global_load_lds_dwordx4 v[138:139], off
	v_lshl_add_u64 v[138:139], v[192:193], 0, s[24:25]
	s_mov_b32 m0, s54
	s_nop 0
	global_load_lds_dwordx4 v[138:139], off
	v_lshl_add_u64 v[138:139], v[244:245], 0, s[24:25]
	s_mov_b32 m0, s55
	s_nop 0
	global_load_lds_dwordx4 v[138:139], off
	s_waitcnt vmcnt(8)
	s_waitcnt lgkmcnt(0)
	s_barrier
	s_setprio 1
	s_waitcnt lgkmcnt(0)
	v_mfma_f32_16x16x32_bf16 v[60:63], v[156:159], v[212:215], v[60:63]
	v_mfma_f32_16x16x32_bf16 v[56:59], v[184:187], v[212:215], v[56:59]
	v_mfma_f32_16x16x32_bf16 v[44:47], v[156:159], v[220:223], v[44:47]
	v_mfma_f32_16x16x32_bf16 v[40:43], v[184:187], v[220:223], v[40:43]
	v_mfma_f32_16x16x32_bf16 v[28:31], v[156:159], v[228:231], v[28:31]
	v_mfma_f32_16x16x32_bf16 v[24:27], v[184:187], v[228:231], v[24:27]
	v_mfma_f32_16x16x32_bf16 v[12:15], v[156:159], v[236:239], v[12:15]
	v_mfma_f32_16x16x32_bf16 v[8:11], v[184:187], v[236:239], v[8:11]
	v_mfma_f32_16x16x32_bf16 v[60:63], v[160:163], v[216:219], v[60:63]
	v_mfma_f32_16x16x32_bf16 v[56:59], v[188:191], v[216:219], v[56:59]
	v_mfma_f32_16x16x32_bf16 v[44:47], v[160:163], v[224:227], v[44:47]
	v_mfma_f32_16x16x32_bf16 v[40:43], v[188:191], v[224:227], v[40:43]
	v_mfma_f32_16x16x32_bf16 v[28:31], v[160:163], v[232:235], v[28:31]
	v_mfma_f32_16x16x32_bf16 v[24:27], v[188:191], v[232:235], v[24:27]
	v_mfma_f32_16x16x32_bf16 v[12:15], v[160:163], v[240:243], v[12:15]
	v_mfma_f32_16x16x32_bf16 v[8:11], v[188:191], v[240:243], v[8:11]
	s_setprio 0
	s_setprio 1
	v_mfma_f32_16x16x32_bf16 v[52:55], v[196:199], v[212:215], v[52:55]
	v_mfma_f32_16x16x32_bf16 v[48:51], v[204:207], v[212:215], v[48:51]
	v_mfma_f32_16x16x32_bf16 v[36:39], v[196:199], v[220:223], v[36:39]
	v_mfma_f32_16x16x32_bf16 v[32:35], v[204:207], v[220:223], v[32:35]
	v_mfma_f32_16x16x32_bf16 v[20:23], v[196:199], v[228:231], v[20:23]
	v_mfma_f32_16x16x32_bf16 v[16:19], v[204:207], v[228:231], v[16:19]
	v_mfma_f32_16x16x32_bf16 v[4:7], v[196:199], v[236:239], v[4:7]
	v_mfma_f32_16x16x32_bf16 v[0:3], v[204:207], v[236:239], v[0:3]
	v_mfma_f32_16x16x32_bf16 v[52:55], v[200:203], v[216:219], v[52:55]
	v_mfma_f32_16x16x32_bf16 v[48:51], v[208:211], v[216:219], v[48:51]
	v_mfma_f32_16x16x32_bf16 v[36:39], v[200:203], v[224:227], v[36:39]
	v_mfma_f32_16x16x32_bf16 v[32:35], v[208:211], v[224:227], v[32:35]
	v_mfma_f32_16x16x32_bf16 v[20:23], v[200:203], v[232:235], v[20:23]
	v_mfma_f32_16x16x32_bf16 v[16:19], v[208:211], v[232:235], v[16:19]
	v_mfma_f32_16x16x32_bf16 v[4:7], v[200:203], v[240:243], v[4:7]
	v_mfma_f32_16x16x32_bf16 v[0:3], v[208:211], v[240:243], v[0:3]
	s_setprio 0
	s_add_i32 s73, s73, 2
	s_add_u32 s14, s14, 0x100
	s_addc_u32 s15, s15, 0
	s_add_u32 s71, s71, 0x100
	s_addc_u32 s72, s72, 0
	s_cmp_gt_u32 s73, 13
	s_barrier
	s_cbranch_scc1 .Lgemm_kdone_3
.LBB0_552:
	ds_read_b128 v[156:159], v155
	ds_read_b128 v[160:163], v155 offset:1024
	ds_read_b128 v[184:187], v155 offset:2048
	ds_read_b128 v[188:191], v155 offset:3072
	ds_read_b128 v[196:199], v166
	ds_read_b128 v[200:203], v166 offset:1024
	ds_read_b128 v[204:207], v166 offset:2048
	ds_read_b128 v[208:211], v166 offset:3072
	s_add_u32 s2, s14, 0xfffc0080
	s_addc_u32 s3, s15, -1
	s_cmp_eq_u32 s73, 12
	s_cselect_b32 s23, s41, s3
	s_cselect_b32 s22, s69, s2
	s_cselect_b32 s3, s39, s72
	s_cselect_b32 s2, s70, s71
	v_lshl_add_u64 v[138:139], s[14:15], 0, v[130:131]
	s_add_i32 m0, s49, 0xc000
	ds_read_b128 v[212:215], v167
	ds_read_b128 v[216:219], v167 offset:1024
	ds_read_b128 v[220:223], v167 offset:2048
	ds_read_b128 v[224:227], v167 offset:3072
	ds_read_b128 v[228:231], v167 offset:4096
	ds_read_b128 v[232:235], v167 offset:5120
	ds_read_b128 v[236:239], v167 offset:6144
	ds_read_b128 v[240:243], v167 offset:7168
	global_load_lds_dwordx4 v[138:139], off
	v_lshl_add_u64 v[138:139], s[14:15], 0, v[132:133]
	s_add_i32 m0, s49, 0xe000
	s_nop 0
	global_load_lds_dwordx4 v[138:139], off
	s_waitcnt vmcnt(8)
	s_waitcnt lgkmcnt(0)
	s_barrier
	s_setprio 1
	s_waitcnt lgkmcnt(0)
	v_mfma_f32_16x16x32_bf16 v[124:127], v[156:159], v[212:215], v[124:127]
	v_mfma_f32_16x16x32_bf16 v[120:123], v[184:187], v[212:215], v[120:123]
	v_mfma_f32_16x16x32_bf16 v[116:119], v[156:159], v[220:223], v[116:119]
	v_mfma_f32_16x16x32_bf16 v[112:115], v[184:187], v[220:223], v[112:115]
	v_mfma_f32_16x16x32_bf16 v[92:95], v[156:159], v[228:231], v[92:95]
	v_mfma_f32_16x16x32_bf16 v[88:91], v[184:187], v[228:231], v[88:91]
	v_mfma_f32_16x16x32_bf16 v[76:79], v[156:159], v[236:239], v[76:79]
	v_mfma_f32_16x16x32_bf16 v[72:75], v[184:187], v[236:239], v[72:75]
	v_mfma_f32_16x16x32_bf16 v[124:127], v[160:163], v[216:219], v[124:127]
	v_mfma_f32_16x16x32_bf16 v[120:123], v[188:191], v[216:219], v[120:123]
	v_mfma_f32_16x16x32_bf16 v[116:119], v[160:163], v[224:227], v[116:119]
	v_mfma_f32_16x16x32_bf16 v[112:115], v[188:191], v[224:227], v[112:115]
	v_mfma_f32_16x16x32_bf16 v[92:95], v[160:163], v[232:235], v[92:95]
	v_mfma_f32_16x16x32_bf16 v[88:91], v[188:191], v[232:235], v[88:91]
	v_mfma_f32_16x16x32_bf16 v[76:79], v[160:163], v[240:243], v[76:79]
	v_mfma_f32_16x16x32_bf16 v[72:75], v[188:191], v[240:243], v[72:75]
	s_setprio 0
	s_setprio 1
	v_mfma_f32_16x16x32_bf16 v[108:111], v[196:199], v[212:215], v[108:111]
	v_mfma_f32_16x16x32_bf16 v[104:107], v[204:207], v[212:215], v[104:107]
	v_mfma_f32_16x16x32_bf16 v[100:103], v[196:199], v[220:223], v[100:103]
	v_mfma_f32_16x16x32_bf16 v[96:99], v[204:207], v[220:223], v[96:99]
	v_mfma_f32_16x16x32_bf16 v[84:87], v[196:199], v[228:231], v[84:87]
	v_mfma_f32_16x16x32_bf16 v[80:83], v[204:207], v[228:231], v[80:83]
	v_mfma_f32_16x16x32_bf16 v[68:71], v[196:199], v[236:239], v[68:71]
	v_mfma_f32_16x16x32_bf16 v[64:67], v[204:207], v[236:239], v[64:67]
	v_mfma_f32_16x16x32_bf16 v[108:111], v[200:203], v[216:219], v[108:111]
	v_mfma_f32_16x16x32_bf16 v[104:107], v[208:211], v[216:219], v[104:107]
	v_mfma_f32_16x16x32_bf16 v[100:103], v[200:203], v[224:227], v[100:103]
	v_mfma_f32_16x16x32_bf16 v[96:99], v[208:211], v[224:227], v[96:99]
	v_mfma_f32_16x16x32_bf16 v[84:87], v[200:203], v[232:235], v[84:87]
	v_mfma_f32_16x16x32_bf16 v[80:83], v[208:211], v[232:235], v[80:83]
	v_mfma_f32_16x16x32_bf16 v[68:71], v[200:203], v[240:243], v[68:71]
	v_mfma_f32_16x16x32_bf16 v[64:67], v[208:211], v[240:243], v[64:67]
	s_setprio 0
	s_barrier
	s_add_i32 s74, s58, s46
	v_lshl_add_u64 v[138:139], s[2:3], 0, v[142:143]
	s_mov_b32 m0, s74
	ds_read_b128 v[212:215], v167 offset:16384
	ds_read_b128 v[216:219], v167 offset:17408
	ds_read_b128 v[220:223], v167 offset:18432
	ds_read_b128 v[224:227], v167 offset:19456
	ds_read_b128 v[228:231], v167 offset:20480
	ds_read_b128 v[232:235], v167 offset:21504
	ds_read_b128 v[236:239], v167 offset:22528
	ds_read_b128 v[240:243], v167 offset:23552
	global_load_lds_dwordx4 v[138:139], off
	s_add_i32 m0, s74, 0x2000
	s_add_u32 s74, s2, 0x40000
	v_lshl_add_u64 v[164:165], s[2:3], 0, v[146:147]
	s_addc_u32 s75, s3, 0
	s_add_i32 s76, s59, s46
	global_load_lds_dwordx4 v[164:165], off
	v_lshl_add_u64 v[192:193], s[74:75], 0, v[142:143]
	s_mov_b32 m0, s76
	v_lshl_add_u64 v[244:245], s[22:23], 0, v[144:145]
	global_load_lds_dwordx4 v[192:193], off
	v_lshl_add_u64 v[192:193], s[74:75], 0, v[146:147]
	s_add_i32 m0, s76, 0x2000
	s_nop 0
	global_load_lds_dwordx4 v[192:193], off
	v_lshl_add_u64 v[192:193], s[22:23], 0, v[140:141]
	s_mov_b32 m0, s49
	s_nop 0
	global_load_lds_dwordx4 v[192:193], off
	s_mov_b32 m0, s50
	s_nop 0
	global_load_lds_dwordx4 v[244:245], off
	s_waitcnt vmcnt(8)
	s_waitcnt lgkmcnt(0)
	s_barrier
	s_setprio 1
	s_waitcnt lgkmcnt(0)
	v_mfma_f32_16x16x32_bf16 v[60:63], v[156:159], v[212:215], v[60:63]
	v_mfma_f32_16x16x32_bf16 v[56:59], v[184:187], v[212:215], v[56:59]
	v_mfma_f32_16x16x32_bf16 v[44:47], v[156:159], v[220:223], v[44:47]
	v_mfma_f32_16x16x32_bf16 v[40:43], v[184:187], v[220:223], v[40:43]
	v_mfma_f32_16x16x32_bf16 v[28:31], v[156:159], v[228:231], v[28:31]
	v_mfma_f32_16x16x32_bf16 v[24:27], v[184:187], v[228:231], v[24:27]
	v_mfma_f32_16x16x32_bf16 v[12:15], v[156:159], v[236:239], v[12:15]
	v_mfma_f32_16x16x32_bf16 v[8:11], v[184:187], v[236:239], v[8:11]
	v_mfma_f32_16x16x32_bf16 v[60:63], v[160:163], v[216:219], v[60:63]
	v_mfma_f32_16x16x32_bf16 v[56:59], v[188:191], v[216:219], v[56:59]
	v_mfma_f32_16x16x32_bf16 v[44:47], v[160:163], v[224:227], v[44:47]
	v_mfma_f32_16x16x32_bf16 v[40:43], v[188:191], v[224:227], v[40:43]
	v_mfma_f32_16x16x32_bf16 v[28:31], v[160:163], v[232:235], v[28:31]
	v_mfma_f32_16x16x32_bf16 v[24:27], v[188:191], v[232:235], v[24:27]
	v_mfma_f32_16x16x32_bf16 v[12:15], v[160:163], v[240:243], v[12:15]
	v_mfma_f32_16x16x32_bf16 v[8:11], v[188:191], v[240:243], v[8:11]
	s_setprio 0
	s_setprio 1
	v_mfma_f32_16x16x32_bf16 v[52:55], v[196:199], v[212:215], v[52:55]
	v_mfma_f32_16x16x32_bf16 v[48:51], v[204:207], v[212:215], v[48:51]
	v_mfma_f32_16x16x32_bf16 v[36:39], v[196:199], v[220:223], v[36:39]
	v_mfma_f32_16x16x32_bf16 v[32:35], v[204:207], v[220:223], v[32:35]
	v_mfma_f32_16x16x32_bf16 v[20:23], v[196:199], v[228:231], v[20:23]
	v_mfma_f32_16x16x32_bf16 v[16:19], v[204:207], v[228:231], v[16:19]
	v_mfma_f32_16x16x32_bf16 v[4:7], v[196:199], v[236:239], v[4:7]
	v_mfma_f32_16x16x32_bf16 v[0:3], v[204:207], v[236:239], v[0:3]
	v_mfma_f32_16x16x32_bf16 v[52:55], v[200:203], v[216:219], v[52:55]
	v_mfma_f32_16x16x32_bf16 v[48:51], v[208:211], v[216:219], v[48:51]
	v_mfma_f32_16x16x32_bf16 v[36:39], v[200:203], v[224:227], v[36:39]
	v_mfma_f32_16x16x32_bf16 v[32:35], v[208:211], v[224:227], v[32:35]
	v_mfma_f32_16x16x32_bf16 v[20:23], v[200:203], v[232:235], v[20:23]
	v_mfma_f32_16x16x32_bf16 v[16:19], v[208:211], v[232:235], v[16:19]
	v_mfma_f32_16x16x32_bf16 v[4:7], v[200:203], v[240:243], v[4:7]
	v_mfma_f32_16x16x32_bf16 v[0:3], v[208:211], v[240:243], v[0:3]
	s_setprio 0
	s_barrier
	s_add_i32 s74, 0, 0x18000
	v_add_u32_e32 v128, s74, v151
	s_add_i32 s75, 0, 0x1c000
	ds_read_b128 v[156:159], v128
	ds_read_b128 v[160:163], v128 offset:1024
	ds_read_b128 v[184:187], v128 offset:2048
	ds_read_b128 v[188:191], v128 offset:3072
	v_add_u32_e32 v128, s75, v151
	ds_read_b128 v[196:199], v128
	ds_read_b128 v[200:203], v128 offset:1024
	ds_read_b128 v[204:207], v128 offset:2048
	ds_read_b128 v[208:211], v128 offset:3072
	s_add_u32 s22, s22, 0x40000
	s_addc_u32 s23, s23, 0
	s_mov_b32 m0, s51
	v_lshl_add_u64 v[246:247], s[22:23], 0, v[140:141]
	ds_read_b128 v[212:215], v167 offset:32768
	ds_read_b128 v[216:219], v167 offset:33792
	ds_read_b128 v[220:223], v167 offset:34816
	ds_read_b128 v[224:227], v167 offset:35840
	ds_read_b128 v[228:231], v167 offset:36864
	ds_read_b128 v[232:235], v167 offset:37888
	ds_read_b128 v[236:239], v167 offset:38912
	ds_read_b128 v[240:243], v167 offset:39936
	global_load_lds_dwordx4 v[246:247], off
	v_lshl_add_u64 v[246:247], s[22:23], 0, v[144:145]
	s_mov_b32 m0, s52
	s_nop 0
	global_load_lds_dwordx4 v[246:247], off
	s_waitcnt vmcnt(8)
	s_waitcnt lgkmcnt(0)
	s_barrier
	s_setprio 1
	s_waitcnt lgkmcnt(0)
	v_mfma_f32_16x16x32_bf16 v[124:127], v[156:159], v[212:215], v[124:127]
	v_mfma_f32_16x16x32_bf16 v[120:123], v[184:187], v[212:215], v[120:123]
	v_mfma_f32_16x16x32_bf16 v[116:119], v[156:159], v[220:223], v[116:119]
	v_mfma_f32_16x16x32_bf16 v[112:115], v[184:187], v[220:223], v[112:115]
	v_mfma_f32_16x16x32_bf16 v[92:95], v[156:159], v[228:231], v[92:95]
	v_mfma_f32_16x16x32_bf16 v[88:91], v[184:187], v[228:231], v[88:91]
	v_mfma_f32_16x16x32_bf16 v[76:79], v[156:159], v[236:239], v[76:79]
	v_mfma_f32_16x16x32_bf16 v[72:75], v[184:187], v[236:239], v[72:75]
	v_mfma_f32_16x16x32_bf16 v[124:127], v[160:163], v[216:219], v[124:127]
	v_mfma_f32_16x16x32_bf16 v[120:123], v[188:191], v[216:219], v[120:123]
	v_mfma_f32_16x16x32_bf16 v[116:119], v[160:163], v[224:227], v[116:119]
	v_mfma_f32_16x16x32_bf16 v[112:115], v[188:191], v[224:227], v[112:115]
	v_mfma_f32_16x16x32_bf16 v[92:95], v[160:163], v[232:235], v[92:95]
	v_mfma_f32_16x16x32_bf16 v[88:91], v[188:191], v[232:235], v[88:91]
	v_mfma_f32_16x16x32_bf16 v[76:79], v[160:163], v[240:243], v[76:79]
	v_mfma_f32_16x16x32_bf16 v[72:75], v[188:191], v[240:243], v[72:75]
	s_setprio 0
	s_setprio 1
	v_mfma_f32_16x16x32_bf16 v[108:111], v[196:199], v[212:215], v[108:111]
	v_mfma_f32_16x16x32_bf16 v[104:107], v[204:207], v[212:215], v[104:107]
	v_mfma_f32_16x16x32_bf16 v[100:103], v[196:199], v[220:223], v[100:103]
	v_mfma_f32_16x16x32_bf16 v[96:99], v[204:207], v[220:223], v[96:99]
	v_mfma_f32_16x16x32_bf16 v[84:87], v[196:199], v[228:231], v[84:87]
	v_mfma_f32_16x16x32_bf16 v[80:83], v[204:207], v[228:231], v[80:83]
	v_mfma_f32_16x16x32_bf16 v[68:71], v[196:199], v[236:239], v[68:71]
	v_mfma_f32_16x16x32_bf16 v[64:67], v[204:207], v[236:239], v[64:67]
	v_mfma_f32_16x16x32_bf16 v[108:111], v[200:203], v[216:219], v[108:111]
	v_mfma_f32_16x16x32_bf16 v[104:107], v[208:211], v[216:219], v[104:107]
	v_mfma_f32_16x16x32_bf16 v[100:103], v[200:203], v[224:227], v[100:103]
	v_mfma_f32_16x16x32_bf16 v[96:99], v[208:211], v[224:227], v[96:99]
	v_mfma_f32_16x16x32_bf16 v[84:87], v[200:203], v[232:235], v[84:87]
	v_mfma_f32_16x16x32_bf16 v[80:83], v[208:211], v[232:235], v[80:83]
	v_mfma_f32_16x16x32_bf16 v[68:71], v[200:203], v[240:243], v[68:71]
	v_mfma_f32_16x16x32_bf16 v[64:67], v[208:211], v[240:243], v[64:67]
	s_setprio 0
	s_barrier
	s_add_i32 s22, s74, s46
	v_lshl_add_u64 v[138:139], v[138:139], 0, s[24:25]
	s_mov_b32 m0, s22
	ds_read_b128 v[212:215], v167 offset:49152
	ds_read_b128 v[216:219], v167 offset:50176
	ds_read_b128 v[220:223], v167 offset:51200
	ds_read_b128 v[224:227], v167 offset:52224
	ds_read_b128 v[228:231], v167 offset:53248
	ds_read_b128 v[232:235], v167 offset:54272
	ds_read_b128 v[236:239], v167 offset:55296
	ds_read_b128 v[240:243], v167 offset:56320
	global_load_lds_dwordx4 v[138:139], off
	s_add_i32 m0, s22, 0x2000
	s_add_u32 s2, s2, 0x40080
	v_lshl_add_u64 v[138:139], v[164:165], 0, s[24:25]
	s_addc_u32 s3, s3, 0
	s_add_i32 s22, s75, s46
	global_load_lds_dwordx4 v[138:139], off
	v_lshl_add_u64 v[138:139], s[2:3], 0, v[142:143]
	s_mov_b32 m0, s22
	s_nop 0
	global_load_lds_dwordx4 v[138:139], off
	v_lshl_add_u64 v[138:139], s[2:3], 0, v[146:147]
	s_add_i32 m0, s22, 0x2000
	s_nop 0
	global_load_lds_dwordx4 v[138:139], off
	v_lshl_add_u64 v[138:139], v[192:193], 0, s[24:25]
	s_mov_b32 m0, s54
	s_nop 0
	global_load_lds_dwordx4 v[138:139], off
	v_lshl_add_u64 v[138:139], v[244:245], 0, s[24:25]
	s_mov_b32 m0, s55
	s_nop 0
	global_load_lds_dwordx4 v[138:139], off
	s_waitcnt vmcnt(8)
	s_waitcnt lgkmcnt(0)
	s_barrier
	s_setprio 1
	s_waitcnt lgkmcnt(0)
	v_mfma_f32_16x16x32_bf16 v[60:63], v[156:159], v[212:215], v[60:63]
	v_mfma_f32_16x16x32_bf16 v[56:59], v[184:187], v[212:215], v[56:59]
	v_mfma_f32_16x16x32_bf16 v[44:47], v[156:159], v[220:223], v[44:47]
	v_mfma_f32_16x16x32_bf16 v[40:43], v[184:187], v[220:223], v[40:43]
	v_mfma_f32_16x16x32_bf16 v[28:31], v[156:159], v[228:231], v[28:31]
	v_mfma_f32_16x16x32_bf16 v[24:27], v[184:187], v[228:231], v[24:27]
	v_mfma_f32_16x16x32_bf16 v[12:15], v[156:159], v[236:239], v[12:15]
	v_mfma_f32_16x16x32_bf16 v[8:11], v[184:187], v[236:239], v[8:11]
	v_mfma_f32_16x16x32_bf16 v[60:63], v[160:163], v[216:219], v[60:63]
	v_mfma_f32_16x16x32_bf16 v[56:59], v[188:191], v[216:219], v[56:59]
	v_mfma_f32_16x16x32_bf16 v[44:47], v[160:163], v[224:227], v[44:47]
	v_mfma_f32_16x16x32_bf16 v[40:43], v[188:191], v[224:227], v[40:43]
	v_mfma_f32_16x16x32_bf16 v[28:31], v[160:163], v[232:235], v[28:31]
	v_mfma_f32_16x16x32_bf16 v[24:27], v[188:191], v[232:235], v[24:27]
	v_mfma_f32_16x16x32_bf16 v[12:15], v[160:163], v[240:243], v[12:15]
	v_mfma_f32_16x16x32_bf16 v[8:11], v[188:191], v[240:243], v[8:11]
	s_setprio 0
	s_setprio 1
	v_mfma_f32_16x16x32_bf16 v[52:55], v[196:199], v[212:215], v[52:55]
	v_mfma_f32_16x16x32_bf16 v[48:51], v[204:207], v[212:215], v[48:51]
	v_mfma_f32_16x16x32_bf16 v[36:39], v[196:199], v[220:223], v[36:39]
	v_mfma_f32_16x16x32_bf16 v[32:35], v[204:207], v[220:223], v[32:35]
	v_mfma_f32_16x16x32_bf16 v[20:23], v[196:199], v[228:231], v[20:23]
	v_mfma_f32_16x16x32_bf16 v[16:19], v[204:207], v[228:231], v[16:19]
	v_mfma_f32_16x16x32_bf16 v[4:7], v[196:199], v[236:239], v[4:7]
	v_mfma_f32_16x16x32_bf16 v[0:3], v[204:207], v[236:239], v[0:3]
	v_mfma_f32_16x16x32_bf16 v[52:55], v[200:203], v[216:219], v[52:55]
	v_mfma_f32_16x16x32_bf16 v[48:51], v[208:211], v[216:219], v[48:51]
	v_mfma_f32_16x16x32_bf16 v[36:39], v[200:203], v[224:227], v[36:39]
	v_mfma_f32_16x16x32_bf16 v[32:35], v[208:211], v[224:227], v[32:35]
	v_mfma_f32_16x16x32_bf16 v[20:23], v[200:203], v[232:235], v[20:23]
	v_mfma_f32_16x16x32_bf16 v[16:19], v[208:211], v[232:235], v[16:19]
	v_mfma_f32_16x16x32_bf16 v[4:7], v[200:203], v[240:243], v[4:7]
	v_mfma_f32_16x16x32_bf16 v[0:3], v[208:211], v[240:243], v[0:3]
	s_setprio 0
	s_add_i32 s73, s73, 2
	s_add_u32 s14, s14, 0x100
	s_addc_u32 s15, s15, 0
	s_add_u32 s71, s71, 0x100
	s_addc_u32 s72, s72, 0
	s_cmp_gt_u32 s73, 13
	s_barrier
	s_cbranch_scc0 .LBB0_552

.LBB0_724:
	s_ashr_i32 s27, s26, 31
	s_lshl_b64 s[22:23], s[26:27], 19
	s_add_u32 s28, s16, s22
	s_addc_u32 s29, s17, s23
	s_and_b64 s[22:23], s[6:7], exec
	s_cselect_b32 s27, s29, s15
	s_cselect_b32 s59, s28, s14
	s_ashr_i32 s25, s24, 31
	s_lshl_b64 s[22:23], s[24:25], 19
	s_add_u32 s30, s35, s22
	s_addc_u32 s31, s38, s23
	s_and_b64 s[22:23], s[6:7], exec
	s_cselect_b32 s25, s31, s3
	s_cselect_b32 s64, s30, s2
	s_add_u32 s14, s14, 0x40080
	s_addc_u32 s15, s15, 0
	s_add_u32 s65, s2, 0x100
	s_addc_u32 s66, s3, 0
	s_mov_b32 s67, -2
	s_waitcnt lgkmcnt(0)
	s_waitcnt vmcnt(0)
	ds_read_b128 v[128:131], v155
	ds_read_b128 v[132:135], v155 offset:1024
	ds_read_b128 v[136:139], v155 offset:2048
	ds_read_b128 v[164:167], v155 offset:3072
	ds_read_b128 v[188:191], v184
	ds_read_b128 v[196:199], v184 offset:1024
	ds_read_b128 v[200:203], v184 offset:2048
	ds_read_b128 v[204:207], v184 offset:3072
	s_add_u32 s2, s14, 0xfffc0080
	s_addc_u32 s3, s15, -1
	s_cmp_eq_u32 s67, 12
	s_cselect_b32 s23, s27, s3
	s_cselect_b32 s22, s59, s2
	s_cselect_b32 s3, s25, s66
	s_cselect_b32 s2, s64, s65
	v_lshl_add_u64 v[168:169], s[14:15], 0, v[156:157]
	s_add_i32 m0, s37, 0xc000
	ds_read_b128 v[208:211], v185
	ds_read_b128 v[212:215], v185 offset:1024
	ds_read_b128 v[216:219], v185 offset:2048
	ds_read_b128 v[220:223], v185 offset:3072
	ds_read_b128 v[224:227], v185 offset:4096
	ds_read_b128 v[228:231], v185 offset:5120
	ds_read_b128 v[232:235], v185 offset:6144
	ds_read_b128 v[236:239], v185 offset:7168
	global_load_lds_dwordx4 v[168:169], off
	v_lshl_add_u64 v[168:169], s[14:15], 0, v[158:159]
	s_add_i32 m0, s37, 0xe000
	s_nop 0
	global_load_lds_dwordx4 v[168:169], off
	s_waitcnt vmcnt(8)
	s_waitcnt lgkmcnt(0)
	s_barrier
	s_setprio 1
	s_waitcnt lgkmcnt(0)
	v_mfma_f32_16x16x32_bf16 v[124:127], v[128:131], v[208:211], 0
	v_mfma_f32_16x16x32_bf16 v[120:123], v[136:139], v[208:211], 0
	v_mfma_f32_16x16x32_bf16 v[108:111], v[128:131], v[216:219], 0
	v_mfma_f32_16x16x32_bf16 v[104:107], v[136:139], v[216:219], 0
	v_mfma_f32_16x16x32_bf16 v[92:95], v[128:131], v[224:227], 0
	v_mfma_f32_16x16x32_bf16 v[88:91], v[136:139], v[224:227], 0
	v_mfma_f32_16x16x32_bf16 v[76:79], v[128:131], v[232:235], 0
	v_mfma_f32_16x16x32_bf16 v[72:75], v[136:139], v[232:235], 0
	v_mfma_f32_16x16x32_bf16 v[124:127], v[132:135], v[212:215], v[124:127]
	v_mfma_f32_16x16x32_bf16 v[120:123], v[164:167], v[212:215], v[120:123]
	v_mfma_f32_16x16x32_bf16 v[108:111], v[132:135], v[220:223], v[108:111]
	v_mfma_f32_16x16x32_bf16 v[104:107], v[164:167], v[220:223], v[104:107]
	v_mfma_f32_16x16x32_bf16 v[92:95], v[132:135], v[228:231], v[92:95]
	v_mfma_f32_16x16x32_bf16 v[88:91], v[164:167], v[228:231], v[88:91]
	v_mfma_f32_16x16x32_bf16 v[76:79], v[132:135], v[236:239], v[76:79]
	v_mfma_f32_16x16x32_bf16 v[72:75], v[164:167], v[236:239], v[72:75]
	s_setprio 0
	s_setprio 1
	v_mfma_f32_16x16x32_bf16 v[116:119], v[188:191], v[208:211], 0
	v_mfma_f32_16x16x32_bf16 v[112:115], v[200:203], v[208:211], 0
	v_mfma_f32_16x16x32_bf16 v[100:103], v[188:191], v[216:219], 0
	v_mfma_f32_16x16x32_bf16 v[96:99], v[200:203], v[216:219], 0
	v_mfma_f32_16x16x32_bf16 v[84:87], v[188:191], v[224:227], 0
	v_mfma_f32_16x16x32_bf16 v[80:83], v[200:203], v[224:227], 0
	v_mfma_f32_16x16x32_bf16 v[68:71], v[188:191], v[232:235], 0
	v_mfma_f32_16x16x32_bf16 v[64:67], v[200:203], v[232:235], 0
	v_mfma_f32_16x16x32_bf16 v[116:119], v[196:199], v[212:215], v[116:119]
	v_mfma_f32_16x16x32_bf16 v[112:115], v[204:207], v[212:215], v[112:115]
	v_mfma_f32_16x16x32_bf16 v[100:103], v[196:199], v[220:223], v[100:103]
	v_mfma_f32_16x16x32_bf16 v[96:99], v[204:207], v[220:223], v[96:99]
	v_mfma_f32_16x16x32_bf16 v[84:87], v[196:199], v[228:231], v[84:87]
	v_mfma_f32_16x16x32_bf16 v[80:83], v[204:207], v[228:231], v[80:83]
	v_mfma_f32_16x16x32_bf16 v[68:71], v[196:199], v[236:239], v[68:71]
	v_mfma_f32_16x16x32_bf16 v[64:67], v[204:207], v[236:239], v[64:67]
	s_setprio 0
	s_barrier
	s_add_i32 s68, s52, s39
	v_lshl_add_u64 v[168:169], s[2:3], 0, v[142:143]
	s_mov_b32 m0, s68
	ds_read_b128 v[208:211], v185 offset:16384
	ds_read_b128 v[212:215], v185 offset:17408
	ds_read_b128 v[216:219], v185 offset:18432
	ds_read_b128 v[220:223], v185 offset:19456
	ds_read_b128 v[224:227], v185 offset:20480
	ds_read_b128 v[228:231], v185 offset:21504
	ds_read_b128 v[232:235], v185 offset:22528
	ds_read_b128 v[236:239], v185 offset:23552
	global_load_lds_dwordx4 v[168:169], off
	s_add_i32 m0, s68, 0x2000
	s_add_u32 s68, s2, 0x40000
	v_lshl_add_u64 v[192:193], s[2:3], 0, v[146:147]
	s_addc_u32 s69, s3, 0
	s_add_i32 s70, s53, s39
	global_load_lds_dwordx4 v[192:193], off
	v_lshl_add_u64 v[240:241], s[68:69], 0, v[142:143]
	s_mov_b32 m0, s70
	v_lshl_add_u64 v[242:243], s[22:23], 0, v[144:145]
	global_load_lds_dwordx4 v[240:241], off
	v_lshl_add_u64 v[240:241], s[68:69], 0, v[146:147]
	s_add_i32 m0, s70, 0x2000
	s_nop 0
	global_load_lds_dwordx4 v[240:241], off
	v_lshl_add_u64 v[240:241], s[22:23], 0, v[140:141]
	s_mov_b32 m0, s37
	s_nop 0
	global_load_lds_dwordx4 v[240:241], off
	s_mov_b32 m0, s40
	s_nop 0
	global_load_lds_dwordx4 v[242:243], off
	s_waitcnt vmcnt(8)
	s_waitcnt lgkmcnt(0)
	s_barrier
	s_setprio 1
	s_waitcnt lgkmcnt(0)
	v_mfma_f32_16x16x32_bf16 v[60:63], v[128:131], v[208:211], 0
	v_mfma_f32_16x16x32_bf16 v[56:59], v[136:139], v[208:211], 0
	v_mfma_f32_16x16x32_bf16 v[44:47], v[128:131], v[216:219], 0
	v_mfma_f32_16x16x32_bf16 v[40:43], v[136:139], v[216:219], 0
	v_mfma_f32_16x16x32_bf16 v[28:31], v[128:131], v[224:227], 0
	v_mfma_f32_16x16x32_bf16 v[24:27], v[136:139], v[224:227], 0
	v_mfma_f32_16x16x32_bf16 v[12:15], v[128:131], v[232:235], 0
	v_mfma_f32_16x16x32_bf16 v[8:11], v[136:139], v[232:235], 0
	v_mfma_f32_16x16x32_bf16 v[60:63], v[132:135], v[212:215], v[60:63]
	v_mfma_f32_16x16x32_bf16 v[56:59], v[164:167], v[212:215], v[56:59]
	v_mfma_f32_16x16x32_bf16 v[44:47], v[132:135], v[220:223], v[44:47]
	v_mfma_f32_16x16x32_bf16 v[40:43], v[164:167], v[220:223], v[40:43]
	v_mfma_f32_16x16x32_bf16 v[28:31], v[132:135], v[228:231], v[28:31]
	v_mfma_f32_16x16x32_bf16 v[24:27], v[164:167], v[228:231], v[24:27]
	v_mfma_f32_16x16x32_bf16 v[12:15], v[132:135], v[236:239], v[12:15]
	v_mfma_f32_16x16x32_bf16 v[8:11], v[164:167], v[236:239], v[8:11]
	s_setprio 0
	s_setprio 1
	v_mfma_f32_16x16x32_bf16 v[52:55], v[188:191], v[208:211], 0
	v_mfma_f32_16x16x32_bf16 v[48:51], v[200:203], v[208:211], 0
	v_mfma_f32_16x16x32_bf16 v[36:39], v[188:191], v[216:219], 0
	v_mfma_f32_16x16x32_bf16 v[32:35], v[200:203], v[216:219], 0
	v_mfma_f32_16x16x32_bf16 v[20:23], v[188:191], v[224:227], 0
	v_mfma_f32_16x16x32_bf16 v[16:19], v[200:203], v[224:227], 0
	v_mfma_f32_16x16x32_bf16 v[4:7], v[188:191], v[232:235], 0
	v_mfma_f32_16x16x32_bf16 v[0:3], v[200:203], v[232:235], 0
	v_mfma_f32_16x16x32_bf16 v[52:55], v[196:199], v[212:215], v[52:55]
	v_mfma_f32_16x16x32_bf16 v[48:51], v[204:207], v[212:215], v[48:51]
	v_mfma_f32_16x16x32_bf16 v[36:39], v[196:199], v[220:223], v[36:39]
	v_mfma_f32_16x16x32_bf16 v[32:35], v[204:207], v[220:223], v[32:35]
	v_mfma_f32_16x16x32_bf16 v[20:23], v[196:199], v[228:231], v[20:23]
	v_mfma_f32_16x16x32_bf16 v[16:19], v[204:207], v[228:231], v[16:19]
	v_mfma_f32_16x16x32_bf16 v[4:7], v[196:199], v[236:239], v[4:7]
	v_mfma_f32_16x16x32_bf16 v[0:3], v[204:207], v[236:239], v[0:3]
	s_setprio 0
	s_barrier
	s_add_i32 s68, 0, 0x18000
	s_add_i32 s69, 0, 0x1c000
	v_add_u32_e32 v164, s68, v149
	v_add_u32_e32 v187, s69, v149
	ds_read_b128 v[128:131], v164
	ds_read_b128 v[132:135], v164 offset:1024
	ds_read_b128 v[136:139], v164 offset:2048
	ds_read_b128 v[164:167], v164 offset:3072
	ds_read_b128 v[188:191], v187
	ds_read_b128 v[196:199], v187 offset:1024
	ds_read_b128 v[200:203], v187 offset:2048
	ds_read_b128 v[204:207], v187 offset:3072
	s_add_u32 s22, s22, 0x40000
	s_addc_u32 s23, s23, 0
	s_mov_b32 m0, s41
	v_lshl_add_u64 v[244:245], s[22:23], 0, v[140:141]
	ds_read_b128 v[208:211], v185 offset:32768
	ds_read_b128 v[212:215], v185 offset:33792
	ds_read_b128 v[216:219], v185 offset:34816
	ds_read_b128 v[220:223], v185 offset:35840
	ds_read_b128 v[224:227], v185 offset:36864
	ds_read_b128 v[228:231], v185 offset:37888
	ds_read_b128 v[232:235], v185 offset:38912
	ds_read_b128 v[236:239], v185 offset:39936
	global_load_lds_dwordx4 v[244:245], off
	v_lshl_add_u64 v[244:245], s[22:23], 0, v[144:145]
	s_mov_b32 m0, s42
	s_nop 0
	global_load_lds_dwordx4 v[244:245], off
	s_waitcnt vmcnt(8)
	s_waitcnt lgkmcnt(0)
	s_barrier
	s_setprio 1
	s_waitcnt lgkmcnt(0)
	v_mfma_f32_16x16x32_bf16 v[124:127], v[128:131], v[208:211], v[124:127]
	v_mfma_f32_16x16x32_bf16 v[120:123], v[136:139], v[208:211], v[120:123]
	v_mfma_f32_16x16x32_bf16 v[108:111], v[128:131], v[216:219], v[108:111]
	v_mfma_f32_16x16x32_bf16 v[104:107], v[136:139], v[216:219], v[104:107]
	v_mfma_f32_16x16x32_bf16 v[92:95], v[128:131], v[224:227], v[92:95]
	v_mfma_f32_16x16x32_bf16 v[88:91], v[136:139], v[224:227], v[88:91]
	v_mfma_f32_16x16x32_bf16 v[76:79], v[128:131], v[232:235], v[76:79]
	v_mfma_f32_16x16x32_bf16 v[72:75], v[136:139], v[232:235], v[72:75]
	v_mfma_f32_16x16x32_bf16 v[124:127], v[132:135], v[212:215], v[124:127]
	v_mfma_f32_16x16x32_bf16 v[120:123], v[164:167], v[212:215], v[120:123]
	v_mfma_f32_16x16x32_bf16 v[108:111], v[132:135], v[220:223], v[108:111]
	v_mfma_f32_16x16x32_bf16 v[104:107], v[164:167], v[220:223], v[104:107]
	v_mfma_f32_16x16x32_bf16 v[92:95], v[132:135], v[228:231], v[92:95]
	v_mfma_f32_16x16x32_bf16 v[88:91], v[164:167], v[228:231], v[88:91]
	v_mfma_f32_16x16x32_bf16 v[76:79], v[132:135], v[236:239], v[76:79]
	v_mfma_f32_16x16x32_bf16 v[72:75], v[164:167], v[236:239], v[72:75]
	s_setprio 0
	s_setprio 1
	v_mfma_f32_16x16x32_bf16 v[116:119], v[188:191], v[208:211], v[116:119]
	v_mfma_f32_16x16x32_bf16 v[112:115], v[200:203], v[208:211], v[112:115]
	v_mfma_f32_16x16x32_bf16 v[100:103], v[188:191], v[216:219], v[100:103]
	v_mfma_f32_16x16x32_bf16 v[96:99], v[200:203], v[216:219], v[96:99]
	v_mfma_f32_16x16x32_bf16 v[84:87], v[188:191], v[224:227], v[84:87]
	v_mfma_f32_16x16x32_bf16 v[80:83], v[200:203], v[224:227], v[80:83]
	v_mfma_f32_16x16x32_bf16 v[68:71], v[188:191], v[232:235], v[68:71]
	v_mfma_f32_16x16x32_bf16 v[64:67], v[200:203], v[232:235], v[64:67]
	v_mfma_f32_16x16x32_bf16 v[116:119], v[196:199], v[212:215], v[116:119]
	v_mfma_f32_16x16x32_bf16 v[112:115], v[204:207], v[212:215], v[112:115]
	v_mfma_f32_16x16x32_bf16 v[100:103], v[196:199], v[220:223], v[100:103]
	v_mfma_f32_16x16x32_bf16 v[96:99], v[204:207], v[220:223], v[96:99]
	v_mfma_f32_16x16x32_bf16 v[84:87], v[196:199], v[228:231], v[84:87]
	v_mfma_f32_16x16x32_bf16 v[80:83], v[204:207], v[228:231], v[80:83]
	v_mfma_f32_16x16x32_bf16 v[68:71], v[196:199], v[236:239], v[68:71]
	v_mfma_f32_16x16x32_bf16 v[64:67], v[204:207], v[236:239], v[64:67]
	s_setprio 0
	s_barrier
	s_add_i32 s22, s68, s39
	v_lshl_add_u64 v[168:169], v[168:169], 0, s[18:19]
	s_mov_b32 m0, s22
	ds_read_b128 v[208:211], v185 offset:49152
	ds_read_b128 v[212:215], v185 offset:50176
	ds_read_b128 v[216:219], v185 offset:51200
	ds_read_b128 v[220:223], v185 offset:52224
	ds_read_b128 v[224:227], v185 offset:53248
	ds_read_b128 v[228:231], v185 offset:54272
	ds_read_b128 v[232:235], v185 offset:55296
	ds_read_b128 v[236:239], v185 offset:56320
	global_load_lds_dwordx4 v[168:169], off
	s_add_i32 m0, s22, 0x2000
	s_add_u32 s2, s2, 0x40080
	v_lshl_add_u64 v[168:169], v[192:193], 0, s[18:19]
	s_addc_u32 s3, s3, 0
	s_add_i32 s22, s69, s39
	global_load_lds_dwordx4 v[168:169], off
	v_lshl_add_u64 v[168:169], s[2:3], 0, v[142:143]
	s_mov_b32 m0, s22
	s_nop 0
	global_load_lds_dwordx4 v[168:169], off
	v_lshl_add_u64 v[168:169], s[2:3], 0, v[146:147]
	s_add_i32 m0, s22, 0x2000
	s_nop 0
	global_load_lds_dwordx4 v[168:169], off
	v_lshl_add_u64 v[168:169], v[240:241], 0, s[18:19]
	s_mov_b32 m0, s46
	s_nop 0
	global_load_lds_dwordx4 v[168:169], off
	v_lshl_add_u64 v[168:169], v[242:243], 0, s[18:19]
	s_mov_b32 m0, s47
	s_nop 0
	global_load_lds_dwordx4 v[168:169], off
	s_waitcnt vmcnt(8)
	s_waitcnt lgkmcnt(0)
	s_barrier
	s_setprio 1
	s_waitcnt lgkmcnt(0)
	v_mfma_f32_16x16x32_bf16 v[60:63], v[128:131], v[208:211], v[60:63]
	v_mfma_f32_16x16x32_bf16 v[56:59], v[136:139], v[208:211], v[56:59]
	v_mfma_f32_16x16x32_bf16 v[44:47], v[128:131], v[216:219], v[44:47]
	v_mfma_f32_16x16x32_bf16 v[40:43], v[136:139], v[216:219], v[40:43]
	v_mfma_f32_16x16x32_bf16 v[28:31], v[128:131], v[224:227], v[28:31]
	v_mfma_f32_16x16x32_bf16 v[24:27], v[136:139], v[224:227], v[24:27]
	v_mfma_f32_16x16x32_bf16 v[12:15], v[128:131], v[232:235], v[12:15]
	v_mfma_f32_16x16x32_bf16 v[8:11], v[136:139], v[232:235], v[8:11]
	v_mfma_f32_16x16x32_bf16 v[60:63], v[132:135], v[212:215], v[60:63]
	v_mfma_f32_16x16x32_bf16 v[56:59], v[164:167], v[212:215], v[56:59]
	v_mfma_f32_16x16x32_bf16 v[44:47], v[132:135], v[220:223], v[44:47]
	v_mfma_f32_16x16x32_bf16 v[40:43], v[164:167], v[220:223], v[40:43]
	v_mfma_f32_16x16x32_bf16 v[28:31], v[132:135], v[228:231], v[28:31]
	v_mfma_f32_16x16x32_bf16 v[24:27], v[164:167], v[228:231], v[24:27]
	v_mfma_f32_16x16x32_bf16 v[12:15], v[132:135], v[236:239], v[12:15]
	v_mfma_f32_16x16x32_bf16 v[8:11], v[164:167], v[236:239], v[8:11]
	s_setprio 0
	s_setprio 1
	v_mfma_f32_16x16x32_bf16 v[52:55], v[188:191], v[208:211], v[52:55]
	v_mfma_f32_16x16x32_bf16 v[48:51], v[200:203], v[208:211], v[48:51]
	v_mfma_f32_16x16x32_bf16 v[36:39], v[188:191], v[216:219], v[36:39]
	v_mfma_f32_16x16x32_bf16 v[32:35], v[200:203], v[216:219], v[32:35]
	v_mfma_f32_16x16x32_bf16 v[20:23], v[188:191], v[224:227], v[20:23]
	v_mfma_f32_16x16x32_bf16 v[16:19], v[200:203], v[224:227], v[16:19]
	v_mfma_f32_16x16x32_bf16 v[4:7], v[188:191], v[232:235], v[4:7]
	v_mfma_f32_16x16x32_bf16 v[0:3], v[200:203], v[232:235], v[0:3]
	v_mfma_f32_16x16x32_bf16 v[52:55], v[196:199], v[212:215], v[52:55]
	v_mfma_f32_16x16x32_bf16 v[48:51], v[204:207], v[212:215], v[48:51]
	v_mfma_f32_16x16x32_bf16 v[36:39], v[196:199], v[220:223], v[36:39]
	v_mfma_f32_16x16x32_bf16 v[32:35], v[204:207], v[220:223], v[32:35]
	v_mfma_f32_16x16x32_bf16 v[20:23], v[196:199], v[228:231], v[20:23]
	v_mfma_f32_16x16x32_bf16 v[16:19], v[204:207], v[228:231], v[16:19]
	v_mfma_f32_16x16x32_bf16 v[4:7], v[196:199], v[236:239], v[4:7]
	v_mfma_f32_16x16x32_bf16 v[0:3], v[204:207], v[236:239], v[0:3]
	s_setprio 0
	s_add_i32 s67, s67, 2
	s_add_u32 s14, s14, 0x100
	s_addc_u32 s15, s15, 0
	s_add_u32 s65, s65, 0x100
	s_addc_u32 s66, s66, 0
	s_cmp_gt_u32 s67, 13
	s_barrier
	s_cbranch_scc1 .Lgemm_kdone_4
.LBB0_725:
	ds_read_b128 v[128:131], v155
	ds_read_b128 v[132:135], v155 offset:1024
	ds_read_b128 v[136:139], v155 offset:2048
	ds_read_b128 v[164:167], v155 offset:3072
	ds_read_b128 v[188:191], v184
	ds_read_b128 v[196:199], v184 offset:1024
	ds_read_b128 v[200:203], v184 offset:2048
	ds_read_b128 v[204:207], v184 offset:3072
	s_add_u32 s2, s14, 0xfffc0080
	s_addc_u32 s3, s15, -1
	s_cmp_eq_u32 s67, 12
	s_cselect_b32 s23, s27, s3
	s_cselect_b32 s22, s59, s2
	s_cselect_b32 s3, s25, s66
	s_cselect_b32 s2, s64, s65
	v_lshl_add_u64 v[168:169], s[14:15], 0, v[156:157]
	s_add_i32 m0, s37, 0xc000
	ds_read_b128 v[208:211], v185
	ds_read_b128 v[212:215], v185 offset:1024
	ds_read_b128 v[216:219], v185 offset:2048
	ds_read_b128 v[220:223], v185 offset:3072
	ds_read_b128 v[224:227], v185 offset:4096
	ds_read_b128 v[228:231], v185 offset:5120
	ds_read_b128 v[232:235], v185 offset:6144
	ds_read_b128 v[236:239], v185 offset:7168
	global_load_lds_dwordx4 v[168:169], off
	v_lshl_add_u64 v[168:169], s[14:15], 0, v[158:159]
	s_add_i32 m0, s37, 0xe000
	s_nop 0
	global_load_lds_dwordx4 v[168:169], off
	s_waitcnt vmcnt(8)
	s_waitcnt lgkmcnt(0)
	s_barrier
	s_setprio 1
	s_waitcnt lgkmcnt(0)
	v_mfma_f32_16x16x32_bf16 v[124:127], v[128:131], v[208:211], v[124:127]
	v_mfma_f32_16x16x32_bf16 v[120:123], v[136:139], v[208:211], v[120:123]
	v_mfma_f32_16x16x32_bf16 v[108:111], v[128:131], v[216:219], v[108:111]
	v_mfma_f32_16x16x32_bf16 v[104:107], v[136:139], v[216:219], v[104:107]
	v_mfma_f32_16x16x32_bf16 v[92:95], v[128:131], v[224:227], v[92:95]
	v_mfma_f32_16x16x32_bf16 v[88:91], v[136:139], v[224:227], v[88:91]
	v_mfma_f32_16x16x32_bf16 v[76:79], v[128:131], v[232:235], v[76:79]
	v_mfma_f32_16x16x32_bf16 v[72:75], v[136:139], v[232:235], v[72:75]
	v_mfma_f32_16x16x32_bf16 v[124:127], v[132:135], v[212:215], v[124:127]
	v_mfma_f32_16x16x32_bf16 v[120:123], v[164:167], v[212:215], v[120:123]
	v_mfma_f32_16x16x32_bf16 v[108:111], v[132:135], v[220:223], v[108:111]
	v_mfma_f32_16x16x32_bf16 v[104:107], v[164:167], v[220:223], v[104:107]
	v_mfma_f32_16x16x32_bf16 v[92:95], v[132:135], v[228:231], v[92:95]
	v_mfma_f32_16x16x32_bf16 v[88:91], v[164:167], v[228:231], v[88:91]
	v_mfma_f32_16x16x32_bf16 v[76:79], v[132:135], v[236:239], v[76:79]
	v_mfma_f32_16x16x32_bf16 v[72:75], v[164:167], v[236:239], v[72:75]
	s_setprio 0
	s_setprio 1
	v_mfma_f32_16x16x32_bf16 v[116:119], v[188:191], v[208:211], v[116:119]
	v_mfma_f32_16x16x32_bf16 v[112:115], v[200:203], v[208:211], v[112:115]
	v_mfma_f32_16x16x32_bf16 v[100:103], v[188:191], v[216:219], v[100:103]
	v_mfma_f32_16x16x32_bf16 v[96:99], v[200:203], v[216:219], v[96:99]
	v_mfma_f32_16x16x32_bf16 v[84:87], v[188:191], v[224:227], v[84:87]
	v_mfma_f32_16x16x32_bf16 v[80:83], v[200:203], v[224:227], v[80:83]
	v_mfma_f32_16x16x32_bf16 v[68:71], v[188:191], v[232:235], v[68:71]
	v_mfma_f32_16x16x32_bf16 v[64:67], v[200:203], v[232:235], v[64:67]
	v_mfma_f32_16x16x32_bf16 v[116:119], v[196:199], v[212:215], v[116:119]
	v_mfma_f32_16x16x32_bf16 v[112:115], v[204:207], v[212:215], v[112:115]
	v_mfma_f32_16x16x32_bf16 v[100:103], v[196:199], v[220:223], v[100:103]
	v_mfma_f32_16x16x32_bf16 v[96:99], v[204:207], v[220:223], v[96:99]
	v_mfma_f32_16x16x32_bf16 v[84:87], v[196:199], v[228:231], v[84:87]
	v_mfma_f32_16x16x32_bf16 v[80:83], v[204:207], v[228:231], v[80:83]
	v_mfma_f32_16x16x32_bf16 v[68:71], v[196:199], v[236:239], v[68:71]
	v_mfma_f32_16x16x32_bf16 v[64:67], v[204:207], v[236:239], v[64:67]
	s_setprio 0
	s_barrier
	s_add_i32 s68, s52, s39
	v_lshl_add_u64 v[168:169], s[2:3], 0, v[142:143]
	s_mov_b32 m0, s68
	ds_read_b128 v[208:211], v185 offset:16384
	ds_read_b128 v[212:215], v185 offset:17408
	ds_read_b128 v[216:219], v185 offset:18432
	ds_read_b128 v[220:223], v185 offset:19456
	ds_read_b128 v[224:227], v185 offset:20480
	ds_read_b128 v[228:231], v185 offset:21504
	ds_read_b128 v[232:235], v185 offset:22528
	ds_read_b128 v[236:239], v185 offset:23552
	global_load_lds_dwordx4 v[168:169], off
	s_add_i32 m0, s68, 0x2000
	s_add_u32 s68, s2, 0x40000
	v_lshl_add_u64 v[192:193], s[2:3], 0, v[146:147]
	s_addc_u32 s69, s3, 0
	s_add_i32 s70, s53, s39
	global_load_lds_dwordx4 v[192:193], off
	v_lshl_add_u64 v[240:241], s[68:69], 0, v[142:143]
	s_mov_b32 m0, s70
	v_lshl_add_u64 v[242:243], s[22:23], 0, v[144:145]
	global_load_lds_dwordx4 v[240:241], off
	v_lshl_add_u64 v[240:241], s[68:69], 0, v[146:147]
	s_add_i32 m0, s70, 0x2000
	s_nop 0
	global_load_lds_dwordx4 v[240:241], off
	v_lshl_add_u64 v[240:241], s[22:23], 0, v[140:141]
	s_mov_b32 m0, s37
	s_nop 0
	global_load_lds_dwordx4 v[240:241], off
	s_mov_b32 m0, s40
	s_nop 0
	global_load_lds_dwordx4 v[242:243], off
	s_waitcnt vmcnt(8)
	s_waitcnt lgkmcnt(0)
	s_barrier
	s_setprio 1
	s_waitcnt lgkmcnt(0)
	v_mfma_f32_16x16x32_bf16 v[60:63], v[128:131], v[208:211], v[60:63]
	v_mfma_f32_16x16x32_bf16 v[56:59], v[136:139], v[208:211], v[56:59]
	v_mfma_f32_16x16x32_bf16 v[44:47], v[128:131], v[216:219], v[44:47]
	v_mfma_f32_16x16x32_bf16 v[40:43], v[136:139], v[216:219], v[40:43]
	v_mfma_f32_16x16x32_bf16 v[28:31], v[128:131], v[224:227], v[28:31]
	v_mfma_f32_16x16x32_bf16 v[24:27], v[136:139], v[224:227], v[24:27]
	v_mfma_f32_16x16x32_bf16 v[12:15], v[128:131], v[232:235], v[12:15]
	v_mfma_f32_16x16x32_bf16 v[8:11], v[136:139], v[232:235], v[8:11]
	v_mfma_f32_16x16x32_bf16 v[60:63], v[132:135], v[212:215], v[60:63]
	v_mfma_f32_16x16x32_bf16 v[56:59], v[164:167], v[212:215], v[56:59]
	v_mfma_f32_16x16x32_bf16 v[44:47], v[132:135], v[220:223], v[44:47]
	v_mfma_f32_16x16x32_bf16 v[40:43], v[164:167], v[220:223], v[40:43]
	v_mfma_f32_16x16x32_bf16 v[28:31], v[132:135], v[228:231], v[28:31]
	v_mfma_f32_16x16x32_bf16 v[24:27], v[164:167], v[228:231], v[24:27]
	v_mfma_f32_16x16x32_bf16 v[12:15], v[132:135], v[236:239], v[12:15]
	v_mfma_f32_16x16x32_bf16 v[8:11], v[164:167], v[236:239], v[8:11]
	s_setprio 0
	s_setprio 1
	v_mfma_f32_16x16x32_bf16 v[52:55], v[188:191], v[208:211], v[52:55]
	v_mfma_f32_16x16x32_bf16 v[48:51], v[200:203], v[208:211], v[48:51]
	v_mfma_f32_16x16x32_bf16 v[36:39], v[188:191], v[216:219], v[36:39]
	v_mfma_f32_16x16x32_bf16 v[32:35], v[200:203], v[216:219], v[32:35]
	v_mfma_f32_16x16x32_bf16 v[20:23], v[188:191], v[224:227], v[20:23]
	v_mfma_f32_16x16x32_bf16 v[16:19], v[200:203], v[224:227], v[16:19]
	v_mfma_f32_16x16x32_bf16 v[4:7], v[188:191], v[232:235], v[4:7]
	v_mfma_f32_16x16x32_bf16 v[0:3], v[200:203], v[232:235], v[0:3]
	v_mfma_f32_16x16x32_bf16 v[52:55], v[196:199], v[212:215], v[52:55]
	v_mfma_f32_16x16x32_bf16 v[48:51], v[204:207], v[212:215], v[48:51]
	v_mfma_f32_16x16x32_bf16 v[36:39], v[196:199], v[220:223], v[36:39]
	v_mfma_f32_16x16x32_bf16 v[32:35], v[204:207], v[220:223], v[32:35]
	v_mfma_f32_16x16x32_bf16 v[20:23], v[196:199], v[228:231], v[20:23]
	v_mfma_f32_16x16x32_bf16 v[16:19], v[204:207], v[228:231], v[16:19]
	v_mfma_f32_16x16x32_bf16 v[4:7], v[196:199], v[236:239], v[4:7]
	v_mfma_f32_16x16x32_bf16 v[0:3], v[204:207], v[236:239], v[0:3]
	s_setprio 0
	s_barrier
	s_add_i32 s68, 0, 0x18000
	s_add_i32 s69, 0, 0x1c000
	v_add_u32_e32 v164, s68, v149
	v_add_u32_e32 v187, s69, v149
	ds_read_b128 v[128:131], v164
	ds_read_b128 v[132:135], v164 offset:1024
	ds_read_b128 v[136:139], v164 offset:2048
	ds_read_b128 v[164:167], v164 offset:3072
	ds_read_b128 v[188:191], v187
	ds_read_b128 v[196:199], v187 offset:1024
	ds_read_b128 v[200:203], v187 offset:2048
	ds_read_b128 v[204:207], v187 offset:3072
	s_add_u32 s22, s22, 0x40000
	s_addc_u32 s23, s23, 0
	s_mov_b32 m0, s41
	v_lshl_add_u64 v[244:245], s[22:23], 0, v[140:141]
	ds_read_b128 v[208:211], v185 offset:32768
	ds_read_b128 v[212:215], v185 offset:33792
	ds_read_b128 v[216:219], v185 offset:34816
	ds_read_b128 v[220:223], v185 offset:35840
	ds_read_b128 v[224:227], v185 offset:36864
	ds_read_b128 v[228:231], v185 offset:37888
	ds_read_b128 v[232:235], v185 offset:38912
	ds_read_b128 v[236:239], v185 offset:39936
	global_load_lds_dwordx4 v[244:245], off
	v_lshl_add_u64 v[244:245], s[22:23], 0, v[144:145]
	s_mov_b32 m0, s42
	s_nop 0
	global_load_lds_dwordx4 v[244:245], off
	s_waitcnt vmcnt(8)
	s_waitcnt lgkmcnt(0)
	s_barrier
	s_setprio 1
	s_waitcnt lgkmcnt(0)
	v_mfma_f32_16x16x32_bf16 v[124:127], v[128:131], v[208:211], v[124:127]
	v_mfma_f32_16x16x32_bf16 v[120:123], v[136:139], v[208:211], v[120:123]
	v_mfma_f32_16x16x32_bf16 v[108:111], v[128:131], v[216:219], v[108:111]
	v_mfma_f32_16x16x32_bf16 v[104:107], v[136:139], v[216:219], v[104:107]
	v_mfma_f32_16x16x32_bf16 v[92:95], v[128:131], v[224:227], v[92:95]
	v_mfma_f32_16x16x32_bf16 v[88:91], v[136:139], v[224:227], v[88:91]
	v_mfma_f32_16x16x32_bf16 v[76:79], v[128:131], v[232:235], v[76:79]
	v_mfma_f32_16x16x32_bf16 v[72:75], v[136:139], v[232:235], v[72:75]
	v_mfma_f32_16x16x32_bf16 v[124:127], v[132:135], v[212:215], v[124:127]
	v_mfma_f32_16x16x32_bf16 v[120:123], v[164:167], v[212:215], v[120:123]
	v_mfma_f32_16x16x32_bf16 v[108:111], v[132:135], v[220:223], v[108:111]
	v_mfma_f32_16x16x32_bf16 v[104:107], v[164:167], v[220:223], v[104:107]
	v_mfma_f32_16x16x32_bf16 v[92:95], v[132:135], v[228:231], v[92:95]
	v_mfma_f32_16x16x32_bf16 v[88:91], v[164:167], v[228:231], v[88:91]
	v_mfma_f32_16x16x32_bf16 v[76:79], v[132:135], v[236:239], v[76:79]
	v_mfma_f32_16x16x32_bf16 v[72:75], v[164:167], v[236:239], v[72:75]
	s_setprio 0
	s_setprio 1
	v_mfma_f32_16x16x32_bf16 v[116:119], v[188:191], v[208:211], v[116:119]
	v_mfma_f32_16x16x32_bf16 v[112:115], v[200:203], v[208:211], v[112:115]
	v_mfma_f32_16x16x32_bf16 v[100:103], v[188:191], v[216:219], v[100:103]
	v_mfma_f32_16x16x32_bf16 v[96:99], v[200:203], v[216:219], v[96:99]
	v_mfma_f32_16x16x32_bf16 v[84:87], v[188:191], v[224:227], v[84:87]
	v_mfma_f32_16x16x32_bf16 v[80:83], v[200:203], v[224:227], v[80:83]
	v_mfma_f32_16x16x32_bf16 v[68:71], v[188:191], v[232:235], v[68:71]
	v_mfma_f32_16x16x32_bf16 v[64:67], v[200:203], v[232:235], v[64:67]
	v_mfma_f32_16x16x32_bf16 v[116:119], v[196:199], v[212:215], v[116:119]
	v_mfma_f32_16x16x32_bf16 v[112:115], v[204:207], v[212:215], v[112:115]
	v_mfma_f32_16x16x32_bf16 v[100:103], v[196:199], v[220:223], v[100:103]
	v_mfma_f32_16x16x32_bf16 v[96:99], v[204:207], v[220:223], v[96:99]
	v_mfma_f32_16x16x32_bf16 v[84:87], v[196:199], v[228:231], v[84:87]
	v_mfma_f32_16x16x32_bf16 v[80:83], v[204:207], v[228:231], v[80:83]
	v_mfma_f32_16x16x32_bf16 v[68:71], v[196:199], v[236:239], v[68:71]
	v_mfma_f32_16x16x32_bf16 v[64:67], v[204:207], v[236:239], v[64:67]
	s_setprio 0
	s_barrier
	s_add_i32 s22, s68, s39
	v_lshl_add_u64 v[168:169], v[168:169], 0, s[18:19]
	s_mov_b32 m0, s22
	ds_read_b128 v[208:211], v185 offset:49152
	ds_read_b128 v[212:215], v185 offset:50176
	ds_read_b128 v[216:219], v185 offset:51200
	ds_read_b128 v[220:223], v185 offset:52224
	ds_read_b128 v[224:227], v185 offset:53248
	ds_read_b128 v[228:231], v185 offset:54272
	ds_read_b128 v[232:235], v185 offset:55296
	ds_read_b128 v[236:239], v185 offset:56320
	global_load_lds_dwordx4 v[168:169], off
	s_add_i32 m0, s22, 0x2000
	s_add_u32 s2, s2, 0x40080
	v_lshl_add_u64 v[168:169], v[192:193], 0, s[18:19]
	s_addc_u32 s3, s3, 0
	s_add_i32 s22, s69, s39
	global_load_lds_dwordx4 v[168:169], off
	v_lshl_add_u64 v[168:169], s[2:3], 0, v[142:143]
	s_mov_b32 m0, s22
	s_nop 0
	global_load_lds_dwordx4 v[168:169], off
	v_lshl_add_u64 v[168:169], s[2:3], 0, v[146:147]
	s_add_i32 m0, s22, 0x2000
	s_nop 0
	global_load_lds_dwordx4 v[168:169], off
	v_lshl_add_u64 v[168:169], v[240:241], 0, s[18:19]
	s_mov_b32 m0, s46
	s_nop 0
	global_load_lds_dwordx4 v[168:169], off
	v_lshl_add_u64 v[168:169], v[242:243], 0, s[18:19]
	s_mov_b32 m0, s47
	s_nop 0
	global_load_lds_dwordx4 v[168:169], off
	s_waitcnt vmcnt(8)
	s_waitcnt lgkmcnt(0)
	s_barrier
	s_setprio 1
	s_waitcnt lgkmcnt(0)
	v_mfma_f32_16x16x32_bf16 v[60:63], v[128:131], v[208:211], v[60:63]
	v_mfma_f32_16x16x32_bf16 v[56:59], v[136:139], v[208:211], v[56:59]
	v_mfma_f32_16x16x32_bf16 v[44:47], v[128:131], v[216:219], v[44:47]
	v_mfma_f32_16x16x32_bf16 v[40:43], v[136:139], v[216:219], v[40:43]
	v_mfma_f32_16x16x32_bf16 v[28:31], v[128:131], v[224:227], v[28:31]
	v_mfma_f32_16x16x32_bf16 v[24:27], v[136:139], v[224:227], v[24:27]
	v_mfma_f32_16x16x32_bf16 v[12:15], v[128:131], v[232:235], v[12:15]
	v_mfma_f32_16x16x32_bf16 v[8:11], v[136:139], v[232:235], v[8:11]
	v_mfma_f32_16x16x32_bf16 v[60:63], v[132:135], v[212:215], v[60:63]
	v_mfma_f32_16x16x32_bf16 v[56:59], v[164:167], v[212:215], v[56:59]
	v_mfma_f32_16x16x32_bf16 v[44:47], v[132:135], v[220:223], v[44:47]
	v_mfma_f32_16x16x32_bf16 v[40:43], v[164:167], v[220:223], v[40:43]
	v_mfma_f32_16x16x32_bf16 v[28:31], v[132:135], v[228:231], v[28:31]
	v_mfma_f32_16x16x32_bf16 v[24:27], v[164:167], v[228:231], v[24:27]
	v_mfma_f32_16x16x32_bf16 v[12:15], v[132:135], v[236:239], v[12:15]
	v_mfma_f32_16x16x32_bf16 v[8:11], v[164:167], v[236:239], v[8:11]
	s_setprio 0
	s_setprio 1
	v_mfma_f32_16x16x32_bf16 v[52:55], v[188:191], v[208:211], v[52:55]
	v_mfma_f32_16x16x32_bf16 v[48:51], v[200:203], v[208:211], v[48:51]
	v_mfma_f32_16x16x32_bf16 v[36:39], v[188:191], v[216:219], v[36:39]
	v_mfma_f32_16x16x32_bf16 v[32:35], v[200:203], v[216:219], v[32:35]
	v_mfma_f32_16x16x32_bf16 v[20:23], v[188:191], v[224:227], v[20:23]
	v_mfma_f32_16x16x32_bf16 v[16:19], v[200:203], v[224:227], v[16:19]
	v_mfma_f32_16x16x32_bf16 v[4:7], v[188:191], v[232:235], v[4:7]
	v_mfma_f32_16x16x32_bf16 v[0:3], v[200:203], v[232:235], v[0:3]
	v_mfma_f32_16x16x32_bf16 v[52:55], v[196:199], v[212:215], v[52:55]
	v_mfma_f32_16x16x32_bf16 v[48:51], v[204:207], v[212:215], v[48:51]
	v_mfma_f32_16x16x32_bf16 v[36:39], v[196:199], v[220:223], v[36:39]
	v_mfma_f32_16x16x32_bf16 v[32:35], v[204:207], v[220:223], v[32:35]
	v_mfma_f32_16x16x32_bf16 v[20:23], v[196:199], v[228:231], v[20:23]
	v_mfma_f32_16x16x32_bf16 v[16:19], v[204:207], v[228:231], v[16:19]
	v_mfma_f32_16x16x32_bf16 v[4:7], v[196:199], v[236:239], v[4:7]
	v_mfma_f32_16x16x32_bf16 v[0:3], v[204:207], v[236:239], v[0:3]
	s_setprio 0
	s_add_i32 s67, s67, 2
	s_add_u32 s14, s14, 0x100
	s_addc_u32 s15, s15, 0
	s_add_u32 s65, s65, 0x100
	s_addc_u32 s66, s66, 0
	s_cmp_gt_u32 s67, 13
	s_barrier
	s_cbranch_scc0 .LBB0_725

.LBB0_808:
	s_ashr_i32 s25, s24, 31
	s_lshl_b64 s[22:23], s[24:25], 19
	s_add_u32 s26, s84, s22
	s_addc_u32 s27, s85, s23
	s_and_b64 s[22:23], s[4:5], exec
	s_cselect_b32 s25, s27, s15
	s_cselect_b32 s50, s26, s14
	s_ashr_i32 s21, s20, 31
	s_lshl_b64 s[22:23], s[20:21], 19
	s_add_u32 s28, s30, s22
	s_addc_u32 s29, s31, s23
	s_and_b64 s[22:23], s[4:5], exec
	s_cselect_b32 s21, s29, s3
	s_cselect_b32 s51, s28, s2
	s_add_u32 s14, s14, 0x40080
	s_addc_u32 s15, s15, 0
	s_add_u32 s52, s2, 0x100
	s_addc_u32 s53, s3, 0
	s_mov_b32 s54, -2
	s_waitcnt vmcnt(0)
	ds_read_b128 v[136:139], v155
	ds_read_b128 v[162:165], v155 offset:1024
	ds_read_b128 v[166:169], v155 offset:2048
	ds_read_b128 v[178:181], v155 offset:3072
	ds_read_b128 v[184:187], v158
	ds_read_b128 v[188:191], v158 offset:1024
	ds_read_b128 v[196:199], v158 offset:2048
	ds_read_b128 v[200:203], v158 offset:3072
	s_add_u32 s2, s14, 0xfffc0080
	s_addc_u32 s3, s15, -1
	s_cmp_eq_u32 s54, 12
	s_cselect_b32 s23, s25, s3
	s_cselect_b32 s22, s50, s2
	s_cselect_b32 s3, s21, s53
	s_cselect_b32 s2, s51, s52
	v_lshl_add_u64 v[156:157], s[14:15], 0, v[128:129]
	s_add_i32 m0, s37, 0xc000
	ds_read_b128 v[204:207], v159
	ds_read_b128 v[208:211], v159 offset:1024
	ds_read_b128 v[212:215], v159 offset:2048
	ds_read_b128 v[216:219], v159 offset:3072
	ds_read_b128 v[220:223], v159 offset:4096
	ds_read_b128 v[224:227], v159 offset:5120
	ds_read_b128 v[228:231], v159 offset:6144
	ds_read_b128 v[232:235], v159 offset:7168
	global_load_lds_dwordx4 v[156:157], off
	v_lshl_add_u64 v[156:157], s[14:15], 0, v[130:131]
	s_add_i32 m0, s37, 0xe000
	s_nop 0
	global_load_lds_dwordx4 v[156:157], off
	s_waitcnt vmcnt(8)
	s_waitcnt lgkmcnt(0)
	s_barrier
	s_setprio 1
	s_waitcnt lgkmcnt(0)
	v_mfma_f32_16x16x32_bf16 v[112:115], v[136:139], v[204:207], 0
	v_mfma_f32_16x16x32_bf16 v[108:111], v[166:169], v[204:207], 0
	v_mfma_f32_16x16x32_bf16 v[104:107], v[136:139], v[212:215], 0
	v_mfma_f32_16x16x32_bf16 v[100:103], v[166:169], v[212:215], 0
	v_mfma_f32_16x16x32_bf16 v[92:95], v[136:139], v[220:223], 0
	v_mfma_f32_16x16x32_bf16 v[84:87], v[166:169], v[220:223], 0
	v_mfma_f32_16x16x32_bf16 v[76:79], v[136:139], v[228:231], 0
	v_mfma_f32_16x16x32_bf16 v[68:71], v[166:169], v[228:231], 0
	v_mfma_f32_16x16x32_bf16 v[112:115], v[162:165], v[208:211], v[112:115]
	v_mfma_f32_16x16x32_bf16 v[108:111], v[178:181], v[208:211], v[108:111]
	v_mfma_f32_16x16x32_bf16 v[104:107], v[162:165], v[216:219], v[104:107]
	v_mfma_f32_16x16x32_bf16 v[100:103], v[178:181], v[216:219], v[100:103]
	v_mfma_f32_16x16x32_bf16 v[92:95], v[162:165], v[224:227], v[92:95]
	v_mfma_f32_16x16x32_bf16 v[84:87], v[178:181], v[224:227], v[84:87]
	v_mfma_f32_16x16x32_bf16 v[76:79], v[162:165], v[232:235], v[76:79]
	v_mfma_f32_16x16x32_bf16 v[68:71], v[178:181], v[232:235], v[68:71]
	s_setprio 0
	s_setprio 1
	v_mfma_f32_16x16x32_bf16 v[124:127], v[184:187], v[204:207], 0
	v_mfma_f32_16x16x32_bf16 v[120:123], v[196:199], v[204:207], 0
	v_mfma_f32_16x16x32_bf16 v[116:119], v[184:187], v[212:215], 0
	v_mfma_f32_16x16x32_bf16 v[96:99], v[196:199], v[212:215], 0
	v_mfma_f32_16x16x32_bf16 v[88:91], v[184:187], v[220:223], 0
	v_mfma_f32_16x16x32_bf16 v[80:83], v[196:199], v[220:223], 0
	v_mfma_f32_16x16x32_bf16 v[72:75], v[184:187], v[228:231], 0
	v_mfma_f32_16x16x32_bf16 v[64:67], v[196:199], v[228:231], 0
	v_mfma_f32_16x16x32_bf16 v[124:127], v[188:191], v[208:211], v[124:127]
	v_mfma_f32_16x16x32_bf16 v[120:123], v[200:203], v[208:211], v[120:123]
	v_mfma_f32_16x16x32_bf16 v[116:119], v[188:191], v[216:219], v[116:119]
	v_mfma_f32_16x16x32_bf16 v[96:99], v[200:203], v[216:219], v[96:99]
	v_mfma_f32_16x16x32_bf16 v[88:91], v[188:191], v[224:227], v[88:91]
	v_mfma_f32_16x16x32_bf16 v[80:83], v[200:203], v[224:227], v[80:83]
	v_mfma_f32_16x16x32_bf16 v[72:75], v[188:191], v[232:235], v[72:75]
	v_mfma_f32_16x16x32_bf16 v[64:67], v[200:203], v[232:235], v[64:67]
	s_setprio 0
	s_barrier
	s_add_i32 s55, s46, s34
	v_lshl_add_u64 v[156:157], s[2:3], 0, v[142:143]
	s_mov_b32 m0, s55
	ds_read_b128 v[204:207], v159 offset:16384
	ds_read_b128 v[208:211], v159 offset:17408
	ds_read_b128 v[212:215], v159 offset:18432
	ds_read_b128 v[216:219], v159 offset:19456
	ds_read_b128 v[220:223], v159 offset:20480
	ds_read_b128 v[224:227], v159 offset:21504
	ds_read_b128 v[228:231], v159 offset:22528
	ds_read_b128 v[232:235], v159 offset:23552
	global_load_lds_dwordx4 v[156:157], off
	s_add_i32 m0, s55, 0x2000
	s_add_u32 s56, s2, 0x40000
	v_lshl_add_u64 v[192:193], s[2:3], 0, v[146:147]
	s_addc_u32 s57, s3, 0
	s_add_i32 s55, s47, s34
	global_load_lds_dwordx4 v[192:193], off
	v_lshl_add_u64 v[236:237], s[56:57], 0, v[142:143]
	s_mov_b32 m0, s55
	v_lshl_add_u64 v[238:239], s[22:23], 0, v[144:145]
	global_load_lds_dwordx4 v[236:237], off
	v_lshl_add_u64 v[236:237], s[56:57], 0, v[146:147]
	s_add_i32 m0, s55, 0x2000
	s_nop 0
	global_load_lds_dwordx4 v[236:237], off
	v_lshl_add_u64 v[236:237], s[22:23], 0, v[140:141]
	s_mov_b32 m0, s37
	s_nop 0
	global_load_lds_dwordx4 v[236:237], off
	s_mov_b32 m0, s38
	s_nop 0
	global_load_lds_dwordx4 v[238:239], off
	s_waitcnt vmcnt(8)
	s_waitcnt lgkmcnt(0)
	s_barrier
	s_setprio 1
	s_waitcnt lgkmcnt(0)
	v_mfma_f32_16x16x32_bf16 v[60:63], v[136:139], v[204:207], 0
	v_mfma_f32_16x16x32_bf16 v[52:55], v[166:169], v[204:207], 0
	v_mfma_f32_16x16x32_bf16 v[44:47], v[136:139], v[212:215], 0
	v_mfma_f32_16x16x32_bf16 v[36:39], v[166:169], v[212:215], 0
	v_mfma_f32_16x16x32_bf16 v[28:31], v[136:139], v[220:223], 0
	v_mfma_f32_16x16x32_bf16 v[20:23], v[166:169], v[220:223], 0
	v_mfma_f32_16x16x32_bf16 v[12:15], v[136:139], v[228:231], 0
	v_mfma_f32_16x16x32_bf16 v[4:7], v[166:169], v[228:231], 0
	v_mfma_f32_16x16x32_bf16 v[60:63], v[162:165], v[208:211], v[60:63]
	v_mfma_f32_16x16x32_bf16 v[52:55], v[178:181], v[208:211], v[52:55]
	v_mfma_f32_16x16x32_bf16 v[44:47], v[162:165], v[216:219], v[44:47]
	v_mfma_f32_16x16x32_bf16 v[36:39], v[178:181], v[216:219], v[36:39]
	v_mfma_f32_16x16x32_bf16 v[28:31], v[162:165], v[224:227], v[28:31]
	v_mfma_f32_16x16x32_bf16 v[20:23], v[178:181], v[224:227], v[20:23]
	v_mfma_f32_16x16x32_bf16 v[12:15], v[162:165], v[232:235], v[12:15]
	v_mfma_f32_16x16x32_bf16 v[4:7], v[178:181], v[232:235], v[4:7]
	s_setprio 0
	s_setprio 1
	v_mfma_f32_16x16x32_bf16 v[56:59], v[184:187], v[204:207], 0
	v_mfma_f32_16x16x32_bf16 v[48:51], v[196:199], v[204:207], 0
	v_mfma_f32_16x16x32_bf16 v[40:43], v[184:187], v[212:215], 0
	v_mfma_f32_16x16x32_bf16 v[32:35], v[196:199], v[212:215], 0
	v_mfma_f32_16x16x32_bf16 v[24:27], v[184:187], v[220:223], 0
	v_mfma_f32_16x16x32_bf16 v[16:19], v[196:199], v[220:223], 0
	v_mfma_f32_16x16x32_bf16 v[8:11], v[184:187], v[228:231], 0
	v_mfma_f32_16x16x32_bf16 v[0:3], v[196:199], v[228:231], 0
	v_mfma_f32_16x16x32_bf16 v[56:59], v[188:191], v[208:211], v[56:59]
	v_mfma_f32_16x16x32_bf16 v[48:51], v[200:203], v[208:211], v[48:51]
	v_mfma_f32_16x16x32_bf16 v[40:43], v[188:191], v[216:219], v[40:43]
	v_mfma_f32_16x16x32_bf16 v[32:35], v[200:203], v[216:219], v[32:35]
	v_mfma_f32_16x16x32_bf16 v[24:27], v[188:191], v[224:227], v[24:27]
	v_mfma_f32_16x16x32_bf16 v[16:19], v[200:203], v[224:227], v[16:19]
	v_mfma_f32_16x16x32_bf16 v[8:11], v[188:191], v[232:235], v[8:11]
	v_mfma_f32_16x16x32_bf16 v[0:3], v[200:203], v[232:235], v[0:3]
	s_setprio 0
	s_barrier
	s_add_i32 s55, 0, 0x18000
	v_add_u32_e32 v161, s55, v151
	s_add_i32 s56, 0, 0x1c000
	ds_read_b128 v[136:139], v161
	ds_read_b128 v[162:165], v161 offset:1024
	ds_read_b128 v[166:169], v161 offset:2048
	ds_read_b128 v[178:181], v161 offset:3072
	v_add_u32_e32 v161, s56, v151
	ds_read_b128 v[184:187], v161
	ds_read_b128 v[188:191], v161 offset:1024
	ds_read_b128 v[196:199], v161 offset:2048
	ds_read_b128 v[200:203], v161 offset:3072
	s_add_u32 s22, s22, 0x40000
	s_addc_u32 s23, s23, 0
	s_mov_b32 m0, s39
	v_lshl_add_u64 v[240:241], s[22:23], 0, v[140:141]
	ds_read_b128 v[204:207], v159 offset:32768
	ds_read_b128 v[208:211], v159 offset:33792
	ds_read_b128 v[212:215], v159 offset:34816
	ds_read_b128 v[216:219], v159 offset:35840
	ds_read_b128 v[220:223], v159 offset:36864
	ds_read_b128 v[224:227], v159 offset:37888
	ds_read_b128 v[228:231], v159 offset:38912
	ds_read_b128 v[232:235], v159 offset:39936
	global_load_lds_dwordx4 v[240:241], off
	v_lshl_add_u64 v[240:241], s[22:23], 0, v[144:145]
	s_mov_b32 m0, s40
	s_nop 0
	global_load_lds_dwordx4 v[240:241], off
	s_waitcnt vmcnt(8)
	s_waitcnt lgkmcnt(0)
	s_barrier
	s_setprio 1
	s_waitcnt lgkmcnt(0)
	v_mfma_f32_16x16x32_bf16 v[112:115], v[136:139], v[204:207], v[112:115]
	v_mfma_f32_16x16x32_bf16 v[108:111], v[166:169], v[204:207], v[108:111]
	v_mfma_f32_16x16x32_bf16 v[104:107], v[136:139], v[212:215], v[104:107]
	v_mfma_f32_16x16x32_bf16 v[100:103], v[166:169], v[212:215], v[100:103]
	v_mfma_f32_16x16x32_bf16 v[92:95], v[136:139], v[220:223], v[92:95]
	v_mfma_f32_16x16x32_bf16 v[84:87], v[166:169], v[220:223], v[84:87]
	v_mfma_f32_16x16x32_bf16 v[76:79], v[136:139], v[228:231], v[76:79]
	v_mfma_f32_16x16x32_bf16 v[68:71], v[166:169], v[228:231], v[68:71]
	v_mfma_f32_16x16x32_bf16 v[112:115], v[162:165], v[208:211], v[112:115]
	v_mfma_f32_16x16x32_bf16 v[108:111], v[178:181], v[208:211], v[108:111]
	v_mfma_f32_16x16x32_bf16 v[104:107], v[162:165], v[216:219], v[104:107]
	v_mfma_f32_16x16x32_bf16 v[100:103], v[178:181], v[216:219], v[100:103]
	v_mfma_f32_16x16x32_bf16 v[92:95], v[162:165], v[224:227], v[92:95]
	v_mfma_f32_16x16x32_bf16 v[84:87], v[178:181], v[224:227], v[84:87]
	v_mfma_f32_16x16x32_bf16 v[76:79], v[162:165], v[232:235], v[76:79]
	v_mfma_f32_16x16x32_bf16 v[68:71], v[178:181], v[232:235], v[68:71]
	s_setprio 0
	s_setprio 1
	v_mfma_f32_16x16x32_bf16 v[124:127], v[184:187], v[204:207], v[124:127]
	v_mfma_f32_16x16x32_bf16 v[120:123], v[196:199], v[204:207], v[120:123]
	v_mfma_f32_16x16x32_bf16 v[116:119], v[184:187], v[212:215], v[116:119]
	v_mfma_f32_16x16x32_bf16 v[96:99], v[196:199], v[212:215], v[96:99]
	v_mfma_f32_16x16x32_bf16 v[88:91], v[184:187], v[220:223], v[88:91]
	v_mfma_f32_16x16x32_bf16 v[80:83], v[196:199], v[220:223], v[80:83]
	v_mfma_f32_16x16x32_bf16 v[72:75], v[184:187], v[228:231], v[72:75]
	v_mfma_f32_16x16x32_bf16 v[64:67], v[196:199], v[228:231], v[64:67]
	v_mfma_f32_16x16x32_bf16 v[124:127], v[188:191], v[208:211], v[124:127]
	v_mfma_f32_16x16x32_bf16 v[120:123], v[200:203], v[208:211], v[120:123]
	v_mfma_f32_16x16x32_bf16 v[116:119], v[188:191], v[216:219], v[116:119]
	v_mfma_f32_16x16x32_bf16 v[96:99], v[200:203], v[216:219], v[96:99]
	v_mfma_f32_16x16x32_bf16 v[88:91], v[188:191], v[224:227], v[88:91]
	v_mfma_f32_16x16x32_bf16 v[80:83], v[200:203], v[224:227], v[80:83]
	v_mfma_f32_16x16x32_bf16 v[72:75], v[188:191], v[232:235], v[72:75]
	v_mfma_f32_16x16x32_bf16 v[64:67], v[200:203], v[232:235], v[64:67]
	s_setprio 0
	s_barrier
	s_add_i32 s22, s55, s34
	v_lshl_add_u64 v[156:157], v[156:157], 0, s[12:13]
	s_mov_b32 m0, s22
	ds_read_b128 v[204:207], v159 offset:49152
	ds_read_b128 v[208:211], v159 offset:50176
	ds_read_b128 v[212:215], v159 offset:51200
	ds_read_b128 v[216:219], v159 offset:52224
	ds_read_b128 v[220:223], v159 offset:53248
	ds_read_b128 v[224:227], v159 offset:54272
	ds_read_b128 v[228:231], v159 offset:55296
	ds_read_b128 v[232:235], v159 offset:56320
	global_load_lds_dwordx4 v[156:157], off
	s_add_i32 m0, s22, 0x2000
	s_add_u32 s2, s2, 0x40080
	v_lshl_add_u64 v[156:157], v[192:193], 0, s[12:13]
	s_addc_u32 s3, s3, 0
	s_add_i32 s22, s56, s34
	global_load_lds_dwordx4 v[156:157], off
	v_lshl_add_u64 v[156:157], s[2:3], 0, v[142:143]
	s_mov_b32 m0, s22
	s_nop 0
	global_load_lds_dwordx4 v[156:157], off
	v_lshl_add_u64 v[156:157], s[2:3], 0, v[146:147]
	s_add_i32 m0, s22, 0x2000
	s_nop 0
	global_load_lds_dwordx4 v[156:157], off
	v_lshl_add_u64 v[156:157], v[236:237], 0, s[12:13]
	s_mov_b32 m0, s42
	s_nop 0
	global_load_lds_dwordx4 v[156:157], off
	v_lshl_add_u64 v[156:157], v[238:239], 0, s[12:13]
	s_mov_b32 m0, s43
	s_nop 0
	global_load_lds_dwordx4 v[156:157], off
	s_waitcnt vmcnt(8)
	s_waitcnt lgkmcnt(0)
	s_barrier
	s_setprio 1
	s_waitcnt lgkmcnt(0)
	v_mfma_f32_16x16x32_bf16 v[60:63], v[136:139], v[204:207], v[60:63]
	v_mfma_f32_16x16x32_bf16 v[52:55], v[166:169], v[204:207], v[52:55]
	v_mfma_f32_16x16x32_bf16 v[44:47], v[136:139], v[212:215], v[44:47]
	v_mfma_f32_16x16x32_bf16 v[36:39], v[166:169], v[212:215], v[36:39]
	v_mfma_f32_16x16x32_bf16 v[28:31], v[136:139], v[220:223], v[28:31]
	v_mfma_f32_16x16x32_bf16 v[20:23], v[166:169], v[220:223], v[20:23]
	v_mfma_f32_16x16x32_bf16 v[12:15], v[136:139], v[228:231], v[12:15]
	v_mfma_f32_16x16x32_bf16 v[4:7], v[166:169], v[228:231], v[4:7]
	v_mfma_f32_16x16x32_bf16 v[60:63], v[162:165], v[208:211], v[60:63]
	v_mfma_f32_16x16x32_bf16 v[52:55], v[178:181], v[208:211], v[52:55]
	v_mfma_f32_16x16x32_bf16 v[44:47], v[162:165], v[216:219], v[44:47]
	v_mfma_f32_16x16x32_bf16 v[36:39], v[178:181], v[216:219], v[36:39]
	v_mfma_f32_16x16x32_bf16 v[28:31], v[162:165], v[224:227], v[28:31]
	v_mfma_f32_16x16x32_bf16 v[20:23], v[178:181], v[224:227], v[20:23]
	v_mfma_f32_16x16x32_bf16 v[12:15], v[162:165], v[232:235], v[12:15]
	v_mfma_f32_16x16x32_bf16 v[4:7], v[178:181], v[232:235], v[4:7]
	s_setprio 0
	s_setprio 1
	v_mfma_f32_16x16x32_bf16 v[56:59], v[184:187], v[204:207], v[56:59]
	v_mfma_f32_16x16x32_bf16 v[48:51], v[196:199], v[204:207], v[48:51]
	v_mfma_f32_16x16x32_bf16 v[40:43], v[184:187], v[212:215], v[40:43]
	v_mfma_f32_16x16x32_bf16 v[32:35], v[196:199], v[212:215], v[32:35]
	v_mfma_f32_16x16x32_bf16 v[24:27], v[184:187], v[220:223], v[24:27]
	v_mfma_f32_16x16x32_bf16 v[16:19], v[196:199], v[220:223], v[16:19]
	v_mfma_f32_16x16x32_bf16 v[8:11], v[184:187], v[228:231], v[8:11]
	v_mfma_f32_16x16x32_bf16 v[0:3], v[196:199], v[228:231], v[0:3]
	v_mfma_f32_16x16x32_bf16 v[56:59], v[188:191], v[208:211], v[56:59]
	v_mfma_f32_16x16x32_bf16 v[48:51], v[200:203], v[208:211], v[48:51]
	v_mfma_f32_16x16x32_bf16 v[40:43], v[188:191], v[216:219], v[40:43]
	v_mfma_f32_16x16x32_bf16 v[32:35], v[200:203], v[216:219], v[32:35]
	v_mfma_f32_16x16x32_bf16 v[24:27], v[188:191], v[224:227], v[24:27]
	v_mfma_f32_16x16x32_bf16 v[16:19], v[200:203], v[224:227], v[16:19]
	v_mfma_f32_16x16x32_bf16 v[8:11], v[188:191], v[232:235], v[8:11]
	v_mfma_f32_16x16x32_bf16 v[0:3], v[200:203], v[232:235], v[0:3]
	s_setprio 0
	s_add_i32 s54, s54, 2
	s_add_u32 s14, s14, 0x100
	s_addc_u32 s15, s15, 0
	s_add_u32 s52, s52, 0x100
	s_addc_u32 s53, s53, 0
	s_cmp_gt_u32 s54, 13
	s_barrier
	s_cbranch_scc1 .Lgemm_kdone_5
.LBB0_809:
	ds_read_b128 v[136:139], v155
	ds_read_b128 v[162:165], v155 offset:1024
	ds_read_b128 v[166:169], v155 offset:2048
	ds_read_b128 v[178:181], v155 offset:3072
	ds_read_b128 v[184:187], v158
	ds_read_b128 v[188:191], v158 offset:1024
	ds_read_b128 v[196:199], v158 offset:2048
	ds_read_b128 v[200:203], v158 offset:3072
	s_add_u32 s2, s14, 0xfffc0080
	s_addc_u32 s3, s15, -1
	s_cmp_eq_u32 s54, 12
	s_cselect_b32 s23, s25, s3
	s_cselect_b32 s22, s50, s2
	s_cselect_b32 s3, s21, s53
	s_cselect_b32 s2, s51, s52
	v_lshl_add_u64 v[156:157], s[14:15], 0, v[128:129]
	s_add_i32 m0, s37, 0xc000
	ds_read_b128 v[204:207], v159
	ds_read_b128 v[208:211], v159 offset:1024
	ds_read_b128 v[212:215], v159 offset:2048
	ds_read_b128 v[216:219], v159 offset:3072
	ds_read_b128 v[220:223], v159 offset:4096
	ds_read_b128 v[224:227], v159 offset:5120
	ds_read_b128 v[228:231], v159 offset:6144
	ds_read_b128 v[232:235], v159 offset:7168
	global_load_lds_dwordx4 v[156:157], off
	v_lshl_add_u64 v[156:157], s[14:15], 0, v[130:131]
	s_add_i32 m0, s37, 0xe000
	s_nop 0
	global_load_lds_dwordx4 v[156:157], off
	s_waitcnt vmcnt(8)
	s_waitcnt lgkmcnt(0)
	s_barrier
	s_setprio 1
	s_waitcnt lgkmcnt(0)
	v_mfma_f32_16x16x32_bf16 v[112:115], v[136:139], v[204:207], v[112:115]
	v_mfma_f32_16x16x32_bf16 v[108:111], v[166:169], v[204:207], v[108:111]
	v_mfma_f32_16x16x32_bf16 v[104:107], v[136:139], v[212:215], v[104:107]
	v_mfma_f32_16x16x32_bf16 v[100:103], v[166:169], v[212:215], v[100:103]
	v_mfma_f32_16x16x32_bf16 v[92:95], v[136:139], v[220:223], v[92:95]
	v_mfma_f32_16x16x32_bf16 v[84:87], v[166:169], v[220:223], v[84:87]
	v_mfma_f32_16x16x32_bf16 v[76:79], v[136:139], v[228:231], v[76:79]
	v_mfma_f32_16x16x32_bf16 v[68:71], v[166:169], v[228:231], v[68:71]
	v_mfma_f32_16x16x32_bf16 v[112:115], v[162:165], v[208:211], v[112:115]
	v_mfma_f32_16x16x32_bf16 v[108:111], v[178:181], v[208:211], v[108:111]
	v_mfma_f32_16x16x32_bf16 v[104:107], v[162:165], v[216:219], v[104:107]
	v_mfma_f32_16x16x32_bf16 v[100:103], v[178:181], v[216:219], v[100:103]
	v_mfma_f32_16x16x32_bf16 v[92:95], v[162:165], v[224:227], v[92:95]
	v_mfma_f32_16x16x32_bf16 v[84:87], v[178:181], v[224:227], v[84:87]
	v_mfma_f32_16x16x32_bf16 v[76:79], v[162:165], v[232:235], v[76:79]
	v_mfma_f32_16x16x32_bf16 v[68:71], v[178:181], v[232:235], v[68:71]
	s_setprio 0
	s_setprio 1
	v_mfma_f32_16x16x32_bf16 v[124:127], v[184:187], v[204:207], v[124:127]
	v_mfma_f32_16x16x32_bf16 v[120:123], v[196:199], v[204:207], v[120:123]
	v_mfma_f32_16x16x32_bf16 v[116:119], v[184:187], v[212:215], v[116:119]
	v_mfma_f32_16x16x32_bf16 v[96:99], v[196:199], v[212:215], v[96:99]
	v_mfma_f32_16x16x32_bf16 v[88:91], v[184:187], v[220:223], v[88:91]
	v_mfma_f32_16x16x32_bf16 v[80:83], v[196:199], v[220:223], v[80:83]
	v_mfma_f32_16x16x32_bf16 v[72:75], v[184:187], v[228:231], v[72:75]
	v_mfma_f32_16x16x32_bf16 v[64:67], v[196:199], v[228:231], v[64:67]
	v_mfma_f32_16x16x32_bf16 v[124:127], v[188:191], v[208:211], v[124:127]
	v_mfma_f32_16x16x32_bf16 v[120:123], v[200:203], v[208:211], v[120:123]
	v_mfma_f32_16x16x32_bf16 v[116:119], v[188:191], v[216:219], v[116:119]
	v_mfma_f32_16x16x32_bf16 v[96:99], v[200:203], v[216:219], v[96:99]
	v_mfma_f32_16x16x32_bf16 v[88:91], v[188:191], v[224:227], v[88:91]
	v_mfma_f32_16x16x32_bf16 v[80:83], v[200:203], v[224:227], v[80:83]
	v_mfma_f32_16x16x32_bf16 v[72:75], v[188:191], v[232:235], v[72:75]
	v_mfma_f32_16x16x32_bf16 v[64:67], v[200:203], v[232:235], v[64:67]
	s_setprio 0
	s_barrier
	s_add_i32 s55, s46, s34
	v_lshl_add_u64 v[156:157], s[2:3], 0, v[142:143]
	s_mov_b32 m0, s55
	ds_read_b128 v[204:207], v159 offset:16384
	ds_read_b128 v[208:211], v159 offset:17408
	ds_read_b128 v[212:215], v159 offset:18432
	ds_read_b128 v[216:219], v159 offset:19456
	ds_read_b128 v[220:223], v159 offset:20480
	ds_read_b128 v[224:227], v159 offset:21504
	ds_read_b128 v[228:231], v159 offset:22528
	ds_read_b128 v[232:235], v159 offset:23552
	global_load_lds_dwordx4 v[156:157], off
	s_add_i32 m0, s55, 0x2000
	s_add_u32 s56, s2, 0x40000
	v_lshl_add_u64 v[192:193], s[2:3], 0, v[146:147]
	s_addc_u32 s57, s3, 0
	s_add_i32 s55, s47, s34
	global_load_lds_dwordx4 v[192:193], off
	v_lshl_add_u64 v[236:237], s[56:57], 0, v[142:143]
	s_mov_b32 m0, s55
	v_lshl_add_u64 v[238:239], s[22:23], 0, v[144:145]
	global_load_lds_dwordx4 v[236:237], off
	v_lshl_add_u64 v[236:237], s[56:57], 0, v[146:147]
	s_add_i32 m0, s55, 0x2000
	s_nop 0
	global_load_lds_dwordx4 v[236:237], off
	v_lshl_add_u64 v[236:237], s[22:23], 0, v[140:141]
	s_mov_b32 m0, s37
	s_nop 0
	global_load_lds_dwordx4 v[236:237], off
	s_mov_b32 m0, s38
	s_nop 0
	global_load_lds_dwordx4 v[238:239], off
	s_waitcnt vmcnt(8)
	s_waitcnt lgkmcnt(0)
	s_barrier
	s_setprio 1
	s_waitcnt lgkmcnt(0)
	v_mfma_f32_16x16x32_bf16 v[60:63], v[136:139], v[204:207], v[60:63]
	v_mfma_f32_16x16x32_bf16 v[52:55], v[166:169], v[204:207], v[52:55]
	v_mfma_f32_16x16x32_bf16 v[44:47], v[136:139], v[212:215], v[44:47]
	v_mfma_f32_16x16x32_bf16 v[36:39], v[166:169], v[212:215], v[36:39]
	v_mfma_f32_16x16x32_bf16 v[28:31], v[136:139], v[220:223], v[28:31]
	v_mfma_f32_16x16x32_bf16 v[20:23], v[166:169], v[220:223], v[20:23]
	v_mfma_f32_16x16x32_bf16 v[12:15], v[136:139], v[228:231], v[12:15]
	v_mfma_f32_16x16x32_bf16 v[4:7], v[166:169], v[228:231], v[4:7]
	v_mfma_f32_16x16x32_bf16 v[60:63], v[162:165], v[208:211], v[60:63]
	v_mfma_f32_16x16x32_bf16 v[52:55], v[178:181], v[208:211], v[52:55]
	v_mfma_f32_16x16x32_bf16 v[44:47], v[162:165], v[216:219], v[44:47]
	v_mfma_f32_16x16x32_bf16 v[36:39], v[178:181], v[216:219], v[36:39]
	v_mfma_f32_16x16x32_bf16 v[28:31], v[162:165], v[224:227], v[28:31]
	v_mfma_f32_16x16x32_bf16 v[20:23], v[178:181], v[224:227], v[20:23]
	v_mfma_f32_16x16x32_bf16 v[12:15], v[162:165], v[232:235], v[12:15]
	v_mfma_f32_16x16x32_bf16 v[4:7], v[178:181], v[232:235], v[4:7]
	s_setprio 0
	s_setprio 1
	v_mfma_f32_16x16x32_bf16 v[56:59], v[184:187], v[204:207], v[56:59]
	v_mfma_f32_16x16x32_bf16 v[48:51], v[196:199], v[204:207], v[48:51]
	v_mfma_f32_16x16x32_bf16 v[40:43], v[184:187], v[212:215], v[40:43]
	v_mfma_f32_16x16x32_bf16 v[32:35], v[196:199], v[212:215], v[32:35]
	v_mfma_f32_16x16x32_bf16 v[24:27], v[184:187], v[220:223], v[24:27]
	v_mfma_f32_16x16x32_bf16 v[16:19], v[196:199], v[220:223], v[16:19]
	v_mfma_f32_16x16x32_bf16 v[8:11], v[184:187], v[228:231], v[8:11]
	v_mfma_f32_16x16x32_bf16 v[0:3], v[196:199], v[228:231], v[0:3]
	v_mfma_f32_16x16x32_bf16 v[56:59], v[188:191], v[208:211], v[56:59]
	v_mfma_f32_16x16x32_bf16 v[48:51], v[200:203], v[208:211], v[48:51]
	v_mfma_f32_16x16x32_bf16 v[40:43], v[188:191], v[216:219], v[40:43]
	v_mfma_f32_16x16x32_bf16 v[32:35], v[200:203], v[216:219], v[32:35]
	v_mfma_f32_16x16x32_bf16 v[24:27], v[188:191], v[224:227], v[24:27]
	v_mfma_f32_16x16x32_bf16 v[16:19], v[200:203], v[224:227], v[16:19]
	v_mfma_f32_16x16x32_bf16 v[8:11], v[188:191], v[232:235], v[8:11]
	v_mfma_f32_16x16x32_bf16 v[0:3], v[200:203], v[232:235], v[0:3]
	s_setprio 0
	s_barrier
	s_add_i32 s55, 0, 0x18000
	v_add_u32_e32 v161, s55, v151
	s_add_i32 s56, 0, 0x1c000
	ds_read_b128 v[136:139], v161
	ds_read_b128 v[162:165], v161 offset:1024
	ds_read_b128 v[166:169], v161 offset:2048
	ds_read_b128 v[178:181], v161 offset:3072
	v_add_u32_e32 v161, s56, v151
	ds_read_b128 v[184:187], v161
	ds_read_b128 v[188:191], v161 offset:1024
	ds_read_b128 v[196:199], v161 offset:2048
	ds_read_b128 v[200:203], v161 offset:3072
	s_add_u32 s22, s22, 0x40000
	s_addc_u32 s23, s23, 0
	s_mov_b32 m0, s39
	v_lshl_add_u64 v[240:241], s[22:23], 0, v[140:141]
	ds_read_b128 v[204:207], v159 offset:32768
	ds_read_b128 v[208:211], v159 offset:33792
	ds_read_b128 v[212:215], v159 offset:34816
	ds_read_b128 v[216:219], v159 offset:35840
	ds_read_b128 v[220:223], v159 offset:36864
	ds_read_b128 v[224:227], v159 offset:37888
	ds_read_b128 v[228:231], v159 offset:38912
	ds_read_b128 v[232:235], v159 offset:39936
	global_load_lds_dwordx4 v[240:241], off
	v_lshl_add_u64 v[240:241], s[22:23], 0, v[144:145]
	s_mov_b32 m0, s40
	s_nop 0
	global_load_lds_dwordx4 v[240:241], off
	s_waitcnt vmcnt(8)
	s_waitcnt lgkmcnt(0)
	s_barrier
	s_setprio 1
	s_waitcnt lgkmcnt(0)
	v_mfma_f32_16x16x32_bf16 v[112:115], v[136:139], v[204:207], v[112:115]
	v_mfma_f32_16x16x32_bf16 v[108:111], v[166:169], v[204:207], v[108:111]
	v_mfma_f32_16x16x32_bf16 v[104:107], v[136:139], v[212:215], v[104:107]
	v_mfma_f32_16x16x32_bf16 v[100:103], v[166:169], v[212:215], v[100:103]
	v_mfma_f32_16x16x32_bf16 v[92:95], v[136:139], v[220:223], v[92:95]
	v_mfma_f32_16x16x32_bf16 v[84:87], v[166:169], v[220:223], v[84:87]
	v_mfma_f32_16x16x32_bf16 v[76:79], v[136:139], v[228:231], v[76:79]
	v_mfma_f32_16x16x32_bf16 v[68:71], v[166:169], v[228:231], v[68:71]
	v_mfma_f32_16x16x32_bf16 v[112:115], v[162:165], v[208:211], v[112:115]
	v_mfma_f32_16x16x32_bf16 v[108:111], v[178:181], v[208:211], v[108:111]
	v_mfma_f32_16x16x32_bf16 v[104:107], v[162:165], v[216:219], v[104:107]
	v_mfma_f32_16x16x32_bf16 v[100:103], v[178:181], v[216:219], v[100:103]
	v_mfma_f32_16x16x32_bf16 v[92:95], v[162:165], v[224:227], v[92:95]
	v_mfma_f32_16x16x32_bf16 v[84:87], v[178:181], v[224:227], v[84:87]
	v_mfma_f32_16x16x32_bf16 v[76:79], v[162:165], v[232:235], v[76:79]
	v_mfma_f32_16x16x32_bf16 v[68:71], v[178:181], v[232:235], v[68:71]
	s_setprio 0
	s_setprio 1
	v_mfma_f32_16x16x32_bf16 v[124:127], v[184:187], v[204:207], v[124:127]
	v_mfma_f32_16x16x32_bf16 v[120:123], v[196:199], v[204:207], v[120:123]
	v_mfma_f32_16x16x32_bf16 v[116:119], v[184:187], v[212:215], v[116:119]
	v_mfma_f32_16x16x32_bf16 v[96:99], v[196:199], v[212:215], v[96:99]
	v_mfma_f32_16x16x32_bf16 v[88:91], v[184:187], v[220:223], v[88:91]
	v_mfma_f32_16x16x32_bf16 v[80:83], v[196:199], v[220:223], v[80:83]
	v_mfma_f32_16x16x32_bf16 v[72:75], v[184:187], v[228:231], v[72:75]
	v_mfma_f32_16x16x32_bf16 v[64:67], v[196:199], v[228:231], v[64:67]
	v_mfma_f32_16x16x32_bf16 v[124:127], v[188:191], v[208:211], v[124:127]
	v_mfma_f32_16x16x32_bf16 v[120:123], v[200:203], v[208:211], v[120:123]
	v_mfma_f32_16x16x32_bf16 v[116:119], v[188:191], v[216:219], v[116:119]
	v_mfma_f32_16x16x32_bf16 v[96:99], v[200:203], v[216:219], v[96:99]
	v_mfma_f32_16x16x32_bf16 v[88:91], v[188:191], v[224:227], v[88:91]
	v_mfma_f32_16x16x32_bf16 v[80:83], v[200:203], v[224:227], v[80:83]
	v_mfma_f32_16x16x32_bf16 v[72:75], v[188:191], v[232:235], v[72:75]
	v_mfma_f32_16x16x32_bf16 v[64:67], v[200:203], v[232:235], v[64:67]
	s_setprio 0
	s_barrier
	s_add_i32 s22, s55, s34
	v_lshl_add_u64 v[156:157], v[156:157], 0, s[12:13]
	s_mov_b32 m0, s22
	ds_read_b128 v[204:207], v159 offset:49152
	ds_read_b128 v[208:211], v159 offset:50176
	ds_read_b128 v[212:215], v159 offset:51200
	ds_read_b128 v[216:219], v159 offset:52224
	ds_read_b128 v[220:223], v159 offset:53248
	ds_read_b128 v[224:227], v159 offset:54272
	ds_read_b128 v[228:231], v159 offset:55296
	ds_read_b128 v[232:235], v159 offset:56320
	global_load_lds_dwordx4 v[156:157], off
	s_add_i32 m0, s22, 0x2000
	s_add_u32 s2, s2, 0x40080
	v_lshl_add_u64 v[156:157], v[192:193], 0, s[12:13]
	s_addc_u32 s3, s3, 0
	s_add_i32 s22, s56, s34
	global_load_lds_dwordx4 v[156:157], off
	v_lshl_add_u64 v[156:157], s[2:3], 0, v[142:143]
	s_mov_b32 m0, s22
	s_nop 0
	global_load_lds_dwordx4 v[156:157], off
	v_lshl_add_u64 v[156:157], s[2:3], 0, v[146:147]
	s_add_i32 m0, s22, 0x2000
	s_nop 0
	global_load_lds_dwordx4 v[156:157], off
	v_lshl_add_u64 v[156:157], v[236:237], 0, s[12:13]
	s_mov_b32 m0, s42
	s_nop 0
	global_load_lds_dwordx4 v[156:157], off
	v_lshl_add_u64 v[156:157], v[238:239], 0, s[12:13]
	s_mov_b32 m0, s43
	s_nop 0
	global_load_lds_dwordx4 v[156:157], off
	s_waitcnt vmcnt(8)
	s_waitcnt lgkmcnt(0)
	s_barrier
	s_setprio 1
	s_waitcnt lgkmcnt(0)
	v_mfma_f32_16x16x32_bf16 v[60:63], v[136:139], v[204:207], v[60:63]
	v_mfma_f32_16x16x32_bf16 v[52:55], v[166:169], v[204:207], v[52:55]
	v_mfma_f32_16x16x32_bf16 v[44:47], v[136:139], v[212:215], v[44:47]
	v_mfma_f32_16x16x32_bf16 v[36:39], v[166:169], v[212:215], v[36:39]
	v_mfma_f32_16x16x32_bf16 v[28:31], v[136:139], v[220:223], v[28:31]
	v_mfma_f32_16x16x32_bf16 v[20:23], v[166:169], v[220:223], v[20:23]
	v_mfma_f32_16x16x32_bf16 v[12:15], v[136:139], v[228:231], v[12:15]
	v_mfma_f32_16x16x32_bf16 v[4:7], v[166:169], v[228:231], v[4:7]
	v_mfma_f32_16x16x32_bf16 v[60:63], v[162:165], v[208:211], v[60:63]
	v_mfma_f32_16x16x32_bf16 v[52:55], v[178:181], v[208:211], v[52:55]
	v_mfma_f32_16x16x32_bf16 v[44:47], v[162:165], v[216:219], v[44:47]
	v_mfma_f32_16x16x32_bf16 v[36:39], v[178:181], v[216:219], v[36:39]
	v_mfma_f32_16x16x32_bf16 v[28:31], v[162:165], v[224:227], v[28:31]
	v_mfma_f32_16x16x32_bf16 v[20:23], v[178:181], v[224:227], v[20:23]
	v_mfma_f32_16x16x32_bf16 v[12:15], v[162:165], v[232:235], v[12:15]
	v_mfma_f32_16x16x32_bf16 v[4:7], v[178:181], v[232:235], v[4:7]
	s_setprio 0
	s_setprio 1
	v_mfma_f32_16x16x32_bf16 v[56:59], v[184:187], v[204:207], v[56:59]
	v_mfma_f32_16x16x32_bf16 v[48:51], v[196:199], v[204:207], v[48:51]
	v_mfma_f32_16x16x32_bf16 v[40:43], v[184:187], v[212:215], v[40:43]
	v_mfma_f32_16x16x32_bf16 v[32:35], v[196:199], v[212:215], v[32:35]
	v_mfma_f32_16x16x32_bf16 v[24:27], v[184:187], v[220:223], v[24:27]
	v_mfma_f32_16x16x32_bf16 v[16:19], v[196:199], v[220:223], v[16:19]
	v_mfma_f32_16x16x32_bf16 v[8:11], v[184:187], v[228:231], v[8:11]
	v_mfma_f32_16x16x32_bf16 v[0:3], v[196:199], v[228:231], v[0:3]
	v_mfma_f32_16x16x32_bf16 v[56:59], v[188:191], v[208:211], v[56:59]
	v_mfma_f32_16x16x32_bf16 v[48:51], v[200:203], v[208:211], v[48:51]
	v_mfma_f32_16x16x32_bf16 v[40:43], v[188:191], v[216:219], v[40:43]
	v_mfma_f32_16x16x32_bf16 v[32:35], v[200:203], v[216:219], v[32:35]
	v_mfma_f32_16x16x32_bf16 v[24:27], v[188:191], v[224:227], v[24:27]
	v_mfma_f32_16x16x32_bf16 v[16:19], v[200:203], v[224:227], v[16:19]
	v_mfma_f32_16x16x32_bf16 v[8:11], v[188:191], v[232:235], v[8:11]
	v_mfma_f32_16x16x32_bf16 v[0:3], v[200:203], v[232:235], v[0:3]
	s_setprio 0
	s_add_i32 s54, s54, 2
	s_add_u32 s14, s14, 0x100
	s_addc_u32 s15, s15, 0
	s_add_u32 s52, s52, 0x100
	s_addc_u32 s53, s53, 0
	s_cmp_gt_u32 s54, 13
	s_barrier
	s_cbranch_scc0 .LBB0_809

.LBB0_890:
	s_add_u32 s14, s14, 0xb0080
	s_addc_u32 s15, s15, 0
	s_add_u32 s53, s2, 0x100
	s_addc_u32 s54, s3, 0
	s_mov_b32 s55, -2
	s_waitcnt lgkmcnt(0)
	s_waitcnt vmcnt(0)
	ds_read_b128 v[128:131], v165
	ds_read_b128 v[132:135], v165 offset:1024
	ds_read_b128 v[136:139], v165 offset:2048
	ds_read_b128 v[156:159], v165 offset:3072
	ds_read_b128 v[172:175], v166
	ds_read_b128 v[176:179], v166 offset:1024
	ds_read_b128 v[180:183], v166 offset:2048
	ds_read_b128 v[184:187], v166 offset:3072
	s_add_u32 s2, s14, 0xfff50080
	s_addc_u32 s3, s15, -1
	s_cmp_eq_u32 s55, 40
	s_cselect_b32 s23, s1, s3
	s_cselect_b32 s22, s0, s2
	s_cselect_b32 s3, s21, s54
	s_cselect_b32 s2, s20, s53
	v_lshl_add_u64 v[160:161], s[14:15], 0, v[140:141]
	s_add_i32 m0, s27, 0xc000
	ds_read_b128 v[188:191], v167
	ds_read_b128 v[196:199], v167 offset:1024
	ds_read_b128 v[200:203], v167 offset:2048
	ds_read_b128 v[204:207], v167 offset:3072
	ds_read_b128 v[208:211], v167 offset:4096
	ds_read_b128 v[212:215], v167 offset:5120
	ds_read_b128 v[216:219], v167 offset:6144
	ds_read_b128 v[220:223], v167 offset:7168
	global_load_lds_dwordx4 v[160:161], off
	v_lshl_add_u64 v[160:161], s[14:15], 0, v[142:143]
	s_add_i32 m0, s27, 0xe000
	s_nop 0
	global_load_lds_dwordx4 v[160:161], off
	s_waitcnt vmcnt(8)
	s_waitcnt lgkmcnt(0)
	s_barrier
	s_setprio 1
	s_waitcnt lgkmcnt(0)
	v_mfma_f32_16x16x32_bf16 v[124:127], v[128:131], v[188:191], 0
	v_mfma_f32_16x16x32_bf16 v[120:123], v[136:139], v[188:191], 0
	v_mfma_f32_16x16x32_bf16 v[108:111], v[128:131], v[200:203], 0
	v_mfma_f32_16x16x32_bf16 v[104:107], v[136:139], v[200:203], 0
	v_mfma_f32_16x16x32_bf16 v[92:95], v[128:131], v[208:211], 0
	v_mfma_f32_16x16x32_bf16 v[88:91], v[136:139], v[208:211], 0
	v_mfma_f32_16x16x32_bf16 v[76:79], v[128:131], v[216:219], 0
	v_mfma_f32_16x16x32_bf16 v[72:75], v[136:139], v[216:219], 0
	v_mfma_f32_16x16x32_bf16 v[124:127], v[132:135], v[196:199], v[124:127]
	v_mfma_f32_16x16x32_bf16 v[120:123], v[156:159], v[196:199], v[120:123]
	v_mfma_f32_16x16x32_bf16 v[108:111], v[132:135], v[204:207], v[108:111]
	v_mfma_f32_16x16x32_bf16 v[104:107], v[156:159], v[204:207], v[104:107]
	v_mfma_f32_16x16x32_bf16 v[92:95], v[132:135], v[212:215], v[92:95]
	v_mfma_f32_16x16x32_bf16 v[88:91], v[156:159], v[212:215], v[88:91]
	v_mfma_f32_16x16x32_bf16 v[76:79], v[132:135], v[220:223], v[76:79]
	v_mfma_f32_16x16x32_bf16 v[72:75], v[156:159], v[220:223], v[72:75]
	s_setprio 0
	s_setprio 1
	v_mfma_f32_16x16x32_bf16 v[116:119], v[172:175], v[188:191], 0
	v_mfma_f32_16x16x32_bf16 v[112:115], v[180:183], v[188:191], 0
	v_mfma_f32_16x16x32_bf16 v[100:103], v[172:175], v[200:203], 0
	v_mfma_f32_16x16x32_bf16 v[96:99], v[180:183], v[200:203], 0
	v_mfma_f32_16x16x32_bf16 v[84:87], v[172:175], v[208:211], 0
	v_mfma_f32_16x16x32_bf16 v[80:83], v[180:183], v[208:211], 0
	v_mfma_f32_16x16x32_bf16 v[68:71], v[172:175], v[216:219], 0
	v_mfma_f32_16x16x32_bf16 v[64:67], v[180:183], v[216:219], 0
	v_mfma_f32_16x16x32_bf16 v[116:119], v[176:179], v[196:199], v[116:119]
	v_mfma_f32_16x16x32_bf16 v[112:115], v[184:187], v[196:199], v[112:115]
	v_mfma_f32_16x16x32_bf16 v[100:103], v[176:179], v[204:207], v[100:103]
	v_mfma_f32_16x16x32_bf16 v[96:99], v[184:187], v[204:207], v[96:99]
	v_mfma_f32_16x16x32_bf16 v[84:87], v[176:179], v[212:215], v[84:87]
	v_mfma_f32_16x16x32_bf16 v[80:83], v[184:187], v[212:215], v[80:83]
	v_mfma_f32_16x16x32_bf16 v[68:71], v[176:179], v[220:223], v[68:71]
	v_mfma_f32_16x16x32_bf16 v[64:67], v[184:187], v[220:223], v[64:67]
	s_setprio 0
	s_barrier
	s_add_i32 s56, s43, s26
	v_lshl_add_u64 v[160:161], s[2:3], 0, v[150:151]
	s_mov_b32 m0, s56
	ds_read_b128 v[188:191], v167 offset:16384
	ds_read_b128 v[196:199], v167 offset:17408
	ds_read_b128 v[200:203], v167 offset:18432
	ds_read_b128 v[204:207], v167 offset:19456
	ds_read_b128 v[208:211], v167 offset:20480
	ds_read_b128 v[212:215], v167 offset:21504
	ds_read_b128 v[216:219], v167 offset:22528
	ds_read_b128 v[220:223], v167 offset:23552
	global_load_lds_dwordx4 v[160:161], off
	s_add_i32 m0, s56, 0x2000
	s_add_u32 s56, s2, 0xb0000
	v_lshl_add_u64 v[192:193], s[2:3], 0, v[154:155]
	s_addc_u32 s57, s3, 0
	s_add_i32 s58, s44, s26
	global_load_lds_dwordx4 v[192:193], off
	v_lshl_add_u64 v[224:225], s[56:57], 0, v[150:151]
	s_mov_b32 m0, s58
	v_lshl_add_u64 v[226:227], s[22:23], 0, v[152:153]
	global_load_lds_dwordx4 v[224:225], off
	v_lshl_add_u64 v[224:225], s[56:57], 0, v[154:155]
	s_add_i32 m0, s58, 0x2000
	s_nop 0
	global_load_lds_dwordx4 v[224:225], off
	v_lshl_add_u64 v[224:225], s[22:23], 0, v[148:149]
	s_mov_b32 m0, s27
	s_nop 0
	global_load_lds_dwordx4 v[224:225], off
	s_mov_b32 m0, s28
	s_nop 0
	global_load_lds_dwordx4 v[226:227], off
	s_waitcnt vmcnt(8)
	s_waitcnt lgkmcnt(0)
	s_barrier
	s_setprio 1
	s_waitcnt lgkmcnt(0)
	v_mfma_f32_16x16x32_bf16 v[60:63], v[128:131], v[188:191], 0
	v_mfma_f32_16x16x32_bf16 v[56:59], v[136:139], v[188:191], 0
	v_mfma_f32_16x16x32_bf16 v[44:47], v[128:131], v[200:203], 0
	v_mfma_f32_16x16x32_bf16 v[40:43], v[136:139], v[200:203], 0
	v_mfma_f32_16x16x32_bf16 v[28:31], v[128:131], v[208:211], 0
	v_mfma_f32_16x16x32_bf16 v[24:27], v[136:139], v[208:211], 0
	v_mfma_f32_16x16x32_bf16 v[12:15], v[128:131], v[216:219], 0
	v_mfma_f32_16x16x32_bf16 v[8:11], v[136:139], v[216:219], 0
	v_mfma_f32_16x16x32_bf16 v[60:63], v[132:135], v[196:199], v[60:63]
	v_mfma_f32_16x16x32_bf16 v[56:59], v[156:159], v[196:199], v[56:59]
	v_mfma_f32_16x16x32_bf16 v[44:47], v[132:135], v[204:207], v[44:47]
	v_mfma_f32_16x16x32_bf16 v[40:43], v[156:159], v[204:207], v[40:43]
	v_mfma_f32_16x16x32_bf16 v[28:31], v[132:135], v[212:215], v[28:31]
	v_mfma_f32_16x16x32_bf16 v[24:27], v[156:159], v[212:215], v[24:27]
	v_mfma_f32_16x16x32_bf16 v[12:15], v[132:135], v[220:223], v[12:15]
	v_mfma_f32_16x16x32_bf16 v[8:11], v[156:159], v[220:223], v[8:11]
	s_setprio 0
	s_setprio 1
	v_mfma_f32_16x16x32_bf16 v[52:55], v[172:175], v[188:191], 0
	v_mfma_f32_16x16x32_bf16 v[48:51], v[180:183], v[188:191], 0
	v_mfma_f32_16x16x32_bf16 v[36:39], v[172:175], v[200:203], 0
	v_mfma_f32_16x16x32_bf16 v[32:35], v[180:183], v[200:203], 0
	v_mfma_f32_16x16x32_bf16 v[20:23], v[172:175], v[208:211], 0
	v_mfma_f32_16x16x32_bf16 v[16:19], v[180:183], v[208:211], 0
	v_mfma_f32_16x16x32_bf16 v[4:7], v[172:175], v[216:219], 0
	v_mfma_f32_16x16x32_bf16 v[0:3], v[180:183], v[216:219], 0
	v_mfma_f32_16x16x32_bf16 v[52:55], v[176:179], v[196:199], v[52:55]
	v_mfma_f32_16x16x32_bf16 v[48:51], v[184:187], v[196:199], v[48:51]
	v_mfma_f32_16x16x32_bf16 v[36:39], v[176:179], v[204:207], v[36:39]
	v_mfma_f32_16x16x32_bf16 v[32:35], v[184:187], v[204:207], v[32:35]
	v_mfma_f32_16x16x32_bf16 v[20:23], v[176:179], v[212:215], v[20:23]
	v_mfma_f32_16x16x32_bf16 v[16:19], v[184:187], v[212:215], v[16:19]
	v_mfma_f32_16x16x32_bf16 v[4:7], v[176:179], v[220:223], v[4:7]
	v_mfma_f32_16x16x32_bf16 v[0:3], v[184:187], v[220:223], v[0:3]
	s_setprio 0
	s_barrier
	s_add_i32 s56, 0, 0x18000
	s_add_i32 s57, 0, 0x1c000
	v_add_u32_e32 v156, s56, v162
	v_add_u32_e32 v169, s57, v162
	ds_read_b128 v[128:131], v156
	ds_read_b128 v[132:135], v156 offset:1024
	ds_read_b128 v[136:139], v156 offset:2048
	ds_read_b128 v[156:159], v156 offset:3072
	ds_read_b128 v[172:175], v169
	ds_read_b128 v[176:179], v169 offset:1024
	ds_read_b128 v[180:183], v169 offset:2048
	ds_read_b128 v[184:187], v169 offset:3072
	s_add_u32 s22, s22, 0xb0000
	s_addc_u32 s23, s23, 0
	s_mov_b32 m0, s29
	v_lshl_add_u64 v[228:229], s[22:23], 0, v[148:149]
	ds_read_b128 v[188:191], v167 offset:32768
	ds_read_b128 v[196:199], v167 offset:33792
	ds_read_b128 v[200:203], v167 offset:34816
	ds_read_b128 v[204:207], v167 offset:35840
	ds_read_b128 v[208:211], v167 offset:36864
	ds_read_b128 v[212:215], v167 offset:37888
	ds_read_b128 v[216:219], v167 offset:38912
	ds_read_b128 v[220:223], v167 offset:39936
	global_load_lds_dwordx4 v[228:229], off
	v_lshl_add_u64 v[228:229], s[22:23], 0, v[152:153]
	s_mov_b32 m0, s30
	s_nop 0
	global_load_lds_dwordx4 v[228:229], off
	s_waitcnt vmcnt(8)
	s_waitcnt lgkmcnt(0)
	s_barrier
	s_setprio 1
	s_waitcnt lgkmcnt(0)
	v_mfma_f32_16x16x32_bf16 v[124:127], v[128:131], v[188:191], v[124:127]
	v_mfma_f32_16x16x32_bf16 v[120:123], v[136:139], v[188:191], v[120:123]
	v_mfma_f32_16x16x32_bf16 v[108:111], v[128:131], v[200:203], v[108:111]
	v_mfma_f32_16x16x32_bf16 v[104:107], v[136:139], v[200:203], v[104:107]
	v_mfma_f32_16x16x32_bf16 v[92:95], v[128:131], v[208:211], v[92:95]
	v_mfma_f32_16x16x32_bf16 v[88:91], v[136:139], v[208:211], v[88:91]
	v_mfma_f32_16x16x32_bf16 v[76:79], v[128:131], v[216:219], v[76:79]
	v_mfma_f32_16x16x32_bf16 v[72:75], v[136:139], v[216:219], v[72:75]
	v_mfma_f32_16x16x32_bf16 v[124:127], v[132:135], v[196:199], v[124:127]
	v_mfma_f32_16x16x32_bf16 v[120:123], v[156:159], v[196:199], v[120:123]
	v_mfma_f32_16x16x32_bf16 v[108:111], v[132:135], v[204:207], v[108:111]
	v_mfma_f32_16x16x32_bf16 v[104:107], v[156:159], v[204:207], v[104:107]
	v_mfma_f32_16x16x32_bf16 v[92:95], v[132:135], v[212:215], v[92:95]
	v_mfma_f32_16x16x32_bf16 v[88:91], v[156:159], v[212:215], v[88:91]
	v_mfma_f32_16x16x32_bf16 v[76:79], v[132:135], v[220:223], v[76:79]
	v_mfma_f32_16x16x32_bf16 v[72:75], v[156:159], v[220:223], v[72:75]
	s_setprio 0
	s_setprio 1
	v_mfma_f32_16x16x32_bf16 v[116:119], v[172:175], v[188:191], v[116:119]
	v_mfma_f32_16x16x32_bf16 v[112:115], v[180:183], v[188:191], v[112:115]
	v_mfma_f32_16x16x32_bf16 v[100:103], v[172:175], v[200:203], v[100:103]
	v_mfma_f32_16x16x32_bf16 v[96:99], v[180:183], v[200:203], v[96:99]
	v_mfma_f32_16x16x32_bf16 v[84:87], v[172:175], v[208:211], v[84:87]
	v_mfma_f32_16x16x32_bf16 v[80:83], v[180:183], v[208:211], v[80:83]
	v_mfma_f32_16x16x32_bf16 v[68:71], v[172:175], v[216:219], v[68:71]
	v_mfma_f32_16x16x32_bf16 v[64:67], v[180:183], v[216:219], v[64:67]
	v_mfma_f32_16x16x32_bf16 v[116:119], v[176:179], v[196:199], v[116:119]
	v_mfma_f32_16x16x32_bf16 v[112:115], v[184:187], v[196:199], v[112:115]
	v_mfma_f32_16x16x32_bf16 v[100:103], v[176:179], v[204:207], v[100:103]
	v_mfma_f32_16x16x32_bf16 v[96:99], v[184:187], v[204:207], v[96:99]
	v_mfma_f32_16x16x32_bf16 v[84:87], v[176:179], v[212:215], v[84:87]
	v_mfma_f32_16x16x32_bf16 v[80:83], v[184:187], v[212:215], v[80:83]
	v_mfma_f32_16x16x32_bf16 v[68:71], v[176:179], v[220:223], v[68:71]
	v_mfma_f32_16x16x32_bf16 v[64:67], v[184:187], v[220:223], v[64:67]
	s_setprio 0
	s_barrier
	s_add_i32 s22, s56, s26
	v_lshl_add_u64 v[160:161], v[160:161], 0, s[12:13]
	s_mov_b32 m0, s22
	ds_read_b128 v[188:191], v167 offset:49152
	ds_read_b128 v[196:199], v167 offset:50176
	ds_read_b128 v[200:203], v167 offset:51200
	ds_read_b128 v[204:207], v167 offset:52224
	ds_read_b128 v[208:211], v167 offset:53248
	ds_read_b128 v[212:215], v167 offset:54272
	ds_read_b128 v[216:219], v167 offset:55296
	ds_read_b128 v[220:223], v167 offset:56320
	global_load_lds_dwordx4 v[160:161], off
	s_add_i32 m0, s22, 0x2000
	s_add_u32 s2, s2, 0xb0080
	v_lshl_add_u64 v[160:161], v[192:193], 0, s[12:13]
	s_addc_u32 s3, s3, 0
	s_add_i32 s22, s57, s26
	global_load_lds_dwordx4 v[160:161], off
	v_lshl_add_u64 v[160:161], s[2:3], 0, v[150:151]
	s_mov_b32 m0, s22
	s_nop 0
	global_load_lds_dwordx4 v[160:161], off
	v_lshl_add_u64 v[160:161], s[2:3], 0, v[154:155]
	s_add_i32 m0, s22, 0x2000
	s_nop 0
	global_load_lds_dwordx4 v[160:161], off
	v_lshl_add_u64 v[160:161], v[224:225], 0, s[12:13]
	s_mov_b32 m0, s36
	s_nop 0
	global_load_lds_dwordx4 v[160:161], off
	v_lshl_add_u64 v[160:161], v[226:227], 0, s[12:13]
	s_mov_b32 m0, s37
	s_nop 0
	global_load_lds_dwordx4 v[160:161], off
	s_waitcnt vmcnt(8)
	s_waitcnt lgkmcnt(0)
	s_barrier
	s_setprio 1
	s_waitcnt lgkmcnt(0)
	v_mfma_f32_16x16x32_bf16 v[60:63], v[128:131], v[188:191], v[60:63]
	v_mfma_f32_16x16x32_bf16 v[56:59], v[136:139], v[188:191], v[56:59]
	v_mfma_f32_16x16x32_bf16 v[44:47], v[128:131], v[200:203], v[44:47]
	v_mfma_f32_16x16x32_bf16 v[40:43], v[136:139], v[200:203], v[40:43]
	v_mfma_f32_16x16x32_bf16 v[28:31], v[128:131], v[208:211], v[28:31]
	v_mfma_f32_16x16x32_bf16 v[24:27], v[136:139], v[208:211], v[24:27]
	v_mfma_f32_16x16x32_bf16 v[12:15], v[128:131], v[216:219], v[12:15]
	v_mfma_f32_16x16x32_bf16 v[8:11], v[136:139], v[216:219], v[8:11]
	v_mfma_f32_16x16x32_bf16 v[60:63], v[132:135], v[196:199], v[60:63]
	v_mfma_f32_16x16x32_bf16 v[56:59], v[156:159], v[196:199], v[56:59]
	v_mfma_f32_16x16x32_bf16 v[44:47], v[132:135], v[204:207], v[44:47]
	v_mfma_f32_16x16x32_bf16 v[40:43], v[156:159], v[204:207], v[40:43]
	v_mfma_f32_16x16x32_bf16 v[28:31], v[132:135], v[212:215], v[28:31]
	v_mfma_f32_16x16x32_bf16 v[24:27], v[156:159], v[212:215], v[24:27]
	v_mfma_f32_16x16x32_bf16 v[12:15], v[132:135], v[220:223], v[12:15]
	v_mfma_f32_16x16x32_bf16 v[8:11], v[156:159], v[220:223], v[8:11]
	s_setprio 0
	s_setprio 1
	v_mfma_f32_16x16x32_bf16 v[52:55], v[172:175], v[188:191], v[52:55]
	v_mfma_f32_16x16x32_bf16 v[48:51], v[180:183], v[188:191], v[48:51]
	v_mfma_f32_16x16x32_bf16 v[36:39], v[172:175], v[200:203], v[36:39]
	v_mfma_f32_16x16x32_bf16 v[32:35], v[180:183], v[200:203], v[32:35]
	v_mfma_f32_16x16x32_bf16 v[20:23], v[172:175], v[208:211], v[20:23]
	v_mfma_f32_16x16x32_bf16 v[16:19], v[180:183], v[208:211], v[16:19]
	v_mfma_f32_16x16x32_bf16 v[4:7], v[172:175], v[216:219], v[4:7]
	v_mfma_f32_16x16x32_bf16 v[0:3], v[180:183], v[216:219], v[0:3]
	v_mfma_f32_16x16x32_bf16 v[52:55], v[176:179], v[196:199], v[52:55]
	v_mfma_f32_16x16x32_bf16 v[48:51], v[184:187], v[196:199], v[48:51]
	v_mfma_f32_16x16x32_bf16 v[36:39], v[176:179], v[204:207], v[36:39]
	v_mfma_f32_16x16x32_bf16 v[32:35], v[184:187], v[204:207], v[32:35]
	v_mfma_f32_16x16x32_bf16 v[20:23], v[176:179], v[212:215], v[20:23]
	v_mfma_f32_16x16x32_bf16 v[16:19], v[184:187], v[212:215], v[16:19]
	v_mfma_f32_16x16x32_bf16 v[4:7], v[176:179], v[220:223], v[4:7]
	v_mfma_f32_16x16x32_bf16 v[0:3], v[184:187], v[220:223], v[0:3]
	s_setprio 0
	s_add_i32 s55, s55, 2
	s_add_u32 s14, s14, 0x100
	s_addc_u32 s15, s15, 0
	s_add_u32 s53, s53, 0x100
	s_addc_u32 s54, s54, 0
	s_cmp_gt_u32 s55, 41
	s_barrier
	s_cbranch_scc1 .Lgemm_kdone_6
.LBB0_891:
	ds_read_b128 v[128:131], v165
	ds_read_b128 v[132:135], v165 offset:1024
	ds_read_b128 v[136:139], v165 offset:2048
	ds_read_b128 v[156:159], v165 offset:3072
	ds_read_b128 v[172:175], v166
	ds_read_b128 v[176:179], v166 offset:1024
	ds_read_b128 v[180:183], v166 offset:2048
	ds_read_b128 v[184:187], v166 offset:3072
	s_add_u32 s2, s14, 0xfff50080
	s_addc_u32 s3, s15, -1
	s_cmp_eq_u32 s55, 40
	s_cselect_b32 s23, s1, s3
	s_cselect_b32 s22, s0, s2
	s_cselect_b32 s3, s21, s54
	s_cselect_b32 s2, s20, s53
	v_lshl_add_u64 v[160:161], s[14:15], 0, v[140:141]
	s_add_i32 m0, s27, 0xc000
	ds_read_b128 v[188:191], v167
	ds_read_b128 v[196:199], v167 offset:1024
	ds_read_b128 v[200:203], v167 offset:2048
	ds_read_b128 v[204:207], v167 offset:3072
	ds_read_b128 v[208:211], v167 offset:4096
	ds_read_b128 v[212:215], v167 offset:5120
	ds_read_b128 v[216:219], v167 offset:6144
	ds_read_b128 v[220:223], v167 offset:7168
	global_load_lds_dwordx4 v[160:161], off
	v_lshl_add_u64 v[160:161], s[14:15], 0, v[142:143]
	s_add_i32 m0, s27, 0xe000
	s_nop 0
	global_load_lds_dwordx4 v[160:161], off
	s_waitcnt vmcnt(8)
	s_waitcnt lgkmcnt(0)
	s_barrier
	s_setprio 1
	s_waitcnt lgkmcnt(0)
	v_mfma_f32_16x16x32_bf16 v[124:127], v[128:131], v[188:191], v[124:127]
	v_mfma_f32_16x16x32_bf16 v[120:123], v[136:139], v[188:191], v[120:123]
	v_mfma_f32_16x16x32_bf16 v[108:111], v[128:131], v[200:203], v[108:111]
	v_mfma_f32_16x16x32_bf16 v[104:107], v[136:139], v[200:203], v[104:107]
	v_mfma_f32_16x16x32_bf16 v[92:95], v[128:131], v[208:211], v[92:95]
	v_mfma_f32_16x16x32_bf16 v[88:91], v[136:139], v[208:211], v[88:91]
	v_mfma_f32_16x16x32_bf16 v[76:79], v[128:131], v[216:219], v[76:79]
	v_mfma_f32_16x16x32_bf16 v[72:75], v[136:139], v[216:219], v[72:75]
	v_mfma_f32_16x16x32_bf16 v[124:127], v[132:135], v[196:199], v[124:127]
	v_mfma_f32_16x16x32_bf16 v[120:123], v[156:159], v[196:199], v[120:123]
	v_mfma_f32_16x16x32_bf16 v[108:111], v[132:135], v[204:207], v[108:111]
	v_mfma_f32_16x16x32_bf16 v[104:107], v[156:159], v[204:207], v[104:107]
	v_mfma_f32_16x16x32_bf16 v[92:95], v[132:135], v[212:215], v[92:95]
	v_mfma_f32_16x16x32_bf16 v[88:91], v[156:159], v[212:215], v[88:91]
	v_mfma_f32_16x16x32_bf16 v[76:79], v[132:135], v[220:223], v[76:79]
	v_mfma_f32_16x16x32_bf16 v[72:75], v[156:159], v[220:223], v[72:75]
	s_setprio 0
	s_setprio 1
	v_mfma_f32_16x16x32_bf16 v[116:119], v[172:175], v[188:191], v[116:119]
	v_mfma_f32_16x16x32_bf16 v[112:115], v[180:183], v[188:191], v[112:115]
	v_mfma_f32_16x16x32_bf16 v[100:103], v[172:175], v[200:203], v[100:103]
	v_mfma_f32_16x16x32_bf16 v[96:99], v[180:183], v[200:203], v[96:99]
	v_mfma_f32_16x16x32_bf16 v[84:87], v[172:175], v[208:211], v[84:87]
	v_mfma_f32_16x16x32_bf16 v[80:83], v[180:183], v[208:211], v[80:83]
	v_mfma_f32_16x16x32_bf16 v[68:71], v[172:175], v[216:219], v[68:71]
	v_mfma_f32_16x16x32_bf16 v[64:67], v[180:183], v[216:219], v[64:67]
	v_mfma_f32_16x16x32_bf16 v[116:119], v[176:179], v[196:199], v[116:119]
	v_mfma_f32_16x16x32_bf16 v[112:115], v[184:187], v[196:199], v[112:115]
	v_mfma_f32_16x16x32_bf16 v[100:103], v[176:179], v[204:207], v[100:103]
	v_mfma_f32_16x16x32_bf16 v[96:99], v[184:187], v[204:207], v[96:99]
	v_mfma_f32_16x16x32_bf16 v[84:87], v[176:179], v[212:215], v[84:87]
	v_mfma_f32_16x16x32_bf16 v[80:83], v[184:187], v[212:215], v[80:83]
	v_mfma_f32_16x16x32_bf16 v[68:71], v[176:179], v[220:223], v[68:71]
	v_mfma_f32_16x16x32_bf16 v[64:67], v[184:187], v[220:223], v[64:67]
	s_setprio 0
	s_barrier
	s_add_i32 s56, s43, s26
	v_lshl_add_u64 v[160:161], s[2:3], 0, v[150:151]
	s_mov_b32 m0, s56
	ds_read_b128 v[188:191], v167 offset:16384
	ds_read_b128 v[196:199], v167 offset:17408
	ds_read_b128 v[200:203], v167 offset:18432
	ds_read_b128 v[204:207], v167 offset:19456
	ds_read_b128 v[208:211], v167 offset:20480
	ds_read_b128 v[212:215], v167 offset:21504
	ds_read_b128 v[216:219], v167 offset:22528
	ds_read_b128 v[220:223], v167 offset:23552
	global_load_lds_dwordx4 v[160:161], off
	s_add_i32 m0, s56, 0x2000
	s_add_u32 s56, s2, 0xb0000
	v_lshl_add_u64 v[192:193], s[2:3], 0, v[154:155]
	s_addc_u32 s57, s3, 0
	s_add_i32 s58, s44, s26
	global_load_lds_dwordx4 v[192:193], off
	v_lshl_add_u64 v[224:225], s[56:57], 0, v[150:151]
	s_mov_b32 m0, s58
	v_lshl_add_u64 v[226:227], s[22:23], 0, v[152:153]
	global_load_lds_dwordx4 v[224:225], off
	v_lshl_add_u64 v[224:225], s[56:57], 0, v[154:155]
	s_add_i32 m0, s58, 0x2000
	s_nop 0
	global_load_lds_dwordx4 v[224:225], off
	v_lshl_add_u64 v[224:225], s[22:23], 0, v[148:149]
	s_mov_b32 m0, s27
	s_nop 0
	global_load_lds_dwordx4 v[224:225], off
	s_mov_b32 m0, s28
	s_nop 0
	global_load_lds_dwordx4 v[226:227], off
	s_waitcnt vmcnt(8)
	s_waitcnt lgkmcnt(0)
	s_barrier
	s_setprio 1
	s_waitcnt lgkmcnt(0)
	v_mfma_f32_16x16x32_bf16 v[60:63], v[128:131], v[188:191], v[60:63]
	v_mfma_f32_16x16x32_bf16 v[56:59], v[136:139], v[188:191], v[56:59]
	v_mfma_f32_16x16x32_bf16 v[44:47], v[128:131], v[200:203], v[44:47]
	v_mfma_f32_16x16x32_bf16 v[40:43], v[136:139], v[200:203], v[40:43]
	v_mfma_f32_16x16x32_bf16 v[28:31], v[128:131], v[208:211], v[28:31]
	v_mfma_f32_16x16x32_bf16 v[24:27], v[136:139], v[208:211], v[24:27]
	v_mfma_f32_16x16x32_bf16 v[12:15], v[128:131], v[216:219], v[12:15]
	v_mfma_f32_16x16x32_bf16 v[8:11], v[136:139], v[216:219], v[8:11]
	v_mfma_f32_16x16x32_bf16 v[60:63], v[132:135], v[196:199], v[60:63]
	v_mfma_f32_16x16x32_bf16 v[56:59], v[156:159], v[196:199], v[56:59]
	v_mfma_f32_16x16x32_bf16 v[44:47], v[132:135], v[204:207], v[44:47]
	v_mfma_f32_16x16x32_bf16 v[40:43], v[156:159], v[204:207], v[40:43]
	v_mfma_f32_16x16x32_bf16 v[28:31], v[132:135], v[212:215], v[28:31]
	v_mfma_f32_16x16x32_bf16 v[24:27], v[156:159], v[212:215], v[24:27]
	v_mfma_f32_16x16x32_bf16 v[12:15], v[132:135], v[220:223], v[12:15]
	v_mfma_f32_16x16x32_bf16 v[8:11], v[156:159], v[220:223], v[8:11]
	s_setprio 0
	s_setprio 1
	v_mfma_f32_16x16x32_bf16 v[52:55], v[172:175], v[188:191], v[52:55]
	v_mfma_f32_16x16x32_bf16 v[48:51], v[180:183], v[188:191], v[48:51]
	v_mfma_f32_16x16x32_bf16 v[36:39], v[172:175], v[200:203], v[36:39]
	v_mfma_f32_16x16x32_bf16 v[32:35], v[180:183], v[200:203], v[32:35]
	v_mfma_f32_16x16x32_bf16 v[20:23], v[172:175], v[208:211], v[20:23]
	v_mfma_f32_16x16x32_bf16 v[16:19], v[180:183], v[208:211], v[16:19]
	v_mfma_f32_16x16x32_bf16 v[4:7], v[172:175], v[216:219], v[4:7]
	v_mfma_f32_16x16x32_bf16 v[0:3], v[180:183], v[216:219], v[0:3]
	v_mfma_f32_16x16x32_bf16 v[52:55], v[176:179], v[196:199], v[52:55]
	v_mfma_f32_16x16x32_bf16 v[48:51], v[184:187], v[196:199], v[48:51]
	v_mfma_f32_16x16x32_bf16 v[36:39], v[176:179], v[204:207], v[36:39]
	v_mfma_f32_16x16x32_bf16 v[32:35], v[184:187], v[204:207], v[32:35]
	v_mfma_f32_16x16x32_bf16 v[20:23], v[176:179], v[212:215], v[20:23]
	v_mfma_f32_16x16x32_bf16 v[16:19], v[184:187], v[212:215], v[16:19]
	v_mfma_f32_16x16x32_bf16 v[4:7], v[176:179], v[220:223], v[4:7]
	v_mfma_f32_16x16x32_bf16 v[0:3], v[184:187], v[220:223], v[0:3]
	s_setprio 0
	s_barrier
	s_add_i32 s56, 0, 0x18000
	s_add_i32 s57, 0, 0x1c000
	v_add_u32_e32 v156, s56, v162
	v_add_u32_e32 v169, s57, v162
	ds_read_b128 v[128:131], v156
	ds_read_b128 v[132:135], v156 offset:1024
	ds_read_b128 v[136:139], v156 offset:2048
	ds_read_b128 v[156:159], v156 offset:3072
	ds_read_b128 v[172:175], v169
	ds_read_b128 v[176:179], v169 offset:1024
	ds_read_b128 v[180:183], v169 offset:2048
	ds_read_b128 v[184:187], v169 offset:3072
	s_add_u32 s22, s22, 0xb0000
	s_addc_u32 s23, s23, 0
	s_mov_b32 m0, s29
	v_lshl_add_u64 v[228:229], s[22:23], 0, v[148:149]
	ds_read_b128 v[188:191], v167 offset:32768
	ds_read_b128 v[196:199], v167 offset:33792
	ds_read_b128 v[200:203], v167 offset:34816
	ds_read_b128 v[204:207], v167 offset:35840
	ds_read_b128 v[208:211], v167 offset:36864
	ds_read_b128 v[212:215], v167 offset:37888
	ds_read_b128 v[216:219], v167 offset:38912
	ds_read_b128 v[220:223], v167 offset:39936
	global_load_lds_dwordx4 v[228:229], off
	v_lshl_add_u64 v[228:229], s[22:23], 0, v[152:153]
	s_mov_b32 m0, s30
	s_nop 0
	global_load_lds_dwordx4 v[228:229], off
	s_waitcnt vmcnt(8)
	s_waitcnt lgkmcnt(0)
	s_barrier
	s_setprio 1
	s_waitcnt lgkmcnt(0)
	v_mfma_f32_16x16x32_bf16 v[124:127], v[128:131], v[188:191], v[124:127]
	v_mfma_f32_16x16x32_bf16 v[120:123], v[136:139], v[188:191], v[120:123]
	v_mfma_f32_16x16x32_bf16 v[108:111], v[128:131], v[200:203], v[108:111]
	v_mfma_f32_16x16x32_bf16 v[104:107], v[136:139], v[200:203], v[104:107]
	v_mfma_f32_16x16x32_bf16 v[92:95], v[128:131], v[208:211], v[92:95]
	v_mfma_f32_16x16x32_bf16 v[88:91], v[136:139], v[208:211], v[88:91]
	v_mfma_f32_16x16x32_bf16 v[76:79], v[128:131], v[216:219], v[76:79]
	v_mfma_f32_16x16x32_bf16 v[72:75], v[136:139], v[216:219], v[72:75]
	v_mfma_f32_16x16x32_bf16 v[124:127], v[132:135], v[196:199], v[124:127]
	v_mfma_f32_16x16x32_bf16 v[120:123], v[156:159], v[196:199], v[120:123]
	v_mfma_f32_16x16x32_bf16 v[108:111], v[132:135], v[204:207], v[108:111]
	v_mfma_f32_16x16x32_bf16 v[104:107], v[156:159], v[204:207], v[104:107]
	v_mfma_f32_16x16x32_bf16 v[92:95], v[132:135], v[212:215], v[92:95]
	v_mfma_f32_16x16x32_bf16 v[88:91], v[156:159], v[212:215], v[88:91]
	v_mfma_f32_16x16x32_bf16 v[76:79], v[132:135], v[220:223], v[76:79]
	v_mfma_f32_16x16x32_bf16 v[72:75], v[156:159], v[220:223], v[72:75]
	s_setprio 0
	s_setprio 1
	v_mfma_f32_16x16x32_bf16 v[116:119], v[172:175], v[188:191], v[116:119]
	v_mfma_f32_16x16x32_bf16 v[112:115], v[180:183], v[188:191], v[112:115]
	v_mfma_f32_16x16x32_bf16 v[100:103], v[172:175], v[200:203], v[100:103]
	v_mfma_f32_16x16x32_bf16 v[96:99], v[180:183], v[200:203], v[96:99]
	v_mfma_f32_16x16x32_bf16 v[84:87], v[172:175], v[208:211], v[84:87]
	v_mfma_f32_16x16x32_bf16 v[80:83], v[180:183], v[208:211], v[80:83]
	v_mfma_f32_16x16x32_bf16 v[68:71], v[172:175], v[216:219], v[68:71]
	v_mfma_f32_16x16x32_bf16 v[64:67], v[180:183], v[216:219], v[64:67]
	v_mfma_f32_16x16x32_bf16 v[116:119], v[176:179], v[196:199], v[116:119]
	v_mfma_f32_16x16x32_bf16 v[112:115], v[184:187], v[196:199], v[112:115]
	v_mfma_f32_16x16x32_bf16 v[100:103], v[176:179], v[204:207], v[100:103]
	v_mfma_f32_16x16x32_bf16 v[96:99], v[184:187], v[204:207], v[96:99]
	v_mfma_f32_16x16x32_bf16 v[84:87], v[176:179], v[212:215], v[84:87]
	v_mfma_f32_16x16x32_bf16 v[80:83], v[184:187], v[212:215], v[80:83]
	v_mfma_f32_16x16x32_bf16 v[68:71], v[176:179], v[220:223], v[68:71]
	v_mfma_f32_16x16x32_bf16 v[64:67], v[184:187], v[220:223], v[64:67]
	s_setprio 0
	s_barrier
	s_add_i32 s22, s56, s26
	v_lshl_add_u64 v[160:161], v[160:161], 0, s[12:13]
	s_mov_b32 m0, s22
	ds_read_b128 v[188:191], v167 offset:49152
	ds_read_b128 v[196:199], v167 offset:50176
	ds_read_b128 v[200:203], v167 offset:51200
	ds_read_b128 v[204:207], v167 offset:52224
	ds_read_b128 v[208:211], v167 offset:53248
	ds_read_b128 v[212:215], v167 offset:54272
	ds_read_b128 v[216:219], v167 offset:55296
	ds_read_b128 v[220:223], v167 offset:56320
	global_load_lds_dwordx4 v[160:161], off
	s_add_i32 m0, s22, 0x2000
	s_add_u32 s2, s2, 0xb0080
	v_lshl_add_u64 v[160:161], v[192:193], 0, s[12:13]
	s_addc_u32 s3, s3, 0
	s_add_i32 s22, s57, s26
	global_load_lds_dwordx4 v[160:161], off
	v_lshl_add_u64 v[160:161], s[2:3], 0, v[150:151]
	s_mov_b32 m0, s22
	s_nop 0
	global_load_lds_dwordx4 v[160:161], off
	v_lshl_add_u64 v[160:161], s[2:3], 0, v[154:155]
	s_add_i32 m0, s22, 0x2000
	s_nop 0
	global_load_lds_dwordx4 v[160:161], off
	v_lshl_add_u64 v[160:161], v[224:225], 0, s[12:13]
	s_mov_b32 m0, s36
	s_nop 0
	global_load_lds_dwordx4 v[160:161], off
	v_lshl_add_u64 v[160:161], v[226:227], 0, s[12:13]
	s_mov_b32 m0, s37
	s_nop 0
	global_load_lds_dwordx4 v[160:161], off
	s_waitcnt vmcnt(8)
	s_waitcnt lgkmcnt(0)
	s_barrier
	s_setprio 1
	s_waitcnt lgkmcnt(0)
	v_mfma_f32_16x16x32_bf16 v[60:63], v[128:131], v[188:191], v[60:63]
	v_mfma_f32_16x16x32_bf16 v[56:59], v[136:139], v[188:191], v[56:59]
	v_mfma_f32_16x16x32_bf16 v[44:47], v[128:131], v[200:203], v[44:47]
	v_mfma_f32_16x16x32_bf16 v[40:43], v[136:139], v[200:203], v[40:43]
	v_mfma_f32_16x16x32_bf16 v[28:31], v[128:131], v[208:211], v[28:31]
	v_mfma_f32_16x16x32_bf16 v[24:27], v[136:139], v[208:211], v[24:27]
	v_mfma_f32_16x16x32_bf16 v[12:15], v[128:131], v[216:219], v[12:15]
	v_mfma_f32_16x16x32_bf16 v[8:11], v[136:139], v[216:219], v[8:11]
	v_mfma_f32_16x16x32_bf16 v[60:63], v[132:135], v[196:199], v[60:63]
	v_mfma_f32_16x16x32_bf16 v[56:59], v[156:159], v[196:199], v[56:59]
	v_mfma_f32_16x16x32_bf16 v[44:47], v[132:135], v[204:207], v[44:47]
	v_mfma_f32_16x16x32_bf16 v[40:43], v[156:159], v[204:207], v[40:43]
	v_mfma_f32_16x16x32_bf16 v[28:31], v[132:135], v[212:215], v[28:31]
	v_mfma_f32_16x16x32_bf16 v[24:27], v[156:159], v[212:215], v[24:27]
	v_mfma_f32_16x16x32_bf16 v[12:15], v[132:135], v[220:223], v[12:15]
	v_mfma_f32_16x16x32_bf16 v[8:11], v[156:159], v[220:223], v[8:11]
	s_setprio 0
	s_setprio 1
	v_mfma_f32_16x16x32_bf16 v[52:55], v[172:175], v[188:191], v[52:55]
	v_mfma_f32_16x16x32_bf16 v[48:51], v[180:183], v[188:191], v[48:51]
	v_mfma_f32_16x16x32_bf16 v[36:39], v[172:175], v[200:203], v[36:39]
	v_mfma_f32_16x16x32_bf16 v[32:35], v[180:183], v[200:203], v[32:35]
	v_mfma_f32_16x16x32_bf16 v[20:23], v[172:175], v[208:211], v[20:23]
	v_mfma_f32_16x16x32_bf16 v[16:19], v[180:183], v[208:211], v[16:19]
	v_mfma_f32_16x16x32_bf16 v[4:7], v[172:175], v[216:219], v[4:7]
	v_mfma_f32_16x16x32_bf16 v[0:3], v[180:183], v[216:219], v[0:3]
	v_mfma_f32_16x16x32_bf16 v[52:55], v[176:179], v[196:199], v[52:55]
	v_mfma_f32_16x16x32_bf16 v[48:51], v[184:187], v[196:199], v[48:51]
	v_mfma_f32_16x16x32_bf16 v[36:39], v[176:179], v[204:207], v[36:39]
	v_mfma_f32_16x16x32_bf16 v[32:35], v[184:187], v[204:207], v[32:35]
	v_mfma_f32_16x16x32_bf16 v[20:23], v[176:179], v[212:215], v[20:23]
	v_mfma_f32_16x16x32_bf16 v[16:19], v[184:187], v[212:215], v[16:19]
	v_mfma_f32_16x16x32_bf16 v[4:7], v[176:179], v[220:223], v[4:7]
	v_mfma_f32_16x16x32_bf16 v[0:3], v[184:187], v[220:223], v[0:3]
	s_setprio 0
	s_add_i32 s55, s55, 2
	s_add_u32 s14, s14, 0x100
	s_addc_u32 s15, s15, 0
	s_add_u32 s53, s53, 0x100
	s_addc_u32 s54, s54, 0
	s_cmp_gt_u32 s55, 41
	s_barrier
	s_cbranch_scc0 .LBB0_891
